# GEMM K loops: LDS-DMA loads issued before the fragment ds_reads inside each load segment (where register dependences allow)
# speedup vs baseline: 1.0089x; 1.0011x over previous
.LBB0_195:
	v_mov_b32_e32 v127, 0
	s_andn2_b64 vcc, exec, s[80:81]
	v_mov_b32_e32 v126, v127
	v_mov_b32_e32 v125, v127
	v_mov_b32_e32 v124, v127
	v_mov_b32_e32 v123, v127
	v_mov_b32_e32 v122, v127
	v_mov_b32_e32 v121, v127
	v_mov_b32_e32 v120, v127
	v_mov_b32_e32 v111, v127
	v_mov_b32_e32 v110, v127
	v_mov_b32_e32 v109, v127
	v_mov_b32_e32 v108, v127
	v_mov_b32_e32 v107, v127
	v_mov_b32_e32 v106, v127
	v_mov_b32_e32 v105, v127
	v_mov_b32_e32 v104, v127
	v_mov_b32_e32 v95, v127
	v_mov_b32_e32 v94, v127
	v_mov_b32_e32 v93, v127
	v_mov_b32_e32 v92, v127
	v_mov_b32_e32 v91, v127
	v_mov_b32_e32 v90, v127
	v_mov_b32_e32 v89, v127
	v_mov_b32_e32 v88, v127
	v_mov_b32_e32 v79, v127
	v_mov_b32_e32 v78, v127
	v_mov_b32_e32 v77, v127
	v_mov_b32_e32 v76, v127
	v_mov_b32_e32 v75, v127
	v_mov_b32_e32 v74, v127
	v_mov_b32_e32 v73, v127
	v_mov_b32_e32 v72, v127
	v_mov_b32_e32 v119, v127
	v_mov_b32_e32 v118, v127
	v_mov_b32_e32 v117, v127
	v_mov_b32_e32 v116, v127
	v_mov_b32_e32 v115, v127
	v_mov_b32_e32 v114, v127
	v_mov_b32_e32 v113, v127
	v_mov_b32_e32 v112, v127
	v_mov_b32_e32 v103, v127
	v_mov_b32_e32 v102, v127
	v_mov_b32_e32 v101, v127
	v_mov_b32_e32 v100, v127
	v_mov_b32_e32 v99, v127
	v_mov_b32_e32 v98, v127
	v_mov_b32_e32 v97, v127
	v_mov_b32_e32 v96, v127
	v_mov_b32_e32 v87, v127
	v_mov_b32_e32 v86, v127
	v_mov_b32_e32 v85, v127
	v_mov_b32_e32 v84, v127
	v_mov_b32_e32 v83, v127
	v_mov_b32_e32 v82, v127
	v_mov_b32_e32 v81, v127
	v_mov_b32_e32 v80, v127
	v_mov_b32_e32 v71, v127
	v_mov_b32_e32 v70, v127
	v_mov_b32_e32 v69, v127
	v_mov_b32_e32 v68, v127
	v_mov_b32_e32 v67, v127
	v_mov_b32_e32 v66, v127
	v_mov_b32_e32 v65, v127
	v_mov_b32_e32 v64, v127
	v_mov_b32_e32 v63, v127
	v_mov_b32_e32 v62, v127
	v_mov_b32_e32 v61, v127
	v_mov_b32_e32 v60, v127
	v_mov_b32_e32 v59, v127
	v_mov_b32_e32 v58, v127
	v_mov_b32_e32 v57, v127
	v_mov_b32_e32 v56, v127
	v_mov_b32_e32 v47, v127
	v_mov_b32_e32 v46, v127
	v_mov_b32_e32 v45, v127
	v_mov_b32_e32 v44, v127
	v_mov_b32_e32 v43, v127
	v_mov_b32_e32 v42, v127
	v_mov_b32_e32 v41, v127
	v_mov_b32_e32 v40, v127
	v_mov_b32_e32 v31, v127
	v_mov_b32_e32 v30, v127
	v_mov_b32_e32 v29, v127
	v_mov_b32_e32 v28, v127
	v_mov_b32_e32 v27, v127
	v_mov_b32_e32 v26, v127
	v_mov_b32_e32 v25, v127
	v_mov_b32_e32 v24, v127
	v_mov_b32_e32 v15, v127
	v_mov_b32_e32 v14, v127
	v_mov_b32_e32 v13, v127
	v_mov_b32_e32 v12, v127
	v_mov_b32_e32 v11, v127
	v_mov_b32_e32 v10, v127
	v_mov_b32_e32 v9, v127
	v_mov_b32_e32 v8, v127
	v_mov_b32_e32 v55, v127
	v_mov_b32_e32 v54, v127
	v_mov_b32_e32 v53, v127
	v_mov_b32_e32 v52, v127
	v_mov_b32_e32 v51, v127
	v_mov_b32_e32 v50, v127
	v_mov_b32_e32 v49, v127
	v_mov_b32_e32 v48, v127
	v_mov_b32_e32 v39, v127
	v_mov_b32_e32 v38, v127
	v_mov_b32_e32 v37, v127
	v_mov_b32_e32 v36, v127
	v_mov_b32_e32 v35, v127
	v_mov_b32_e32 v34, v127
	v_mov_b32_e32 v33, v127
	v_mov_b32_e32 v32, v127
	v_mov_b32_e32 v23, v127
	v_mov_b32_e32 v22, v127
	v_mov_b32_e32 v21, v127
	v_mov_b32_e32 v20, v127
	v_mov_b32_e32 v19, v127
	v_mov_b32_e32 v18, v127
	v_mov_b32_e32 v17, v127
	v_mov_b32_e32 v16, v127
	v_mov_b32_e32 v7, v127
	v_mov_b32_e32 v6, v127
	v_mov_b32_e32 v5, v127
	v_mov_b32_e32 v4, v127
	v_mov_b32_e32 v3, v127
	v_mov_b32_e32 v2, v127
	v_mov_b32_e32 v1, v127
	v_mov_b32_e32 v0, v127
	s_cbranch_vccnz .LBB0_198
	s_add_u32 s10, s6, 0x100
	s_addc_u32 s40, s7, 0
	s_add_u32 s6, s38, 0x80
	s_addc_u32 s7, s39, 0
	s_mov_b32 s2, 0
	s_add_i32 s41, s2, 2
	s_add_u32 s21, s6, 0x80
	s_addc_u32 s3, s7, 0
	s_add_i32 s42, 0, 0x10000
	v_add_u32_e32 v140, s42, v154
	s_cmp_eq_u32 s9, s2
	s_cselect_b32 s2, s68, s21
	s_cselect_b32 s3, s69, s3
	s_cselect_b32 s39, s95, s40
	s_cselect_b32 s38, s94, s10
	v_lshl_add_u64 v[226:227], s[6:7], 0, v[138:139]
	s_add_i32 m0, s79, 0xc000
	s_nop 0
	global_load_lds_dwordx4 v[226:227], off
	v_lshl_add_u64 v[226:227], s[6:7], 0, v[136:137]
	s_add_i32 m0, s79, 0xe000
	s_nop 0
	global_load_lds_dwordx4 v[226:227], off
	ds_read_b128 v[142:145], v140
	ds_read_b128 v[162:165], v140 offset:1024
	ds_read_b128 v[166:169], v140 offset:2048
	ds_read_b128 v[170:173], v140 offset:3072
	ds_read_b128 v[174:177], v155
	ds_read_b128 v[178:181], v155 offset:1024
	ds_read_b128 v[182:185], v155 offset:2048
	ds_read_b128 v[186:189], v155 offset:3072
	ds_read_b128 v[206:209], v155 offset:4096
	ds_read_b128 v[214:217], v155 offset:5120
	ds_read_b128 v[218:221], v155 offset:6144
	ds_read_b128 v[222:225], v155 offset:7168
	s_waitcnt lgkmcnt(8)
	s_barrier
	s_waitcnt lgkmcnt(0)
	v_mfma_f32_16x16x32_bf16 v[124:127], v[142:145], v[174:177], 0
	v_mfma_f32_16x16x32_bf16 v[120:123], v[166:169], v[174:177], 0
	v_mfma_f32_16x16x32_bf16 v[108:111], v[142:145], v[182:185], 0
	v_mfma_f32_16x16x32_bf16 v[104:107], v[166:169], v[182:185], 0
	v_mfma_f32_16x16x32_bf16 v[92:95], v[142:145], v[206:209], 0
	v_mfma_f32_16x16x32_bf16 v[88:91], v[166:169], v[206:209], 0
	v_mfma_f32_16x16x32_bf16 v[76:79], v[142:145], v[218:221], 0
	v_mfma_f32_16x16x32_bf16 v[72:75], v[166:169], v[218:221], 0
	v_mfma_f32_16x16x32_bf16 v[124:127], v[162:165], v[178:181], v[124:127]
	v_mfma_f32_16x16x32_bf16 v[120:123], v[170:173], v[178:181], v[120:123]
	v_mfma_f32_16x16x32_bf16 v[108:111], v[162:165], v[186:189], v[108:111]
	v_mfma_f32_16x16x32_bf16 v[104:107], v[170:173], v[186:189], v[104:107]
	v_mfma_f32_16x16x32_bf16 v[92:95], v[162:165], v[214:217], v[92:95]
	v_mfma_f32_16x16x32_bf16 v[88:91], v[170:173], v[214:217], v[88:91]
	v_mfma_f32_16x16x32_bf16 v[76:79], v[162:165], v[222:225], v[76:79]
	v_mfma_f32_16x16x32_bf16 v[72:75], v[170:173], v[222:225], v[72:75]
	s_barrier
	s_add_i32 s21, 0, 0x14000
	s_add_i32 s42, s42, s54
	v_add_u32_e32 v140, s21, v154
	v_lshl_add_u64 v[242:243], s[38:39], 0, v[130:131]
	s_mov_b32 m0, s42
	s_nop 0
	global_load_lds_dwordx4 v[242:243], off
	v_lshl_add_u64 v[244:245], s[38:39], 0, v[128:129]
	s_add_i32 m0, s42, 0x2000
	s_nop 0
	global_load_lds_dwordx4 v[244:245], off
	ds_read_b128 v[226:229], v140
	ds_read_b128 v[230:233], v140 offset:1024
	ds_read_b128 v[234:237], v140 offset:2048
	ds_read_b128 v[238:241], v140 offset:3072
	s_barrier
	s_waitcnt lgkmcnt(0)
	v_mfma_f32_16x16x32_bf16 v[116:119], v[226:229], v[174:177], 0
	v_mfma_f32_16x16x32_bf16 v[112:115], v[234:237], v[174:177], 0
	v_mfma_f32_16x16x32_bf16 v[100:103], v[226:229], v[182:185], 0
	v_mfma_f32_16x16x32_bf16 v[96:99], v[234:237], v[182:185], 0
	v_mfma_f32_16x16x32_bf16 v[84:87], v[226:229], v[206:209], 0
	v_mfma_f32_16x16x32_bf16 v[80:83], v[234:237], v[206:209], 0
	v_mfma_f32_16x16x32_bf16 v[68:71], v[226:229], v[218:221], 0
	v_mfma_f32_16x16x32_bf16 v[64:67], v[234:237], v[218:221], 0
	v_mfma_f32_16x16x32_bf16 v[116:119], v[230:233], v[178:181], v[116:119]
	v_mfma_f32_16x16x32_bf16 v[112:115], v[238:241], v[178:181], v[112:115]
	v_mfma_f32_16x16x32_bf16 v[100:103], v[230:233], v[186:189], v[100:103]
	v_mfma_f32_16x16x32_bf16 v[96:99], v[238:241], v[186:189], v[96:99]
	v_mfma_f32_16x16x32_bf16 v[84:87], v[230:233], v[214:217], v[84:87]
	v_mfma_f32_16x16x32_bf16 v[80:83], v[238:241], v[214:217], v[80:83]
	v_mfma_f32_16x16x32_bf16 v[68:71], v[230:233], v[222:225], v[68:71]
	v_mfma_f32_16x16x32_bf16 v[64:67], v[238:241], v[222:225], v[64:67]
	s_mov_b32 m0, s79
	v_lshl_add_u64 v[246:247], s[2:3], 0, v[130:131]
	s_barrier
	global_load_lds_dwordx4 v[246:247], off
	v_lshl_add_u64 v[248:249], s[2:3], 0, v[128:129]
	s_mov_b32 m0, s34
	s_nop 0
	global_load_lds_dwordx4 v[248:249], off
	ds_read_b128 v[174:177], v155 offset:16384
	ds_read_b128 v[178:181], v155 offset:17408
	ds_read_b128 v[182:185], v155 offset:18432
	ds_read_b128 v[186:189], v155 offset:19456
	ds_read_b128 v[206:209], v155 offset:20480
	ds_read_b128 v[214:217], v155 offset:21504
	ds_read_b128 v[218:221], v155 offset:22528
	ds_read_b128 v[222:225], v155 offset:23552
	s_barrier
	s_waitcnt lgkmcnt(0)
	v_mfma_f32_16x16x32_bf16 v[60:63], v[142:145], v[174:177], 0
	v_mfma_f32_16x16x32_bf16 v[56:59], v[166:169], v[174:177], 0
	v_mfma_f32_16x16x32_bf16 v[44:47], v[142:145], v[182:185], 0
	v_mfma_f32_16x16x32_bf16 v[40:43], v[166:169], v[182:185], 0
	v_mfma_f32_16x16x32_bf16 v[28:31], v[142:145], v[206:209], 0
	v_mfma_f32_16x16x32_bf16 v[24:27], v[166:169], v[206:209], 0
	v_mfma_f32_16x16x32_bf16 v[12:15], v[142:145], v[218:221], 0
	v_mfma_f32_16x16x32_bf16 v[8:11], v[166:169], v[218:221], 0
	v_mfma_f32_16x16x32_bf16 v[60:63], v[162:165], v[178:181], v[60:63]
	v_mfma_f32_16x16x32_bf16 v[56:59], v[170:173], v[178:181], v[56:59]
	v_mfma_f32_16x16x32_bf16 v[44:47], v[162:165], v[186:189], v[44:47]
	v_mfma_f32_16x16x32_bf16 v[40:43], v[170:173], v[186:189], v[40:43]
	v_mfma_f32_16x16x32_bf16 v[28:31], v[162:165], v[214:217], v[28:31]
	v_mfma_f32_16x16x32_bf16 v[24:27], v[170:173], v[214:217], v[24:27]
	v_mfma_f32_16x16x32_bf16 v[12:15], v[162:165], v[222:225], v[12:15]
	v_mfma_f32_16x16x32_bf16 v[8:11], v[170:173], v[222:225], v[8:11]
	s_barrier
	s_add_u32 s38, s38, s88
	s_addc_u32 s39, s39, s89
	s_add_i32 s21, s21, s54
	v_lshl_add_u64 v[250:251], s[38:39], 0, v[130:131]
	s_mov_b32 m0, s21
	v_lshl_add_u64 v[252:253], s[38:39], 0, v[128:129]
	global_load_lds_dwordx4 v[250:251], off
	s_add_i32 m0, s21, 0x2000
	s_nop 0
	global_load_lds_dwordx4 v[252:253], off
	s_waitcnt vmcnt(6)
	s_barrier
	v_mfma_f32_16x16x32_bf16 v[52:55], v[226:229], v[174:177], 0
	v_mfma_f32_16x16x32_bf16 v[48:51], v[234:237], v[174:177], 0
	v_mfma_f32_16x16x32_bf16 v[36:39], v[226:229], v[182:185], 0
	v_mfma_f32_16x16x32_bf16 v[32:35], v[234:237], v[182:185], 0
	v_mfma_f32_16x16x32_bf16 v[20:23], v[226:229], v[206:209], 0
	v_mfma_f32_16x16x32_bf16 v[16:19], v[234:237], v[206:209], 0
	v_mfma_f32_16x16x32_bf16 v[4:7], v[226:229], v[218:221], 0
	v_mfma_f32_16x16x32_bf16 v[0:3], v[234:237], v[218:221], 0
	v_mfma_f32_16x16x32_bf16 v[52:55], v[230:233], v[178:181], v[52:55]
	v_mfma_f32_16x16x32_bf16 v[48:51], v[238:241], v[178:181], v[48:51]
	v_mfma_f32_16x16x32_bf16 v[36:39], v[230:233], v[186:189], v[36:39]
	v_mfma_f32_16x16x32_bf16 v[32:35], v[238:241], v[186:189], v[32:35]
	v_mfma_f32_16x16x32_bf16 v[20:23], v[230:233], v[214:217], v[20:23]
	v_mfma_f32_16x16x32_bf16 v[16:19], v[238:241], v[214:217], v[16:19]
	v_mfma_f32_16x16x32_bf16 v[4:7], v[230:233], v[222:225], v[4:7]
	v_mfma_f32_16x16x32_bf16 v[0:3], v[238:241], v[222:225], v[0:3]
	s_add_i32 s21, 0, 0x18000
	v_add_u32_e32 v140, s21, v154
	s_barrier
	s_add_u32 s2, s2, s88
	s_addc_u32 s3, s3, s89
	s_mov_b32 m0, s35
	v_lshl_add_u64 v[226:227], s[2:3], 0, v[130:131]
	global_load_lds_dwordx4 v[226:227], off
	v_lshl_add_u64 v[226:227], s[2:3], 0, v[128:129]
	s_mov_b32 m0, s44
	s_nop 0
	global_load_lds_dwordx4 v[226:227], off
	ds_read_b128 v[142:145], v140
	ds_read_b128 v[162:165], v140 offset:1024
	ds_read_b128 v[166:169], v140 offset:2048
	ds_read_b128 v[170:173], v140 offset:3072
	ds_read_b128 v[174:177], v155 offset:32768
	ds_read_b128 v[178:181], v155 offset:33792
	ds_read_b128 v[182:185], v155 offset:34816
	ds_read_b128 v[186:189], v155 offset:35840
	ds_read_b128 v[206:209], v155 offset:36864
	ds_read_b128 v[214:217], v155 offset:37888
	ds_read_b128 v[218:221], v155 offset:38912
	ds_read_b128 v[222:225], v155 offset:39936
	s_waitcnt lgkmcnt(8)
	s_barrier
	s_waitcnt lgkmcnt(0)
	v_mfma_f32_16x16x32_bf16 v[124:127], v[142:145], v[174:177], v[124:127]
	v_mfma_f32_16x16x32_bf16 v[120:123], v[166:169], v[174:177], v[120:123]
	v_mfma_f32_16x16x32_bf16 v[108:111], v[142:145], v[182:185], v[108:111]
	v_mfma_f32_16x16x32_bf16 v[104:107], v[166:169], v[182:185], v[104:107]
	v_mfma_f32_16x16x32_bf16 v[92:95], v[142:145], v[206:209], v[92:95]
	v_mfma_f32_16x16x32_bf16 v[88:91], v[166:169], v[206:209], v[88:91]
	v_mfma_f32_16x16x32_bf16 v[76:79], v[142:145], v[218:221], v[76:79]
	v_mfma_f32_16x16x32_bf16 v[72:75], v[166:169], v[218:221], v[72:75]
	v_mfma_f32_16x16x32_bf16 v[124:127], v[162:165], v[178:181], v[124:127]
	v_mfma_f32_16x16x32_bf16 v[120:123], v[170:173], v[178:181], v[120:123]
	v_mfma_f32_16x16x32_bf16 v[108:111], v[162:165], v[186:189], v[108:111]
	v_mfma_f32_16x16x32_bf16 v[104:107], v[170:173], v[186:189], v[104:107]
	v_mfma_f32_16x16x32_bf16 v[92:95], v[162:165], v[214:217], v[92:95]
	v_mfma_f32_16x16x32_bf16 v[88:91], v[170:173], v[214:217], v[88:91]
	v_mfma_f32_16x16x32_bf16 v[76:79], v[162:165], v[222:225], v[76:79]
	v_mfma_f32_16x16x32_bf16 v[72:75], v[170:173], v[222:225], v[72:75]
	s_barrier
	s_add_i32 s2, 0, 0x1c000
	s_add_i32 s3, s21, s54
	v_add_u32_e32 v140, s2, v154
	v_lshl_add_u64 v[242:243], v[242:243], 0, s[50:51]
	s_mov_b32 m0, s3
	s_nop 0
	global_load_lds_dwordx4 v[242:243], off
	v_lshl_add_u64 v[242:243], v[244:245], 0, s[50:51]
	s_add_i32 m0, s3, 0x2000
	s_nop 0
	global_load_lds_dwordx4 v[242:243], off
	ds_read_b128 v[226:229], v140
	ds_read_b128 v[230:233], v140 offset:1024
	ds_read_b128 v[234:237], v140 offset:2048
	ds_read_b128 v[238:241], v140 offset:3072
	s_barrier
	s_waitcnt lgkmcnt(0)
	v_mfma_f32_16x16x32_bf16 v[116:119], v[226:229], v[174:177], v[116:119]
	v_mfma_f32_16x16x32_bf16 v[112:115], v[234:237], v[174:177], v[112:115]
	v_mfma_f32_16x16x32_bf16 v[100:103], v[226:229], v[182:185], v[100:103]
	v_mfma_f32_16x16x32_bf16 v[96:99], v[234:237], v[182:185], v[96:99]
	v_mfma_f32_16x16x32_bf16 v[84:87], v[226:229], v[206:209], v[84:87]
	v_mfma_f32_16x16x32_bf16 v[80:83], v[234:237], v[206:209], v[80:83]
	v_mfma_f32_16x16x32_bf16 v[68:71], v[226:229], v[218:221], v[68:71]
	v_mfma_f32_16x16x32_bf16 v[64:67], v[234:237], v[218:221], v[64:67]
	v_mfma_f32_16x16x32_bf16 v[116:119], v[230:233], v[178:181], v[116:119]
	v_mfma_f32_16x16x32_bf16 v[112:115], v[238:241], v[178:181], v[112:115]
	v_mfma_f32_16x16x32_bf16 v[100:103], v[230:233], v[186:189], v[100:103]
	v_mfma_f32_16x16x32_bf16 v[96:99], v[238:241], v[186:189], v[96:99]
	v_mfma_f32_16x16x32_bf16 v[84:87], v[230:233], v[214:217], v[84:87]
	v_mfma_f32_16x16x32_bf16 v[80:83], v[238:241], v[214:217], v[80:83]
	v_mfma_f32_16x16x32_bf16 v[68:71], v[230:233], v[222:225], v[68:71]
	v_mfma_f32_16x16x32_bf16 v[64:67], v[238:241], v[222:225], v[64:67]
	s_mov_b32 m0, s82
	v_lshl_add_u64 v[242:243], v[246:247], 0, s[50:51]
	s_barrier
	global_load_lds_dwordx4 v[242:243], off
	v_lshl_add_u64 v[242:243], v[248:249], 0, s[50:51]
	s_mov_b32 m0, s83
	s_nop 0
	global_load_lds_dwordx4 v[242:243], off
	ds_read_b128 v[174:177], v155 offset:49152
	ds_read_b128 v[178:181], v155 offset:50176
	ds_read_b128 v[182:185], v155 offset:51200
	ds_read_b128 v[186:189], v155 offset:52224
	ds_read_b128 v[206:209], v155 offset:53248
	ds_read_b128 v[214:217], v155 offset:54272
	ds_read_b128 v[218:221], v155 offset:55296
	ds_read_b128 v[222:225], v155 offset:56320
	s_barrier
	s_waitcnt lgkmcnt(0)
	v_mfma_f32_16x16x32_bf16 v[60:63], v[142:145], v[174:177], v[60:63]
	v_mfma_f32_16x16x32_bf16 v[56:59], v[166:169], v[174:177], v[56:59]
	v_mfma_f32_16x16x32_bf16 v[44:47], v[142:145], v[182:185], v[44:47]
	v_mfma_f32_16x16x32_bf16 v[40:43], v[166:169], v[182:185], v[40:43]
	v_mfma_f32_16x16x32_bf16 v[28:31], v[142:145], v[206:209], v[28:31]
	v_mfma_f32_16x16x32_bf16 v[24:27], v[166:169], v[206:209], v[24:27]
	v_mfma_f32_16x16x32_bf16 v[12:15], v[142:145], v[218:221], v[12:15]
	v_mfma_f32_16x16x32_bf16 v[8:11], v[166:169], v[218:221], v[8:11]
	v_mfma_f32_16x16x32_bf16 v[60:63], v[162:165], v[178:181], v[60:63]
	v_mfma_f32_16x16x32_bf16 v[56:59], v[170:173], v[178:181], v[56:59]
	v_mfma_f32_16x16x32_bf16 v[44:47], v[162:165], v[186:189], v[44:47]
	v_mfma_f32_16x16x32_bf16 v[40:43], v[170:173], v[186:189], v[40:43]
	v_mfma_f32_16x16x32_bf16 v[28:31], v[162:165], v[214:217], v[28:31]
	v_mfma_f32_16x16x32_bf16 v[24:27], v[170:173], v[214:217], v[24:27]
	v_mfma_f32_16x16x32_bf16 v[12:15], v[162:165], v[222:225], v[12:15]
	v_mfma_f32_16x16x32_bf16 v[8:11], v[170:173], v[222:225], v[8:11]
	s_barrier
	s_add_i32 s2, s2, s54
	v_lshl_add_u64 v[142:143], v[250:251], 0, s[50:51]
	s_mov_b32 m0, s2
	s_nop 0
	global_load_lds_dwordx4 v[142:143], off
	v_lshl_add_u64 v[142:143], v[252:253], 0, s[50:51]
	s_add_i32 m0, s2, 0x2000
	s_nop 0
	global_load_lds_dwordx4 v[142:143], off
	s_waitcnt vmcnt(6)
	s_barrier
	v_mfma_f32_16x16x32_bf16 v[52:55], v[226:229], v[174:177], v[52:55]
	v_mfma_f32_16x16x32_bf16 v[48:51], v[234:237], v[174:177], v[48:51]
	v_mfma_f32_16x16x32_bf16 v[36:39], v[226:229], v[182:185], v[36:39]
	v_mfma_f32_16x16x32_bf16 v[32:35], v[234:237], v[182:185], v[32:35]
	v_mfma_f32_16x16x32_bf16 v[20:23], v[226:229], v[206:209], v[20:23]
	v_mfma_f32_16x16x32_bf16 v[16:19], v[234:237], v[206:209], v[16:19]
	v_mfma_f32_16x16x32_bf16 v[4:7], v[226:229], v[218:221], v[4:7]
	v_mfma_f32_16x16x32_bf16 v[0:3], v[234:237], v[218:221], v[0:3]
	v_mfma_f32_16x16x32_bf16 v[52:55], v[230:233], v[178:181], v[52:55]
	v_mfma_f32_16x16x32_bf16 v[48:51], v[238:241], v[178:181], v[48:51]
	v_mfma_f32_16x16x32_bf16 v[36:39], v[230:233], v[186:189], v[36:39]
	v_mfma_f32_16x16x32_bf16 v[32:35], v[238:241], v[186:189], v[32:35]
	v_mfma_f32_16x16x32_bf16 v[20:23], v[230:233], v[214:217], v[20:23]
	v_mfma_f32_16x16x32_bf16 v[16:19], v[238:241], v[214:217], v[16:19]
	v_mfma_f32_16x16x32_bf16 v[4:7], v[230:233], v[222:225], v[4:7]
	v_mfma_f32_16x16x32_bf16 v[0:3], v[238:241], v[222:225], v[0:3]
	s_add_u32 s10, s10, 0x100
	s_addc_u32 s40, s40, 0
	s_add_u32 s6, s6, 0x100
	s_addc_u32 s7, s7, 0
	s_cmp_ge_i32 s41, s66
	s_mov_b32 s2, s41
	s_barrier
	s_cbranch_scc1 .Lpost_197
.LBB0_197:
	s_add_i32 s41, s2, 2
	s_add_u32 s21, s6, 0x80
	s_addc_u32 s3, s7, 0
	s_add_i32 s42, 0, 0x10000
	v_add_u32_e32 v140, s42, v154
	ds_read_b128 v[142:145], v140
	ds_read_b128 v[162:165], v140 offset:1024
	ds_read_b128 v[166:169], v140 offset:2048
	ds_read_b128 v[170:173], v140 offset:3072
	s_cmp_eq_u32 s9, s2
	s_cselect_b32 s2, s68, s21
	s_cselect_b32 s3, s69, s3
	s_cselect_b32 s39, s95, s40
	s_cselect_b32 s38, s94, s10
	v_lshl_add_u64 v[226:227], s[6:7], 0, v[138:139]
	s_add_i32 m0, s79, 0xc000
	s_nop 0
	global_load_lds_dwordx4 v[226:227], off
	v_lshl_add_u64 v[226:227], s[6:7], 0, v[136:137]
	s_add_i32 m0, s79, 0xe000
	s_nop 0
	global_load_lds_dwordx4 v[226:227], off
	ds_read_b128 v[174:177], v155
	ds_read_b128 v[178:181], v155 offset:1024
	ds_read_b128 v[182:185], v155 offset:2048
	ds_read_b128 v[186:189], v155 offset:3072
	ds_read_b128 v[206:209], v155 offset:4096
	ds_read_b128 v[214:217], v155 offset:5120
	ds_read_b128 v[218:221], v155 offset:6144
	ds_read_b128 v[222:225], v155 offset:7168
	s_waitcnt lgkmcnt(8)
	s_barrier
	s_waitcnt lgkmcnt(0)
	v_mfma_f32_16x16x32_bf16 v[124:127], v[142:145], v[174:177], v[124:127]
	v_mfma_f32_16x16x32_bf16 v[120:123], v[166:169], v[174:177], v[120:123]
	v_mfma_f32_16x16x32_bf16 v[108:111], v[142:145], v[182:185], v[108:111]
	v_mfma_f32_16x16x32_bf16 v[104:107], v[166:169], v[182:185], v[104:107]
	v_mfma_f32_16x16x32_bf16 v[92:95], v[142:145], v[206:209], v[92:95]
	v_mfma_f32_16x16x32_bf16 v[88:91], v[166:169], v[206:209], v[88:91]
	v_mfma_f32_16x16x32_bf16 v[76:79], v[142:145], v[218:221], v[76:79]
	v_mfma_f32_16x16x32_bf16 v[72:75], v[166:169], v[218:221], v[72:75]
	v_mfma_f32_16x16x32_bf16 v[124:127], v[162:165], v[178:181], v[124:127]
	v_mfma_f32_16x16x32_bf16 v[120:123], v[170:173], v[178:181], v[120:123]
	v_mfma_f32_16x16x32_bf16 v[108:111], v[162:165], v[186:189], v[108:111]
	v_mfma_f32_16x16x32_bf16 v[104:107], v[170:173], v[186:189], v[104:107]
	v_mfma_f32_16x16x32_bf16 v[92:95], v[162:165], v[214:217], v[92:95]
	v_mfma_f32_16x16x32_bf16 v[88:91], v[170:173], v[214:217], v[88:91]
	v_mfma_f32_16x16x32_bf16 v[76:79], v[162:165], v[222:225], v[76:79]
	v_mfma_f32_16x16x32_bf16 v[72:75], v[170:173], v[222:225], v[72:75]
	s_barrier
	s_add_i32 s21, 0, 0x14000
	s_add_i32 s42, s42, s54
	v_add_u32_e32 v140, s21, v154
	v_lshl_add_u64 v[242:243], s[38:39], 0, v[130:131]
	s_mov_b32 m0, s42
	s_nop 0
	global_load_lds_dwordx4 v[242:243], off
	v_lshl_add_u64 v[244:245], s[38:39], 0, v[128:129]
	s_add_i32 m0, s42, 0x2000
	s_nop 0
	global_load_lds_dwordx4 v[244:245], off
	ds_read_b128 v[226:229], v140
	ds_read_b128 v[230:233], v140 offset:1024
	ds_read_b128 v[234:237], v140 offset:2048
	ds_read_b128 v[238:241], v140 offset:3072
	s_barrier
	s_waitcnt lgkmcnt(0)
	v_mfma_f32_16x16x32_bf16 v[116:119], v[226:229], v[174:177], v[116:119]
	v_mfma_f32_16x16x32_bf16 v[112:115], v[234:237], v[174:177], v[112:115]
	v_mfma_f32_16x16x32_bf16 v[100:103], v[226:229], v[182:185], v[100:103]
	v_mfma_f32_16x16x32_bf16 v[96:99], v[234:237], v[182:185], v[96:99]
	v_mfma_f32_16x16x32_bf16 v[84:87], v[226:229], v[206:209], v[84:87]
	v_mfma_f32_16x16x32_bf16 v[80:83], v[234:237], v[206:209], v[80:83]
	v_mfma_f32_16x16x32_bf16 v[68:71], v[226:229], v[218:221], v[68:71]
	v_mfma_f32_16x16x32_bf16 v[64:67], v[234:237], v[218:221], v[64:67]
	v_mfma_f32_16x16x32_bf16 v[116:119], v[230:233], v[178:181], v[116:119]
	v_mfma_f32_16x16x32_bf16 v[112:115], v[238:241], v[178:181], v[112:115]
	v_mfma_f32_16x16x32_bf16 v[100:103], v[230:233], v[186:189], v[100:103]
	v_mfma_f32_16x16x32_bf16 v[96:99], v[238:241], v[186:189], v[96:99]
	v_mfma_f32_16x16x32_bf16 v[84:87], v[230:233], v[214:217], v[84:87]
	v_mfma_f32_16x16x32_bf16 v[80:83], v[238:241], v[214:217], v[80:83]
	v_mfma_f32_16x16x32_bf16 v[68:71], v[230:233], v[222:225], v[68:71]
	v_mfma_f32_16x16x32_bf16 v[64:67], v[238:241], v[222:225], v[64:67]
	s_mov_b32 m0, s79
	v_lshl_add_u64 v[246:247], s[2:3], 0, v[130:131]
	s_barrier
	global_load_lds_dwordx4 v[246:247], off
	v_lshl_add_u64 v[248:249], s[2:3], 0, v[128:129]
	s_mov_b32 m0, s34
	s_nop 0
	global_load_lds_dwordx4 v[248:249], off
	ds_read_b128 v[174:177], v155 offset:16384
	ds_read_b128 v[178:181], v155 offset:17408
	ds_read_b128 v[182:185], v155 offset:18432
	ds_read_b128 v[186:189], v155 offset:19456
	ds_read_b128 v[206:209], v155 offset:20480
	ds_read_b128 v[214:217], v155 offset:21504
	ds_read_b128 v[218:221], v155 offset:22528
	ds_read_b128 v[222:225], v155 offset:23552
	s_barrier
	s_waitcnt lgkmcnt(0)
	v_mfma_f32_16x16x32_bf16 v[60:63], v[142:145], v[174:177], v[60:63]
	v_mfma_f32_16x16x32_bf16 v[56:59], v[166:169], v[174:177], v[56:59]
	v_mfma_f32_16x16x32_bf16 v[44:47], v[142:145], v[182:185], v[44:47]
	v_mfma_f32_16x16x32_bf16 v[40:43], v[166:169], v[182:185], v[40:43]
	v_mfma_f32_16x16x32_bf16 v[28:31], v[142:145], v[206:209], v[28:31]
	v_mfma_f32_16x16x32_bf16 v[24:27], v[166:169], v[206:209], v[24:27]
	v_mfma_f32_16x16x32_bf16 v[12:15], v[142:145], v[218:221], v[12:15]
	v_mfma_f32_16x16x32_bf16 v[8:11], v[166:169], v[218:221], v[8:11]
	v_mfma_f32_16x16x32_bf16 v[60:63], v[162:165], v[178:181], v[60:63]
	v_mfma_f32_16x16x32_bf16 v[56:59], v[170:173], v[178:181], v[56:59]
	v_mfma_f32_16x16x32_bf16 v[44:47], v[162:165], v[186:189], v[44:47]
	v_mfma_f32_16x16x32_bf16 v[40:43], v[170:173], v[186:189], v[40:43]
	v_mfma_f32_16x16x32_bf16 v[28:31], v[162:165], v[214:217], v[28:31]
	v_mfma_f32_16x16x32_bf16 v[24:27], v[170:173], v[214:217], v[24:27]
	v_mfma_f32_16x16x32_bf16 v[12:15], v[162:165], v[222:225], v[12:15]
	v_mfma_f32_16x16x32_bf16 v[8:11], v[170:173], v[222:225], v[8:11]
	s_barrier
	s_add_u32 s38, s38, s88
	s_addc_u32 s39, s39, s89
	s_add_i32 s21, s21, s54
	v_lshl_add_u64 v[250:251], s[38:39], 0, v[130:131]
	s_mov_b32 m0, s21
	v_lshl_add_u64 v[252:253], s[38:39], 0, v[128:129]
	global_load_lds_dwordx4 v[250:251], off
	s_add_i32 m0, s21, 0x2000
	s_nop 0
	global_load_lds_dwordx4 v[252:253], off
	s_waitcnt vmcnt(6)
	s_barrier
	v_mfma_f32_16x16x32_bf16 v[52:55], v[226:229], v[174:177], v[52:55]
	v_mfma_f32_16x16x32_bf16 v[48:51], v[234:237], v[174:177], v[48:51]
	v_mfma_f32_16x16x32_bf16 v[36:39], v[226:229], v[182:185], v[36:39]
	v_mfma_f32_16x16x32_bf16 v[32:35], v[234:237], v[182:185], v[32:35]
	v_mfma_f32_16x16x32_bf16 v[20:23], v[226:229], v[206:209], v[20:23]
	v_mfma_f32_16x16x32_bf16 v[16:19], v[234:237], v[206:209], v[16:19]
	v_mfma_f32_16x16x32_bf16 v[4:7], v[226:229], v[218:221], v[4:7]
	v_mfma_f32_16x16x32_bf16 v[0:3], v[234:237], v[218:221], v[0:3]
	v_mfma_f32_16x16x32_bf16 v[52:55], v[230:233], v[178:181], v[52:55]
	v_mfma_f32_16x16x32_bf16 v[48:51], v[238:241], v[178:181], v[48:51]
	v_mfma_f32_16x16x32_bf16 v[36:39], v[230:233], v[186:189], v[36:39]
	v_mfma_f32_16x16x32_bf16 v[32:35], v[238:241], v[186:189], v[32:35]
	v_mfma_f32_16x16x32_bf16 v[20:23], v[230:233], v[214:217], v[20:23]
	v_mfma_f32_16x16x32_bf16 v[16:19], v[238:241], v[214:217], v[16:19]
	v_mfma_f32_16x16x32_bf16 v[4:7], v[230:233], v[222:225], v[4:7]
	v_mfma_f32_16x16x32_bf16 v[0:3], v[238:241], v[222:225], v[0:3]
	s_add_i32 s21, 0, 0x18000
	v_add_u32_e32 v140, s21, v154
	s_barrier
	ds_read_b128 v[142:145], v140
	ds_read_b128 v[162:165], v140 offset:1024
	ds_read_b128 v[166:169], v140 offset:2048
	ds_read_b128 v[170:173], v140 offset:3072
	s_add_u32 s2, s2, s88
	s_addc_u32 s3, s3, s89
	s_mov_b32 m0, s35
	v_lshl_add_u64 v[226:227], s[2:3], 0, v[130:131]
	global_load_lds_dwordx4 v[226:227], off
	v_lshl_add_u64 v[226:227], s[2:3], 0, v[128:129]
	s_mov_b32 m0, s44
	s_nop 0
	global_load_lds_dwordx4 v[226:227], off
	ds_read_b128 v[174:177], v155 offset:32768
	ds_read_b128 v[178:181], v155 offset:33792
	ds_read_b128 v[182:185], v155 offset:34816
	ds_read_b128 v[186:189], v155 offset:35840
	ds_read_b128 v[206:209], v155 offset:36864
	ds_read_b128 v[214:217], v155 offset:37888
	ds_read_b128 v[218:221], v155 offset:38912
	ds_read_b128 v[222:225], v155 offset:39936
	s_waitcnt lgkmcnt(8)
	s_barrier
	s_waitcnt lgkmcnt(0)
	v_mfma_f32_16x16x32_bf16 v[124:127], v[142:145], v[174:177], v[124:127]
	v_mfma_f32_16x16x32_bf16 v[120:123], v[166:169], v[174:177], v[120:123]
	v_mfma_f32_16x16x32_bf16 v[108:111], v[142:145], v[182:185], v[108:111]
	v_mfma_f32_16x16x32_bf16 v[104:107], v[166:169], v[182:185], v[104:107]
	v_mfma_f32_16x16x32_bf16 v[92:95], v[142:145], v[206:209], v[92:95]
	v_mfma_f32_16x16x32_bf16 v[88:91], v[166:169], v[206:209], v[88:91]
	v_mfma_f32_16x16x32_bf16 v[76:79], v[142:145], v[218:221], v[76:79]
	v_mfma_f32_16x16x32_bf16 v[72:75], v[166:169], v[218:221], v[72:75]
	v_mfma_f32_16x16x32_bf16 v[124:127], v[162:165], v[178:181], v[124:127]
	v_mfma_f32_16x16x32_bf16 v[120:123], v[170:173], v[178:181], v[120:123]
	v_mfma_f32_16x16x32_bf16 v[108:111], v[162:165], v[186:189], v[108:111]
	v_mfma_f32_16x16x32_bf16 v[104:107], v[170:173], v[186:189], v[104:107]
	v_mfma_f32_16x16x32_bf16 v[92:95], v[162:165], v[214:217], v[92:95]
	v_mfma_f32_16x16x32_bf16 v[88:91], v[170:173], v[214:217], v[88:91]
	v_mfma_f32_16x16x32_bf16 v[76:79], v[162:165], v[222:225], v[76:79]
	v_mfma_f32_16x16x32_bf16 v[72:75], v[170:173], v[222:225], v[72:75]
	s_barrier
	s_add_i32 s2, 0, 0x1c000
	s_add_i32 s3, s21, s54
	v_add_u32_e32 v140, s2, v154
	v_lshl_add_u64 v[242:243], v[242:243], 0, s[50:51]
	s_mov_b32 m0, s3
	s_nop 0
	global_load_lds_dwordx4 v[242:243], off
	v_lshl_add_u64 v[242:243], v[244:245], 0, s[50:51]
	s_add_i32 m0, s3, 0x2000
	s_nop 0
	global_load_lds_dwordx4 v[242:243], off
	ds_read_b128 v[226:229], v140
	ds_read_b128 v[230:233], v140 offset:1024
	ds_read_b128 v[234:237], v140 offset:2048
	ds_read_b128 v[238:241], v140 offset:3072
	s_barrier
	s_waitcnt lgkmcnt(0)
	v_mfma_f32_16x16x32_bf16 v[116:119], v[226:229], v[174:177], v[116:119]
	v_mfma_f32_16x16x32_bf16 v[112:115], v[234:237], v[174:177], v[112:115]
	v_mfma_f32_16x16x32_bf16 v[100:103], v[226:229], v[182:185], v[100:103]
	v_mfma_f32_16x16x32_bf16 v[96:99], v[234:237], v[182:185], v[96:99]
	v_mfma_f32_16x16x32_bf16 v[84:87], v[226:229], v[206:209], v[84:87]
	v_mfma_f32_16x16x32_bf16 v[80:83], v[234:237], v[206:209], v[80:83]
	v_mfma_f32_16x16x32_bf16 v[68:71], v[226:229], v[218:221], v[68:71]
	v_mfma_f32_16x16x32_bf16 v[64:67], v[234:237], v[218:221], v[64:67]
	v_mfma_f32_16x16x32_bf16 v[116:119], v[230:233], v[178:181], v[116:119]
	v_mfma_f32_16x16x32_bf16 v[112:115], v[238:241], v[178:181], v[112:115]
	v_mfma_f32_16x16x32_bf16 v[100:103], v[230:233], v[186:189], v[100:103]
	v_mfma_f32_16x16x32_bf16 v[96:99], v[238:241], v[186:189], v[96:99]
	v_mfma_f32_16x16x32_bf16 v[84:87], v[230:233], v[214:217], v[84:87]
	v_mfma_f32_16x16x32_bf16 v[80:83], v[238:241], v[214:217], v[80:83]
	v_mfma_f32_16x16x32_bf16 v[68:71], v[230:233], v[222:225], v[68:71]
	v_mfma_f32_16x16x32_bf16 v[64:67], v[238:241], v[222:225], v[64:67]
	s_mov_b32 m0, s82
	v_lshl_add_u64 v[242:243], v[246:247], 0, s[50:51]
	s_barrier
	global_load_lds_dwordx4 v[242:243], off
	v_lshl_add_u64 v[242:243], v[248:249], 0, s[50:51]
	s_mov_b32 m0, s83
	s_nop 0
	global_load_lds_dwordx4 v[242:243], off
	ds_read_b128 v[174:177], v155 offset:49152
	ds_read_b128 v[178:181], v155 offset:50176
	ds_read_b128 v[182:185], v155 offset:51200
	ds_read_b128 v[186:189], v155 offset:52224
	ds_read_b128 v[206:209], v155 offset:53248
	ds_read_b128 v[214:217], v155 offset:54272
	ds_read_b128 v[218:221], v155 offset:55296
	ds_read_b128 v[222:225], v155 offset:56320
	s_barrier
	s_waitcnt lgkmcnt(0)
	v_mfma_f32_16x16x32_bf16 v[60:63], v[142:145], v[174:177], v[60:63]
	v_mfma_f32_16x16x32_bf16 v[56:59], v[166:169], v[174:177], v[56:59]
	v_mfma_f32_16x16x32_bf16 v[44:47], v[142:145], v[182:185], v[44:47]
	v_mfma_f32_16x16x32_bf16 v[40:43], v[166:169], v[182:185], v[40:43]
	v_mfma_f32_16x16x32_bf16 v[28:31], v[142:145], v[206:209], v[28:31]
	v_mfma_f32_16x16x32_bf16 v[24:27], v[166:169], v[206:209], v[24:27]
	v_mfma_f32_16x16x32_bf16 v[12:15], v[142:145], v[218:221], v[12:15]
	v_mfma_f32_16x16x32_bf16 v[8:11], v[166:169], v[218:221], v[8:11]
	v_mfma_f32_16x16x32_bf16 v[60:63], v[162:165], v[178:181], v[60:63]
	v_mfma_f32_16x16x32_bf16 v[56:59], v[170:173], v[178:181], v[56:59]
	v_mfma_f32_16x16x32_bf16 v[44:47], v[162:165], v[186:189], v[44:47]
	v_mfma_f32_16x16x32_bf16 v[40:43], v[170:173], v[186:189], v[40:43]
	v_mfma_f32_16x16x32_bf16 v[28:31], v[162:165], v[214:217], v[28:31]
	v_mfma_f32_16x16x32_bf16 v[24:27], v[170:173], v[214:217], v[24:27]
	v_mfma_f32_16x16x32_bf16 v[12:15], v[162:165], v[222:225], v[12:15]
	v_mfma_f32_16x16x32_bf16 v[8:11], v[170:173], v[222:225], v[8:11]
	s_barrier
	s_add_i32 s2, s2, s54
	v_lshl_add_u64 v[142:143], v[250:251], 0, s[50:51]
	s_mov_b32 m0, s2
	s_nop 0
	global_load_lds_dwordx4 v[142:143], off
	v_lshl_add_u64 v[142:143], v[252:253], 0, s[50:51]
	s_add_i32 m0, s2, 0x2000
	s_nop 0
	global_load_lds_dwordx4 v[142:143], off
	s_waitcnt vmcnt(6)
	s_barrier
	v_mfma_f32_16x16x32_bf16 v[52:55], v[226:229], v[174:177], v[52:55]
	v_mfma_f32_16x16x32_bf16 v[48:51], v[234:237], v[174:177], v[48:51]
	v_mfma_f32_16x16x32_bf16 v[36:39], v[226:229], v[182:185], v[36:39]
	v_mfma_f32_16x16x32_bf16 v[32:35], v[234:237], v[182:185], v[32:35]
	v_mfma_f32_16x16x32_bf16 v[20:23], v[226:229], v[206:209], v[20:23]
	v_mfma_f32_16x16x32_bf16 v[16:19], v[234:237], v[206:209], v[16:19]
	v_mfma_f32_16x16x32_bf16 v[4:7], v[226:229], v[218:221], v[4:7]
	v_mfma_f32_16x16x32_bf16 v[0:3], v[234:237], v[218:221], v[0:3]
	v_mfma_f32_16x16x32_bf16 v[52:55], v[230:233], v[178:181], v[52:55]
	v_mfma_f32_16x16x32_bf16 v[48:51], v[238:241], v[178:181], v[48:51]
	v_mfma_f32_16x16x32_bf16 v[36:39], v[230:233], v[186:189], v[36:39]
	v_mfma_f32_16x16x32_bf16 v[32:35], v[238:241], v[186:189], v[32:35]
	v_mfma_f32_16x16x32_bf16 v[20:23], v[230:233], v[214:217], v[20:23]
	v_mfma_f32_16x16x32_bf16 v[16:19], v[238:241], v[214:217], v[16:19]
	v_mfma_f32_16x16x32_bf16 v[4:7], v[230:233], v[222:225], v[4:7]
	v_mfma_f32_16x16x32_bf16 v[0:3], v[238:241], v[222:225], v[0:3]
	s_add_u32 s10, s10, 0x100
	s_addc_u32 s40, s40, 0
	s_add_u32 s6, s6, 0x100
	s_addc_u32 s7, s7, 0
	s_cmp_ge_i32 s41, s66
	s_mov_b32 s2, s41
	s_barrier
	s_cbranch_scc0 .LBB0_197

.LBB0_270:
	v_lshl_add_u64 v[0:1], s[40:41], 0, v[156:157]
	v_mov_b32_e32 v129, v157
	v_lshl_add_u64 v[4:5], s[2:3], 0, v[156:157]
	v_lshl_add_u64 v[6:7], s[2:3], 0, v[128:129]
	s_lshl_b32 s2, s19, 5
	s_add_i32 m0, s25, 0x18000
	v_lshl_add_u64 v[0:1], v[0:1], 0, s[50:51]
	s_and_b32 s19, s2, 0x60
	s_waitcnt vmcnt(4)
	s_barrier
	global_load_lds_dwordx4 v[0:1], off
	s_add_i32 m0, s25, 0x1a000
	v_lshl_add_u64 v[2:3], s[40:41], 0, v[128:129]
	s_add_u32 s2, s26, 0x1a4a4080
	v_lshl_add_u64 v[0:1], v[2:3], 0, s[50:51]
	s_addc_u32 s3, s27, 0
	s_add_i32 s45, s25, 0x8000
	global_load_lds_dwordx4 v[0:1], off
	v_lshl_add_u64 v[0:1], s[2:3], 0, v[156:157]
	s_mov_b32 m0, s45
	s_add_i32 s48, s25, 0xa000
	global_load_lds_dwordx4 v[0:1], off
	v_lshl_add_u64 v[0:1], s[2:3], 0, v[128:129]
	s_mov_b32 m0, s48
	v_mov_b32_e32 v127, 0
	global_load_lds_dwordx4 v[0:1], off
	s_add_i32 m0, s25, 0x1c000
	v_lshl_add_u64 v[0:1], v[4:5], 0, s[50:51]
	global_load_lds_dwordx4 v[0:1], off
	v_lshl_add_u64 v[0:1], v[6:7], 0, s[50:51]
	s_add_i32 m0, s25, 0x1e000
	v_lshl_or_b32 v134, s42, 6, v149
	global_load_lds_dwordx4 v[0:1], off
	s_waitcnt vmcnt(6)
	s_cmp_lt_i32 s6, 64
	v_mov_b32_e32 v126, v127
	v_mov_b32_e32 v125, v127
	v_mov_b32_e32 v124, v127
	v_mov_b32_e32 v123, v127
	v_mov_b32_e32 v122, v127
	v_mov_b32_e32 v121, v127
	v_mov_b32_e32 v120, v127
	v_mov_b32_e32 v111, v127
	v_mov_b32_e32 v110, v127
	v_mov_b32_e32 v109, v127
	v_mov_b32_e32 v108, v127
	v_mov_b32_e32 v107, v127
	v_mov_b32_e32 v106, v127
	v_mov_b32_e32 v105, v127
	v_mov_b32_e32 v104, v127
	v_mov_b32_e32 v95, v127
	v_mov_b32_e32 v94, v127
	v_mov_b32_e32 v93, v127
	v_mov_b32_e32 v92, v127
	v_mov_b32_e32 v91, v127
	v_mov_b32_e32 v90, v127
	v_mov_b32_e32 v89, v127
	v_mov_b32_e32 v88, v127
	v_mov_b32_e32 v79, v127
	v_mov_b32_e32 v78, v127
	v_mov_b32_e32 v77, v127
	v_mov_b32_e32 v76, v127
	v_mov_b32_e32 v75, v127
	v_mov_b32_e32 v74, v127
	v_mov_b32_e32 v73, v127
	v_mov_b32_e32 v72, v127
	v_mov_b32_e32 v119, v127
	v_mov_b32_e32 v118, v127
	v_mov_b32_e32 v117, v127
	v_mov_b32_e32 v116, v127
	v_mov_b32_e32 v115, v127
	v_mov_b32_e32 v114, v127
	v_mov_b32_e32 v113, v127
	v_mov_b32_e32 v112, v127
	v_mov_b32_e32 v103, v127
	v_mov_b32_e32 v102, v127
	v_mov_b32_e32 v101, v127
	v_mov_b32_e32 v100, v127
	v_mov_b32_e32 v99, v127
	v_mov_b32_e32 v98, v127
	v_mov_b32_e32 v97, v127
	v_mov_b32_e32 v96, v127
	v_mov_b32_e32 v87, v127
	v_mov_b32_e32 v86, v127
	v_mov_b32_e32 v85, v127
	v_mov_b32_e32 v84, v127
	v_mov_b32_e32 v83, v127
	v_mov_b32_e32 v82, v127
	v_mov_b32_e32 v81, v127
	v_mov_b32_e32 v80, v127
	v_mov_b32_e32 v71, v127
	v_mov_b32_e32 v70, v127
	v_mov_b32_e32 v69, v127
	v_mov_b32_e32 v68, v127
	v_mov_b32_e32 v67, v127
	v_mov_b32_e32 v66, v127
	v_mov_b32_e32 v65, v127
	v_mov_b32_e32 v64, v127
	v_mov_b32_e32 v63, v127
	v_mov_b32_e32 v62, v127
	v_mov_b32_e32 v61, v127
	v_mov_b32_e32 v60, v127
	v_mov_b32_e32 v59, v127
	v_mov_b32_e32 v58, v127
	v_mov_b32_e32 v57, v127
	v_mov_b32_e32 v56, v127
	v_mov_b32_e32 v47, v127
	v_mov_b32_e32 v46, v127
	v_mov_b32_e32 v45, v127
	v_mov_b32_e32 v44, v127
	v_mov_b32_e32 v43, v127
	v_mov_b32_e32 v42, v127
	v_mov_b32_e32 v41, v127
	v_mov_b32_e32 v40, v127
	v_mov_b32_e32 v31, v127
	v_mov_b32_e32 v30, v127
	v_mov_b32_e32 v29, v127
	v_mov_b32_e32 v28, v127
	v_mov_b32_e32 v27, v127
	v_mov_b32_e32 v26, v127
	v_mov_b32_e32 v25, v127
	v_mov_b32_e32 v24, v127
	v_mov_b32_e32 v15, v127
	v_mov_b32_e32 v14, v127
	v_mov_b32_e32 v13, v127
	v_mov_b32_e32 v12, v127
	v_mov_b32_e32 v11, v127
	v_mov_b32_e32 v10, v127
	v_mov_b32_e32 v9, v127
	v_mov_b32_e32 v8, v127
	v_mov_b32_e32 v55, v127
	v_mov_b32_e32 v54, v127
	v_mov_b32_e32 v53, v127
	v_mov_b32_e32 v52, v127
	v_mov_b32_e32 v51, v127
	v_mov_b32_e32 v50, v127
	v_mov_b32_e32 v49, v127
	v_mov_b32_e32 v48, v127
	v_mov_b32_e32 v39, v127
	v_mov_b32_e32 v38, v127
	v_mov_b32_e32 v37, v127
	v_mov_b32_e32 v36, v127
	v_mov_b32_e32 v35, v127
	v_mov_b32_e32 v34, v127
	v_mov_b32_e32 v33, v127
	v_mov_b32_e32 v32, v127
	v_mov_b32_e32 v23, v127
	v_mov_b32_e32 v22, v127
	v_mov_b32_e32 v21, v127
	v_mov_b32_e32 v20, v127
	v_mov_b32_e32 v19, v127
	v_mov_b32_e32 v18, v127
	v_mov_b32_e32 v17, v127
	v_mov_b32_e32 v16, v127
	v_mov_b32_e32 v7, v127
	v_mov_b32_e32 v6, v127
	v_mov_b32_e32 v5, v127
	v_mov_b32_e32 v4, v127
	v_mov_b32_e32 v3, v127
	v_mov_b32_e32 v2, v127
	v_mov_b32_e32 v1, v127
	v_mov_b32_e32 v0, v127
	s_barrier
	s_cbranch_scc1 .LBB0_273
	s_lshr_b32 s2, s7, 26
	s_add_i32 s2, s6, s2
	s_ashr_i32 s49, s2, 6
	v_lshlrev_b32_e32 v0, 6, v134
	s_movk_i32 s2, 0x3c0
	v_lshlrev_b32_e32 v1, 2, v134
	s_add_i32 s53, s49, -2
	v_and_or_b32 v0, v0, s2, v147
	s_lshl_b32 s2, s42, 13
	v_and_b32_e32 v1, 32, v1
	v_bitop3_b32 v2, v0, s2, v1 bitop3:0xde
	s_add_u32 s2, s26, s36
	v_add_u32_e32 v0, v132, v133
	s_addc_u32 s3, s27, s37
	v_add_lshl_u32 v0, v0, v146, 1
	v_mov_b32_e32 v1, v157
	v_lshl_add_u64 v[132:133], s[2:3], 0, v[0:1]
	v_lshl_or_b32 v135, s19, 7, v148
	v_lshl_add_u64 v[130:131], s[2:3], 0, v[128:129]
	s_mov_b32 s2, 0
	s_mov_b64 s[6:7], 0x1a4a4080
	v_add_u32_e32 v136, 0, v2
	s_add_i32 s54, s2, 2
	s_add_u32 s3, s6, 0xe5b5c080
	s_addc_u32 s21, s7, -1
	s_cmp_lg_u32 s53, s2
	s_cselect_b32 s42, s3, 0
	s_cselect_b32 s21, s21, 0
	s_add_u32 s2, s38, s42
	s_addc_u32 s3, s39, s21
	s_add_i32 s55, 0, 0x10000
	v_add_u32_e32 v137, s55, v135
	s_add_u32 s42, s40, s42
	s_addc_u32 s43, s41, s21
	v_lshl_add_u64 v[138:139], v[132:133], 0, s[6:7]
	s_add_i32 m0, s25, 0xc000
	s_nop 0
	global_load_lds_dwordx4 v[138:139], off
	v_lshl_add_u64 v[138:139], v[130:131], 0, s[6:7]
	s_add_i32 m0, s25, 0xe000
	s_nop 0
	global_load_lds_dwordx4 v[138:139], off
	ds_read_b128 v[142:145], v137
	ds_read_b128 v[146:149], v137 offset:1024
	ds_read_b128 v[150:153], v137 offset:2048
	ds_read_b128 v[162:165], v137 offset:3072
	ds_read_b128 v[166:169], v136
	ds_read_b128 v[170:173], v136 offset:1024
	ds_read_b128 v[174:177], v136 offset:2048
	ds_read_b128 v[178:181], v136 offset:3072
	ds_read_b128 v[182:185], v136 offset:4096
	ds_read_b128 v[186:189], v136 offset:5120
	ds_read_b128 v[206:209], v136 offset:6144
	ds_read_b128 v[214:217], v136 offset:7168
	s_waitcnt lgkmcnt(8)
	s_barrier
	s_waitcnt lgkmcnt(0)
	v_mfma_f32_16x16x32_bf16 v[124:127], v[142:145], v[166:169], 0
	v_mfma_f32_16x16x32_bf16 v[120:123], v[150:153], v[166:169], 0
	v_mfma_f32_16x16x32_bf16 v[108:111], v[142:145], v[174:177], 0
	v_mfma_f32_16x16x32_bf16 v[104:107], v[150:153], v[174:177], 0
	v_mfma_f32_16x16x32_bf16 v[92:95], v[142:145], v[182:185], 0
	v_mfma_f32_16x16x32_bf16 v[88:91], v[150:153], v[182:185], 0
	v_mfma_f32_16x16x32_bf16 v[76:79], v[142:145], v[206:209], 0
	v_mfma_f32_16x16x32_bf16 v[72:75], v[150:153], v[206:209], 0
	v_mfma_f32_16x16x32_bf16 v[124:127], v[146:149], v[170:173], v[124:127]
	v_mfma_f32_16x16x32_bf16 v[120:123], v[162:165], v[170:173], v[120:123]
	v_mfma_f32_16x16x32_bf16 v[108:111], v[146:149], v[178:181], v[108:111]
	v_mfma_f32_16x16x32_bf16 v[104:107], v[162:165], v[178:181], v[104:107]
	v_mfma_f32_16x16x32_bf16 v[92:95], v[146:149], v[186:189], v[92:95]
	v_mfma_f32_16x16x32_bf16 v[88:91], v[162:165], v[186:189], v[88:91]
	v_mfma_f32_16x16x32_bf16 v[76:79], v[146:149], v[214:217], v[76:79]
	v_mfma_f32_16x16x32_bf16 v[72:75], v[162:165], v[214:217], v[72:75]
	s_barrier
	s_add_i32 s21, 0, 0x14000
	s_add_i32 s55, s55, s24
	v_add_u32_e32 v137, s21, v135
	v_lshl_add_u64 v[138:139], s[42:43], 0, v[156:157]
	s_mov_b32 m0, s55
	s_nop 0
	global_load_lds_dwordx4 v[138:139], off
	v_lshl_add_u64 v[154:155], s[42:43], 0, v[128:129]
	s_add_i32 m0, s55, 0x2000
	s_nop 0
	global_load_lds_dwordx4 v[154:155], off
	ds_read_b128 v[218:221], v137
	ds_read_b128 v[222:225], v137 offset:1024
	ds_read_b128 v[226:229], v137 offset:2048
	ds_read_b128 v[230:233], v137 offset:3072
	s_barrier
	s_waitcnt lgkmcnt(0)
	v_mfma_f32_16x16x32_bf16 v[116:119], v[218:221], v[166:169], 0
	v_mfma_f32_16x16x32_bf16 v[112:115], v[226:229], v[166:169], 0
	v_mfma_f32_16x16x32_bf16 v[100:103], v[218:221], v[174:177], 0
	v_mfma_f32_16x16x32_bf16 v[96:99], v[226:229], v[174:177], 0
	v_mfma_f32_16x16x32_bf16 v[84:87], v[218:221], v[182:185], 0
	v_mfma_f32_16x16x32_bf16 v[80:83], v[226:229], v[182:185], 0
	v_mfma_f32_16x16x32_bf16 v[68:71], v[218:221], v[206:209], 0
	v_mfma_f32_16x16x32_bf16 v[64:67], v[226:229], v[206:209], 0
	v_mfma_f32_16x16x32_bf16 v[116:119], v[222:225], v[170:173], v[116:119]
	v_mfma_f32_16x16x32_bf16 v[112:115], v[230:233], v[170:173], v[112:115]
	v_mfma_f32_16x16x32_bf16 v[100:103], v[222:225], v[178:181], v[100:103]
	v_mfma_f32_16x16x32_bf16 v[96:99], v[230:233], v[178:181], v[96:99]
	v_mfma_f32_16x16x32_bf16 v[84:87], v[222:225], v[186:189], v[84:87]
	v_mfma_f32_16x16x32_bf16 v[80:83], v[230:233], v[186:189], v[80:83]
	v_mfma_f32_16x16x32_bf16 v[68:71], v[222:225], v[214:217], v[68:71]
	v_mfma_f32_16x16x32_bf16 v[64:67], v[230:233], v[214:217], v[64:67]
	s_mov_b32 m0, s25
	v_lshl_add_u64 v[234:235], s[2:3], 0, v[156:157]
	s_barrier
	global_load_lds_dwordx4 v[234:235], off
	v_lshl_add_u64 v[236:237], s[2:3], 0, v[128:129]
	s_mov_b32 m0, s34
	s_nop 0
	global_load_lds_dwordx4 v[236:237], off
	ds_read_b128 v[166:169], v136 offset:16384
	ds_read_b128 v[170:173], v136 offset:17408
	ds_read_b128 v[174:177], v136 offset:18432
	ds_read_b128 v[178:181], v136 offset:19456
	ds_read_b128 v[182:185], v136 offset:20480
	ds_read_b128 v[186:189], v136 offset:21504
	ds_read_b128 v[206:209], v136 offset:22528
	ds_read_b128 v[214:217], v136 offset:23552
	s_barrier
	s_waitcnt lgkmcnt(0)
	v_mfma_f32_16x16x32_bf16 v[60:63], v[142:145], v[166:169], 0
	v_mfma_f32_16x16x32_bf16 v[56:59], v[150:153], v[166:169], 0
	v_mfma_f32_16x16x32_bf16 v[44:47], v[142:145], v[174:177], 0
	v_mfma_f32_16x16x32_bf16 v[40:43], v[150:153], v[174:177], 0
	v_mfma_f32_16x16x32_bf16 v[28:31], v[142:145], v[182:185], 0
	v_mfma_f32_16x16x32_bf16 v[24:27], v[150:153], v[182:185], 0
	v_mfma_f32_16x16x32_bf16 v[12:15], v[142:145], v[206:209], 0
	v_mfma_f32_16x16x32_bf16 v[8:11], v[150:153], v[206:209], 0
	v_mfma_f32_16x16x32_bf16 v[60:63], v[146:149], v[170:173], v[60:63]
	v_mfma_f32_16x16x32_bf16 v[56:59], v[162:165], v[170:173], v[56:59]
	v_mfma_f32_16x16x32_bf16 v[44:47], v[146:149], v[178:181], v[44:47]
	v_mfma_f32_16x16x32_bf16 v[40:43], v[162:165], v[178:181], v[40:43]
	v_mfma_f32_16x16x32_bf16 v[28:31], v[146:149], v[186:189], v[28:31]
	v_mfma_f32_16x16x32_bf16 v[24:27], v[162:165], v[186:189], v[24:27]
	v_mfma_f32_16x16x32_bf16 v[12:15], v[146:149], v[214:217], v[12:15]
	v_mfma_f32_16x16x32_bf16 v[8:11], v[162:165], v[214:217], v[8:11]
	s_barrier
	s_add_u32 s42, s42, s36
	s_addc_u32 s43, s43, s37
	s_add_i32 s21, s21, s24
	v_lshl_add_u64 v[238:239], s[42:43], 0, v[156:157]
	s_mov_b32 m0, s21
	v_lshl_add_u64 v[240:241], s[42:43], 0, v[128:129]
	global_load_lds_dwordx4 v[238:239], off
	s_add_i32 m0, s21, 0x2000
	s_nop 0
	global_load_lds_dwordx4 v[240:241], off
	s_waitcnt vmcnt(6)
	s_barrier
	v_mfma_f32_16x16x32_bf16 v[52:55], v[218:221], v[166:169], 0
	v_mfma_f32_16x16x32_bf16 v[48:51], v[226:229], v[166:169], 0
	v_mfma_f32_16x16x32_bf16 v[36:39], v[218:221], v[174:177], 0
	v_mfma_f32_16x16x32_bf16 v[32:35], v[226:229], v[174:177], 0
	v_mfma_f32_16x16x32_bf16 v[20:23], v[218:221], v[182:185], 0
	v_mfma_f32_16x16x32_bf16 v[16:19], v[226:229], v[182:185], 0
	v_mfma_f32_16x16x32_bf16 v[4:7], v[218:221], v[206:209], 0
	v_mfma_f32_16x16x32_bf16 v[0:3], v[226:229], v[206:209], 0
	v_mfma_f32_16x16x32_bf16 v[52:55], v[222:225], v[170:173], v[52:55]
	v_mfma_f32_16x16x32_bf16 v[48:51], v[230:233], v[170:173], v[48:51]
	v_mfma_f32_16x16x32_bf16 v[36:39], v[222:225], v[178:181], v[36:39]
	v_mfma_f32_16x16x32_bf16 v[32:35], v[230:233], v[178:181], v[32:35]
	v_mfma_f32_16x16x32_bf16 v[20:23], v[222:225], v[186:189], v[20:23]
	v_mfma_f32_16x16x32_bf16 v[16:19], v[230:233], v[186:189], v[16:19]
	v_mfma_f32_16x16x32_bf16 v[4:7], v[222:225], v[214:217], v[4:7]
	v_mfma_f32_16x16x32_bf16 v[0:3], v[230:233], v[214:217], v[0:3]
	s_add_i32 s21, 0, 0x18000
	v_add_u32_e32 v137, s21, v135
	s_barrier
	s_add_u32 s2, s2, s36
	s_addc_u32 s3, s3, s37
	s_mov_b32 m0, s35
	v_lshl_add_u64 v[218:219], s[2:3], 0, v[156:157]
	global_load_lds_dwordx4 v[218:219], off
	v_lshl_add_u64 v[218:219], s[2:3], 0, v[128:129]
	s_mov_b32 m0, s44
	s_nop 0
	global_load_lds_dwordx4 v[218:219], off
	ds_read_b128 v[142:145], v137
	ds_read_b128 v[146:149], v137 offset:1024
	ds_read_b128 v[150:153], v137 offset:2048
	ds_read_b128 v[162:165], v137 offset:3072
	ds_read_b128 v[166:169], v136 offset:32768
	ds_read_b128 v[170:173], v136 offset:33792
	ds_read_b128 v[174:177], v136 offset:34816
	ds_read_b128 v[178:181], v136 offset:35840
	ds_read_b128 v[182:185], v136 offset:36864
	ds_read_b128 v[186:189], v136 offset:37888
	ds_read_b128 v[206:209], v136 offset:38912
	ds_read_b128 v[214:217], v136 offset:39936
	s_waitcnt lgkmcnt(8)
	s_barrier
	s_waitcnt lgkmcnt(0)
	v_mfma_f32_16x16x32_bf16 v[124:127], v[142:145], v[166:169], v[124:127]
	v_mfma_f32_16x16x32_bf16 v[120:123], v[150:153], v[166:169], v[120:123]
	v_mfma_f32_16x16x32_bf16 v[108:111], v[142:145], v[174:177], v[108:111]
	v_mfma_f32_16x16x32_bf16 v[104:107], v[150:153], v[174:177], v[104:107]
	v_mfma_f32_16x16x32_bf16 v[92:95], v[142:145], v[182:185], v[92:95]
	v_mfma_f32_16x16x32_bf16 v[88:91], v[150:153], v[182:185], v[88:91]
	v_mfma_f32_16x16x32_bf16 v[76:79], v[142:145], v[206:209], v[76:79]
	v_mfma_f32_16x16x32_bf16 v[72:75], v[150:153], v[206:209], v[72:75]
	v_mfma_f32_16x16x32_bf16 v[124:127], v[146:149], v[170:173], v[124:127]
	v_mfma_f32_16x16x32_bf16 v[120:123], v[162:165], v[170:173], v[120:123]
	v_mfma_f32_16x16x32_bf16 v[108:111], v[146:149], v[178:181], v[108:111]
	v_mfma_f32_16x16x32_bf16 v[104:107], v[162:165], v[178:181], v[104:107]
	v_mfma_f32_16x16x32_bf16 v[92:95], v[146:149], v[186:189], v[92:95]
	v_mfma_f32_16x16x32_bf16 v[88:91], v[162:165], v[186:189], v[88:91]
	v_mfma_f32_16x16x32_bf16 v[76:79], v[146:149], v[214:217], v[76:79]
	v_mfma_f32_16x16x32_bf16 v[72:75], v[162:165], v[214:217], v[72:75]
	s_barrier
	s_add_i32 s2, 0, 0x1c000
	s_add_i32 s3, s21, s24
	v_add_u32_e32 v137, s2, v135
	v_lshl_add_u64 v[138:139], v[138:139], 0, s[50:51]
	s_mov_b32 m0, s3
	s_nop 0
	global_load_lds_dwordx4 v[138:139], off
	v_lshl_add_u64 v[138:139], v[154:155], 0, s[50:51]
	s_add_i32 m0, s3, 0x2000
	s_nop 0
	global_load_lds_dwordx4 v[138:139], off
	ds_read_b128 v[218:221], v137
	ds_read_b128 v[222:225], v137 offset:1024
	ds_read_b128 v[226:229], v137 offset:2048
	ds_read_b128 v[230:233], v137 offset:3072
	s_barrier
	s_waitcnt lgkmcnt(0)
	v_mfma_f32_16x16x32_bf16 v[116:119], v[218:221], v[166:169], v[116:119]
	v_mfma_f32_16x16x32_bf16 v[112:115], v[226:229], v[166:169], v[112:115]
	v_mfma_f32_16x16x32_bf16 v[100:103], v[218:221], v[174:177], v[100:103]
	v_mfma_f32_16x16x32_bf16 v[96:99], v[226:229], v[174:177], v[96:99]
	v_mfma_f32_16x16x32_bf16 v[84:87], v[218:221], v[182:185], v[84:87]
	v_mfma_f32_16x16x32_bf16 v[80:83], v[226:229], v[182:185], v[80:83]
	v_mfma_f32_16x16x32_bf16 v[68:71], v[218:221], v[206:209], v[68:71]
	v_mfma_f32_16x16x32_bf16 v[64:67], v[226:229], v[206:209], v[64:67]
	v_mfma_f32_16x16x32_bf16 v[116:119], v[222:225], v[170:173], v[116:119]
	v_mfma_f32_16x16x32_bf16 v[112:115], v[230:233], v[170:173], v[112:115]
	v_mfma_f32_16x16x32_bf16 v[100:103], v[222:225], v[178:181], v[100:103]
	v_mfma_f32_16x16x32_bf16 v[96:99], v[230:233], v[178:181], v[96:99]
	v_mfma_f32_16x16x32_bf16 v[84:87], v[222:225], v[186:189], v[84:87]
	v_mfma_f32_16x16x32_bf16 v[80:83], v[230:233], v[186:189], v[80:83]
	v_mfma_f32_16x16x32_bf16 v[68:71], v[222:225], v[214:217], v[68:71]
	v_mfma_f32_16x16x32_bf16 v[64:67], v[230:233], v[214:217], v[64:67]
	s_mov_b32 m0, s45
	v_lshl_add_u64 v[138:139], v[234:235], 0, s[50:51]
	s_barrier
	global_load_lds_dwordx4 v[138:139], off
	v_lshl_add_u64 v[138:139], v[236:237], 0, s[50:51]
	s_mov_b32 m0, s48
	s_nop 0
	global_load_lds_dwordx4 v[138:139], off
	ds_read_b128 v[166:169], v136 offset:49152
	ds_read_b128 v[170:173], v136 offset:50176
	ds_read_b128 v[174:177], v136 offset:51200
	ds_read_b128 v[178:181], v136 offset:52224
	ds_read_b128 v[182:185], v136 offset:53248
	ds_read_b128 v[186:189], v136 offset:54272
	ds_read_b128 v[206:209], v136 offset:55296
	ds_read_b128 v[214:217], v136 offset:56320
	s_barrier
	s_waitcnt lgkmcnt(0)
	v_mfma_f32_16x16x32_bf16 v[60:63], v[142:145], v[166:169], v[60:63]
	v_mfma_f32_16x16x32_bf16 v[56:59], v[150:153], v[166:169], v[56:59]
	v_mfma_f32_16x16x32_bf16 v[44:47], v[142:145], v[174:177], v[44:47]
	v_mfma_f32_16x16x32_bf16 v[40:43], v[150:153], v[174:177], v[40:43]
	v_mfma_f32_16x16x32_bf16 v[28:31], v[142:145], v[182:185], v[28:31]
	v_mfma_f32_16x16x32_bf16 v[24:27], v[150:153], v[182:185], v[24:27]
	v_mfma_f32_16x16x32_bf16 v[12:15], v[142:145], v[206:209], v[12:15]
	v_mfma_f32_16x16x32_bf16 v[8:11], v[150:153], v[206:209], v[8:11]
	v_mfma_f32_16x16x32_bf16 v[60:63], v[146:149], v[170:173], v[60:63]
	v_mfma_f32_16x16x32_bf16 v[56:59], v[162:165], v[170:173], v[56:59]
	v_mfma_f32_16x16x32_bf16 v[44:47], v[146:149], v[178:181], v[44:47]
	v_mfma_f32_16x16x32_bf16 v[40:43], v[162:165], v[178:181], v[40:43]
	v_mfma_f32_16x16x32_bf16 v[28:31], v[146:149], v[186:189], v[28:31]
	v_mfma_f32_16x16x32_bf16 v[24:27], v[162:165], v[186:189], v[24:27]
	v_mfma_f32_16x16x32_bf16 v[12:15], v[146:149], v[214:217], v[12:15]
	v_mfma_f32_16x16x32_bf16 v[8:11], v[162:165], v[214:217], v[8:11]
	s_barrier
	s_add_i32 s2, s2, s24
	v_lshl_add_u64 v[138:139], v[238:239], 0, s[50:51]
	s_mov_b32 m0, s2
	s_nop 0
	global_load_lds_dwordx4 v[138:139], off
	v_lshl_add_u64 v[138:139], v[240:241], 0, s[50:51]
	s_add_i32 m0, s2, 0x2000
	s_nop 0
	global_load_lds_dwordx4 v[138:139], off
	s_waitcnt vmcnt(6)
	s_barrier
	v_mfma_f32_16x16x32_bf16 v[52:55], v[218:221], v[166:169], v[52:55]
	v_mfma_f32_16x16x32_bf16 v[48:51], v[226:229], v[166:169], v[48:51]
	v_mfma_f32_16x16x32_bf16 v[36:39], v[218:221], v[174:177], v[36:39]
	v_mfma_f32_16x16x32_bf16 v[32:35], v[226:229], v[174:177], v[32:35]
	v_mfma_f32_16x16x32_bf16 v[20:23], v[218:221], v[182:185], v[20:23]
	v_mfma_f32_16x16x32_bf16 v[16:19], v[226:229], v[182:185], v[16:19]
	v_mfma_f32_16x16x32_bf16 v[4:7], v[218:221], v[206:209], v[4:7]
	v_mfma_f32_16x16x32_bf16 v[0:3], v[226:229], v[206:209], v[0:3]
	v_mfma_f32_16x16x32_bf16 v[52:55], v[222:225], v[170:173], v[52:55]
	v_mfma_f32_16x16x32_bf16 v[48:51], v[230:233], v[170:173], v[48:51]
	v_mfma_f32_16x16x32_bf16 v[36:39], v[222:225], v[178:181], v[36:39]
	v_mfma_f32_16x16x32_bf16 v[32:35], v[230:233], v[178:181], v[32:35]
	v_mfma_f32_16x16x32_bf16 v[20:23], v[222:225], v[186:189], v[20:23]
	v_mfma_f32_16x16x32_bf16 v[16:19], v[230:233], v[186:189], v[16:19]
	v_mfma_f32_16x16x32_bf16 v[4:7], v[222:225], v[214:217], v[4:7]
	v_mfma_f32_16x16x32_bf16 v[0:3], v[230:233], v[214:217], v[0:3]
	s_add_u32 s6, s6, 0x100
	s_addc_u32 s7, s7, 0
	s_cmp_ge_i32 s54, s49
	s_mov_b32 s2, s54
	s_barrier
	s_cbranch_scc1 .Lpost_272
.LBB0_272:
	s_add_i32 s54, s2, 2
	s_add_u32 s3, s6, 0xe5b5c080
	s_addc_u32 s21, s7, -1
	s_cmp_lg_u32 s53, s2
	s_cselect_b32 s42, s3, 0
	s_cselect_b32 s21, s21, 0
	s_add_u32 s2, s38, s42
	s_addc_u32 s3, s39, s21
	s_add_i32 s55, 0, 0x10000
	v_add_u32_e32 v137, s55, v135
	ds_read_b128 v[142:145], v137
	ds_read_b128 v[146:149], v137 offset:1024
	ds_read_b128 v[150:153], v137 offset:2048
	ds_read_b128 v[162:165], v137 offset:3072
	s_add_u32 s42, s40, s42
	s_addc_u32 s43, s41, s21
	v_lshl_add_u64 v[138:139], v[132:133], 0, s[6:7]
	s_add_i32 m0, s25, 0xc000
	s_nop 0
	global_load_lds_dwordx4 v[138:139], off
	v_lshl_add_u64 v[138:139], v[130:131], 0, s[6:7]
	s_add_i32 m0, s25, 0xe000
	s_nop 0
	global_load_lds_dwordx4 v[138:139], off
	ds_read_b128 v[166:169], v136
	ds_read_b128 v[170:173], v136 offset:1024
	ds_read_b128 v[174:177], v136 offset:2048
	ds_read_b128 v[178:181], v136 offset:3072
	ds_read_b128 v[182:185], v136 offset:4096
	ds_read_b128 v[186:189], v136 offset:5120
	ds_read_b128 v[206:209], v136 offset:6144
	ds_read_b128 v[214:217], v136 offset:7168
	s_waitcnt lgkmcnt(8)
	s_barrier
	s_waitcnt lgkmcnt(0)
	v_mfma_f32_16x16x32_bf16 v[124:127], v[142:145], v[166:169], v[124:127]
	v_mfma_f32_16x16x32_bf16 v[120:123], v[150:153], v[166:169], v[120:123]
	v_mfma_f32_16x16x32_bf16 v[108:111], v[142:145], v[174:177], v[108:111]
	v_mfma_f32_16x16x32_bf16 v[104:107], v[150:153], v[174:177], v[104:107]
	v_mfma_f32_16x16x32_bf16 v[92:95], v[142:145], v[182:185], v[92:95]
	v_mfma_f32_16x16x32_bf16 v[88:91], v[150:153], v[182:185], v[88:91]
	v_mfma_f32_16x16x32_bf16 v[76:79], v[142:145], v[206:209], v[76:79]
	v_mfma_f32_16x16x32_bf16 v[72:75], v[150:153], v[206:209], v[72:75]
	v_mfma_f32_16x16x32_bf16 v[124:127], v[146:149], v[170:173], v[124:127]
	v_mfma_f32_16x16x32_bf16 v[120:123], v[162:165], v[170:173], v[120:123]
	v_mfma_f32_16x16x32_bf16 v[108:111], v[146:149], v[178:181], v[108:111]
	v_mfma_f32_16x16x32_bf16 v[104:107], v[162:165], v[178:181], v[104:107]
	v_mfma_f32_16x16x32_bf16 v[92:95], v[146:149], v[186:189], v[92:95]
	v_mfma_f32_16x16x32_bf16 v[88:91], v[162:165], v[186:189], v[88:91]
	v_mfma_f32_16x16x32_bf16 v[76:79], v[146:149], v[214:217], v[76:79]
	v_mfma_f32_16x16x32_bf16 v[72:75], v[162:165], v[214:217], v[72:75]
	s_barrier
	s_add_i32 s21, 0, 0x14000
	s_add_i32 s55, s55, s24
	v_add_u32_e32 v137, s21, v135
	v_lshl_add_u64 v[138:139], s[42:43], 0, v[156:157]
	s_mov_b32 m0, s55
	s_nop 0
	global_load_lds_dwordx4 v[138:139], off
	v_lshl_add_u64 v[154:155], s[42:43], 0, v[128:129]
	s_add_i32 m0, s55, 0x2000
	s_nop 0
	global_load_lds_dwordx4 v[154:155], off
	ds_read_b128 v[218:221], v137
	ds_read_b128 v[222:225], v137 offset:1024
	ds_read_b128 v[226:229], v137 offset:2048
	ds_read_b128 v[230:233], v137 offset:3072
	s_barrier
	s_waitcnt lgkmcnt(0)
	v_mfma_f32_16x16x32_bf16 v[116:119], v[218:221], v[166:169], v[116:119]
	v_mfma_f32_16x16x32_bf16 v[112:115], v[226:229], v[166:169], v[112:115]
	v_mfma_f32_16x16x32_bf16 v[100:103], v[218:221], v[174:177], v[100:103]
	v_mfma_f32_16x16x32_bf16 v[96:99], v[226:229], v[174:177], v[96:99]
	v_mfma_f32_16x16x32_bf16 v[84:87], v[218:221], v[182:185], v[84:87]
	v_mfma_f32_16x16x32_bf16 v[80:83], v[226:229], v[182:185], v[80:83]
	v_mfma_f32_16x16x32_bf16 v[68:71], v[218:221], v[206:209], v[68:71]
	v_mfma_f32_16x16x32_bf16 v[64:67], v[226:229], v[206:209], v[64:67]
	v_mfma_f32_16x16x32_bf16 v[116:119], v[222:225], v[170:173], v[116:119]
	v_mfma_f32_16x16x32_bf16 v[112:115], v[230:233], v[170:173], v[112:115]
	v_mfma_f32_16x16x32_bf16 v[100:103], v[222:225], v[178:181], v[100:103]
	v_mfma_f32_16x16x32_bf16 v[96:99], v[230:233], v[178:181], v[96:99]
	v_mfma_f32_16x16x32_bf16 v[84:87], v[222:225], v[186:189], v[84:87]
	v_mfma_f32_16x16x32_bf16 v[80:83], v[230:233], v[186:189], v[80:83]
	v_mfma_f32_16x16x32_bf16 v[68:71], v[222:225], v[214:217], v[68:71]
	v_mfma_f32_16x16x32_bf16 v[64:67], v[230:233], v[214:217], v[64:67]
	s_mov_b32 m0, s25
	v_lshl_add_u64 v[234:235], s[2:3], 0, v[156:157]
	s_barrier
	global_load_lds_dwordx4 v[234:235], off
	v_lshl_add_u64 v[236:237], s[2:3], 0, v[128:129]
	s_mov_b32 m0, s34
	s_nop 0
	global_load_lds_dwordx4 v[236:237], off
	ds_read_b128 v[166:169], v136 offset:16384
	ds_read_b128 v[170:173], v136 offset:17408
	ds_read_b128 v[174:177], v136 offset:18432
	ds_read_b128 v[178:181], v136 offset:19456
	ds_read_b128 v[182:185], v136 offset:20480
	ds_read_b128 v[186:189], v136 offset:21504
	ds_read_b128 v[206:209], v136 offset:22528
	ds_read_b128 v[214:217], v136 offset:23552
	s_barrier
	s_waitcnt lgkmcnt(0)
	v_mfma_f32_16x16x32_bf16 v[60:63], v[142:145], v[166:169], v[60:63]
	v_mfma_f32_16x16x32_bf16 v[56:59], v[150:153], v[166:169], v[56:59]
	v_mfma_f32_16x16x32_bf16 v[44:47], v[142:145], v[174:177], v[44:47]
	v_mfma_f32_16x16x32_bf16 v[40:43], v[150:153], v[174:177], v[40:43]
	v_mfma_f32_16x16x32_bf16 v[28:31], v[142:145], v[182:185], v[28:31]
	v_mfma_f32_16x16x32_bf16 v[24:27], v[150:153], v[182:185], v[24:27]
	v_mfma_f32_16x16x32_bf16 v[12:15], v[142:145], v[206:209], v[12:15]
	v_mfma_f32_16x16x32_bf16 v[8:11], v[150:153], v[206:209], v[8:11]
	v_mfma_f32_16x16x32_bf16 v[60:63], v[146:149], v[170:173], v[60:63]
	v_mfma_f32_16x16x32_bf16 v[56:59], v[162:165], v[170:173], v[56:59]
	v_mfma_f32_16x16x32_bf16 v[44:47], v[146:149], v[178:181], v[44:47]
	v_mfma_f32_16x16x32_bf16 v[40:43], v[162:165], v[178:181], v[40:43]
	v_mfma_f32_16x16x32_bf16 v[28:31], v[146:149], v[186:189], v[28:31]
	v_mfma_f32_16x16x32_bf16 v[24:27], v[162:165], v[186:189], v[24:27]
	v_mfma_f32_16x16x32_bf16 v[12:15], v[146:149], v[214:217], v[12:15]
	v_mfma_f32_16x16x32_bf16 v[8:11], v[162:165], v[214:217], v[8:11]
	s_barrier
	s_add_u32 s42, s42, s36
	s_addc_u32 s43, s43, s37
	s_add_i32 s21, s21, s24
	v_lshl_add_u64 v[238:239], s[42:43], 0, v[156:157]
	s_mov_b32 m0, s21
	v_lshl_add_u64 v[240:241], s[42:43], 0, v[128:129]
	global_load_lds_dwordx4 v[238:239], off
	s_add_i32 m0, s21, 0x2000
	s_nop 0
	global_load_lds_dwordx4 v[240:241], off
	s_waitcnt vmcnt(6)
	s_barrier
	v_mfma_f32_16x16x32_bf16 v[52:55], v[218:221], v[166:169], v[52:55]
	v_mfma_f32_16x16x32_bf16 v[48:51], v[226:229], v[166:169], v[48:51]
	v_mfma_f32_16x16x32_bf16 v[36:39], v[218:221], v[174:177], v[36:39]
	v_mfma_f32_16x16x32_bf16 v[32:35], v[226:229], v[174:177], v[32:35]
	v_mfma_f32_16x16x32_bf16 v[20:23], v[218:221], v[182:185], v[20:23]
	v_mfma_f32_16x16x32_bf16 v[16:19], v[226:229], v[182:185], v[16:19]
	v_mfma_f32_16x16x32_bf16 v[4:7], v[218:221], v[206:209], v[4:7]
	v_mfma_f32_16x16x32_bf16 v[0:3], v[226:229], v[206:209], v[0:3]
	v_mfma_f32_16x16x32_bf16 v[52:55], v[222:225], v[170:173], v[52:55]
	v_mfma_f32_16x16x32_bf16 v[48:51], v[230:233], v[170:173], v[48:51]
	v_mfma_f32_16x16x32_bf16 v[36:39], v[222:225], v[178:181], v[36:39]
	v_mfma_f32_16x16x32_bf16 v[32:35], v[230:233], v[178:181], v[32:35]
	v_mfma_f32_16x16x32_bf16 v[20:23], v[222:225], v[186:189], v[20:23]
	v_mfma_f32_16x16x32_bf16 v[16:19], v[230:233], v[186:189], v[16:19]
	v_mfma_f32_16x16x32_bf16 v[4:7], v[222:225], v[214:217], v[4:7]
	v_mfma_f32_16x16x32_bf16 v[0:3], v[230:233], v[214:217], v[0:3]
	s_add_i32 s21, 0, 0x18000
	v_add_u32_e32 v137, s21, v135
	s_barrier
	ds_read_b128 v[142:145], v137
	ds_read_b128 v[146:149], v137 offset:1024
	ds_read_b128 v[150:153], v137 offset:2048
	ds_read_b128 v[162:165], v137 offset:3072
	s_add_u32 s2, s2, s36
	s_addc_u32 s3, s3, s37
	s_mov_b32 m0, s35
	v_lshl_add_u64 v[218:219], s[2:3], 0, v[156:157]
	global_load_lds_dwordx4 v[218:219], off
	v_lshl_add_u64 v[218:219], s[2:3], 0, v[128:129]
	s_mov_b32 m0, s44
	s_nop 0
	global_load_lds_dwordx4 v[218:219], off
	ds_read_b128 v[166:169], v136 offset:32768
	ds_read_b128 v[170:173], v136 offset:33792
	ds_read_b128 v[174:177], v136 offset:34816
	ds_read_b128 v[178:181], v136 offset:35840
	ds_read_b128 v[182:185], v136 offset:36864
	ds_read_b128 v[186:189], v136 offset:37888
	ds_read_b128 v[206:209], v136 offset:38912
	ds_read_b128 v[214:217], v136 offset:39936
	s_waitcnt lgkmcnt(8)
	s_barrier
	s_waitcnt lgkmcnt(0)
	v_mfma_f32_16x16x32_bf16 v[124:127], v[142:145], v[166:169], v[124:127]
	v_mfma_f32_16x16x32_bf16 v[120:123], v[150:153], v[166:169], v[120:123]
	v_mfma_f32_16x16x32_bf16 v[108:111], v[142:145], v[174:177], v[108:111]
	v_mfma_f32_16x16x32_bf16 v[104:107], v[150:153], v[174:177], v[104:107]
	v_mfma_f32_16x16x32_bf16 v[92:95], v[142:145], v[182:185], v[92:95]
	v_mfma_f32_16x16x32_bf16 v[88:91], v[150:153], v[182:185], v[88:91]
	v_mfma_f32_16x16x32_bf16 v[76:79], v[142:145], v[206:209], v[76:79]
	v_mfma_f32_16x16x32_bf16 v[72:75], v[150:153], v[206:209], v[72:75]
	v_mfma_f32_16x16x32_bf16 v[124:127], v[146:149], v[170:173], v[124:127]
	v_mfma_f32_16x16x32_bf16 v[120:123], v[162:165], v[170:173], v[120:123]
	v_mfma_f32_16x16x32_bf16 v[108:111], v[146:149], v[178:181], v[108:111]
	v_mfma_f32_16x16x32_bf16 v[104:107], v[162:165], v[178:181], v[104:107]
	v_mfma_f32_16x16x32_bf16 v[92:95], v[146:149], v[186:189], v[92:95]
	v_mfma_f32_16x16x32_bf16 v[88:91], v[162:165], v[186:189], v[88:91]
	v_mfma_f32_16x16x32_bf16 v[76:79], v[146:149], v[214:217], v[76:79]
	v_mfma_f32_16x16x32_bf16 v[72:75], v[162:165], v[214:217], v[72:75]
	s_barrier
	s_add_i32 s2, 0, 0x1c000
	s_add_i32 s3, s21, s24
	v_add_u32_e32 v137, s2, v135
	v_lshl_add_u64 v[138:139], v[138:139], 0, s[50:51]
	s_mov_b32 m0, s3
	s_nop 0
	global_load_lds_dwordx4 v[138:139], off
	v_lshl_add_u64 v[138:139], v[154:155], 0, s[50:51]
	s_add_i32 m0, s3, 0x2000
	s_nop 0
	global_load_lds_dwordx4 v[138:139], off
	ds_read_b128 v[218:221], v137
	ds_read_b128 v[222:225], v137 offset:1024
	ds_read_b128 v[226:229], v137 offset:2048
	ds_read_b128 v[230:233], v137 offset:3072
	s_barrier
	s_waitcnt lgkmcnt(0)
	v_mfma_f32_16x16x32_bf16 v[116:119], v[218:221], v[166:169], v[116:119]
	v_mfma_f32_16x16x32_bf16 v[112:115], v[226:229], v[166:169], v[112:115]
	v_mfma_f32_16x16x32_bf16 v[100:103], v[218:221], v[174:177], v[100:103]
	v_mfma_f32_16x16x32_bf16 v[96:99], v[226:229], v[174:177], v[96:99]
	v_mfma_f32_16x16x32_bf16 v[84:87], v[218:221], v[182:185], v[84:87]
	v_mfma_f32_16x16x32_bf16 v[80:83], v[226:229], v[182:185], v[80:83]
	v_mfma_f32_16x16x32_bf16 v[68:71], v[218:221], v[206:209], v[68:71]
	v_mfma_f32_16x16x32_bf16 v[64:67], v[226:229], v[206:209], v[64:67]
	v_mfma_f32_16x16x32_bf16 v[116:119], v[222:225], v[170:173], v[116:119]
	v_mfma_f32_16x16x32_bf16 v[112:115], v[230:233], v[170:173], v[112:115]
	v_mfma_f32_16x16x32_bf16 v[100:103], v[222:225], v[178:181], v[100:103]
	v_mfma_f32_16x16x32_bf16 v[96:99], v[230:233], v[178:181], v[96:99]
	v_mfma_f32_16x16x32_bf16 v[84:87], v[222:225], v[186:189], v[84:87]
	v_mfma_f32_16x16x32_bf16 v[80:83], v[230:233], v[186:189], v[80:83]
	v_mfma_f32_16x16x32_bf16 v[68:71], v[222:225], v[214:217], v[68:71]
	v_mfma_f32_16x16x32_bf16 v[64:67], v[230:233], v[214:217], v[64:67]
	s_mov_b32 m0, s45
	v_lshl_add_u64 v[138:139], v[234:235], 0, s[50:51]
	s_barrier
	global_load_lds_dwordx4 v[138:139], off
	v_lshl_add_u64 v[138:139], v[236:237], 0, s[50:51]
	s_mov_b32 m0, s48
	s_nop 0
	global_load_lds_dwordx4 v[138:139], off
	ds_read_b128 v[166:169], v136 offset:49152
	ds_read_b128 v[170:173], v136 offset:50176
	ds_read_b128 v[174:177], v136 offset:51200
	ds_read_b128 v[178:181], v136 offset:52224
	ds_read_b128 v[182:185], v136 offset:53248
	ds_read_b128 v[186:189], v136 offset:54272
	ds_read_b128 v[206:209], v136 offset:55296
	ds_read_b128 v[214:217], v136 offset:56320
	s_barrier
	s_waitcnt lgkmcnt(0)
	v_mfma_f32_16x16x32_bf16 v[60:63], v[142:145], v[166:169], v[60:63]
	v_mfma_f32_16x16x32_bf16 v[56:59], v[150:153], v[166:169], v[56:59]
	v_mfma_f32_16x16x32_bf16 v[44:47], v[142:145], v[174:177], v[44:47]
	v_mfma_f32_16x16x32_bf16 v[40:43], v[150:153], v[174:177], v[40:43]
	v_mfma_f32_16x16x32_bf16 v[28:31], v[142:145], v[182:185], v[28:31]
	v_mfma_f32_16x16x32_bf16 v[24:27], v[150:153], v[182:185], v[24:27]
	v_mfma_f32_16x16x32_bf16 v[12:15], v[142:145], v[206:209], v[12:15]
	v_mfma_f32_16x16x32_bf16 v[8:11], v[150:153], v[206:209], v[8:11]
	v_mfma_f32_16x16x32_bf16 v[60:63], v[146:149], v[170:173], v[60:63]
	v_mfma_f32_16x16x32_bf16 v[56:59], v[162:165], v[170:173], v[56:59]
	v_mfma_f32_16x16x32_bf16 v[44:47], v[146:149], v[178:181], v[44:47]
	v_mfma_f32_16x16x32_bf16 v[40:43], v[162:165], v[178:181], v[40:43]
	v_mfma_f32_16x16x32_bf16 v[28:31], v[146:149], v[186:189], v[28:31]
	v_mfma_f32_16x16x32_bf16 v[24:27], v[162:165], v[186:189], v[24:27]
	v_mfma_f32_16x16x32_bf16 v[12:15], v[146:149], v[214:217], v[12:15]
	v_mfma_f32_16x16x32_bf16 v[8:11], v[162:165], v[214:217], v[8:11]
	s_barrier
	s_add_i32 s2, s2, s24
	v_lshl_add_u64 v[138:139], v[238:239], 0, s[50:51]
	s_mov_b32 m0, s2
	s_nop 0
	global_load_lds_dwordx4 v[138:139], off
	v_lshl_add_u64 v[138:139], v[240:241], 0, s[50:51]
	s_add_i32 m0, s2, 0x2000
	s_nop 0
	global_load_lds_dwordx4 v[138:139], off
	s_waitcnt vmcnt(6)
	s_barrier
	v_mfma_f32_16x16x32_bf16 v[52:55], v[218:221], v[166:169], v[52:55]
	v_mfma_f32_16x16x32_bf16 v[48:51], v[226:229], v[166:169], v[48:51]
	v_mfma_f32_16x16x32_bf16 v[36:39], v[218:221], v[174:177], v[36:39]
	v_mfma_f32_16x16x32_bf16 v[32:35], v[226:229], v[174:177], v[32:35]
	v_mfma_f32_16x16x32_bf16 v[20:23], v[218:221], v[182:185], v[20:23]
	v_mfma_f32_16x16x32_bf16 v[16:19], v[226:229], v[182:185], v[16:19]
	v_mfma_f32_16x16x32_bf16 v[4:7], v[218:221], v[206:209], v[4:7]
	v_mfma_f32_16x16x32_bf16 v[0:3], v[226:229], v[206:209], v[0:3]
	v_mfma_f32_16x16x32_bf16 v[52:55], v[222:225], v[170:173], v[52:55]
	v_mfma_f32_16x16x32_bf16 v[48:51], v[230:233], v[170:173], v[48:51]
	v_mfma_f32_16x16x32_bf16 v[36:39], v[222:225], v[178:181], v[36:39]
	v_mfma_f32_16x16x32_bf16 v[32:35], v[230:233], v[178:181], v[32:35]
	v_mfma_f32_16x16x32_bf16 v[20:23], v[222:225], v[186:189], v[20:23]
	v_mfma_f32_16x16x32_bf16 v[16:19], v[230:233], v[186:189], v[16:19]
	v_mfma_f32_16x16x32_bf16 v[4:7], v[222:225], v[214:217], v[4:7]
	v_mfma_f32_16x16x32_bf16 v[0:3], v[230:233], v[214:217], v[0:3]
	s_add_u32 s6, s6, 0x100
	s_addc_u32 s7, s7, 0
	s_cmp_ge_i32 s54, s49
	s_mov_b32 s2, s54
	s_barrier
	s_cbranch_scc0 .LBB0_272

.LBB0_285:
	v_bfe_u32 v14, v160, 4, 2
	v_and_b32_e32 v131, 15, v160
	v_lshlrev_b32_e32 v130, 4, v14
	v_lshlrev_b32_e32 v15, 2, v160
	v_lshl_or_b32 v14, v131, 6, v130
	s_lshl_b32 s21, s44, 13
	v_and_b32_e32 v15, 32, v15
	v_bitop3_b32 v16, v14, s21, v15 bitop3:0xde
	s_lshl_b32 s21, s45, 5
	s_lshl_b32 s35, s44, 6
	s_and_b32 s44, s21, 0x60
	s_add_i32 m0, s19, 0x18000
	v_lshl_add_u64 v[6:7], v[6:7], 0, s[50:51]
	s_lshl_b32 s21, s44, 7
	s_waitcnt vmcnt(4)
	s_barrier
	global_load_lds_dwordx4 v[6:7], off
	v_lshl_add_u64 v[4:5], v[4:5], 0, s[50:51]
	s_add_i32 m0, s19, 0x1a000
	s_add_i32 s45, s19, 0x8000
	s_add_i32 s53, s19, 0xa000
	global_load_lds_dwordx4 v[4:5], off
	v_lshl_add_u64 v[2:3], v[2:3], 0, s[50:51]
	s_mov_b32 m0, s45
	s_add_u32 s54, s42, 0x80080
	global_load_lds_dwordx4 v[2:3], off
	v_lshl_add_u64 v[0:1], v[0:1], 0, s[50:51]
	s_mov_b32 m0, s53
	s_addc_u32 s55, s43, 0
	global_load_lds_dwordx4 v[0:1], off
	s_add_i32 m0, s19, 0x1c000
	v_lshl_add_u64 v[0:1], s[54:55], 0, v[156:157]
	global_load_lds_dwordx4 v[0:1], off
	v_lshl_add_u64 v[0:1], s[54:55], 0, v[128:129]
	s_add_i32 m0, s19, 0x1e000
	s_add_u32 s2, s6, s2
	global_load_lds_dwordx4 v[0:1], off
	s_addc_u32 s3, s7, s3
	v_lshlrev_b32_e32 v0, 15, v11
	v_and_b32_e32 v0, 0xffff0000, v0
	s_add_u32 s2, s26, s2
	v_lshl_add_u32 v0, v12, 12, v0
	v_and_b32_e32 v1, 1, v11
	s_addc_u32 s3, s27, s3
	v_lshl_or_b32 v0, v1, 6, v0
	s_add_u32 s2, s2, 0x19524080
	v_lshl_add_u32 v0, v13, 1, v0
	v_mov_b32_e32 v1, v157
	s_addc_u32 s3, s3, 0
	v_lshl_add_u64 v[132:133], s[2:3], 0, v[0:1]
	v_lshlrev_b32_e32 v0, 15, v8
	v_and_b32_e32 v0, 0xffff0000, v0
	v_lshl_add_u32 v0, v9, 12, v0
	v_and_b32_e32 v1, 1, v8
	v_lshl_or_b32 v0, v1, 6, v0
	s_waitcnt vmcnt(6)
	v_lshl_add_u32 v0, v10, 1, v0
	v_mov_b32_e32 v1, v157
	v_lshl_add_u64 v[134:135], s[2:3], 0, v[0:1]
	v_bitop3_b32 v136, s21, v14, v15 bitop3:0xf6
	s_mov_b32 s54, -2
	s_mov_b64 s[6:7], 0
	v_add_u32_e32 v137, 0, v16
	s_barrier
	s_add_u32 s60, s6, 0x100
	s_addc_u32 s61, s7, 0
	s_cmp_lg_u32 s54, 28
	s_cselect_b32 s55, s60, 0
	s_cselect_b32 s21, s61, 0
	s_add_u32 s2, s48, s55
	s_addc_u32 s3, s49, s21
	s_add_i32 s66, 0, 0x10000
	v_add_u32_e32 v150, s66, v136
	s_add_u32 s62, s42, s55
	s_addc_u32 s63, s43, s21
	v_lshl_add_u64 v[154:155], v[134:135], 0, s[6:7]
	s_add_i32 m0, s19, 0xc000
	s_nop 0
	global_load_lds_dwordx4 v[154:155], off
	v_lshl_add_u64 v[154:155], v[132:133], 0, s[6:7]
	s_add_i32 m0, s19, 0xe000
	s_nop 0
	global_load_lds_dwordx4 v[154:155], off
	ds_read_b128 v[138:141], v150
	ds_read_b128 v[142:145], v150 offset:1024
	ds_read_b128 v[146:149], v150 offset:2048
	ds_read_b128 v[150:153], v150 offset:3072
	ds_read_b128 v[162:165], v137
	ds_read_b128 v[166:169], v137 offset:1024
	ds_read_b128 v[170:173], v137 offset:2048
	ds_read_b128 v[174:177], v137 offset:3072
	ds_read_b128 v[178:181], v137 offset:4096
	ds_read_b128 v[182:185], v137 offset:5120
	ds_read_b128 v[186:189], v137 offset:6144
	ds_read_b128 v[206:209], v137 offset:7168
	s_waitcnt lgkmcnt(8)
	s_barrier
	s_waitcnt lgkmcnt(0)
	v_mfma_f32_16x16x32_bf16 v[124:127], v[138:141], v[162:165], 0
	v_mfma_f32_16x16x32_bf16 v[120:123], v[146:149], v[162:165], 0
	v_mfma_f32_16x16x32_bf16 v[116:119], v[138:141], v[170:173], 0
	v_mfma_f32_16x16x32_bf16 v[112:115], v[146:149], v[170:173], 0
	v_mfma_f32_16x16x32_bf16 v[108:111], v[138:141], v[178:181], 0
	v_mfma_f32_16x16x32_bf16 v[100:103], v[146:149], v[178:181], 0
	v_mfma_f32_16x16x32_bf16 v[92:95], v[138:141], v[186:189], 0
	v_mfma_f32_16x16x32_bf16 v[84:87], v[146:149], v[186:189], 0
	v_mfma_f32_16x16x32_bf16 v[124:127], v[142:145], v[166:169], v[124:127]
	v_mfma_f32_16x16x32_bf16 v[120:123], v[150:153], v[166:169], v[120:123]
	v_mfma_f32_16x16x32_bf16 v[116:119], v[142:145], v[174:177], v[116:119]
	v_mfma_f32_16x16x32_bf16 v[112:115], v[150:153], v[174:177], v[112:115]
	v_mfma_f32_16x16x32_bf16 v[108:111], v[142:145], v[182:185], v[108:111]
	v_mfma_f32_16x16x32_bf16 v[100:103], v[150:153], v[182:185], v[100:103]
	v_mfma_f32_16x16x32_bf16 v[92:95], v[142:145], v[206:209], v[92:95]
	v_mfma_f32_16x16x32_bf16 v[84:87], v[150:153], v[206:209], v[84:87]
	s_barrier
	s_add_i32 s21, 0, 0x14000
	v_add_u32_e32 v154, s21, v136
	s_add_i32 s6, s66, s10
	ds_read_b128 v[214:217], v154
	ds_read_b128 v[218:221], v154 offset:1024
	ds_read_b128 v[222:225], v154 offset:2048
	ds_read_b128 v[226:229], v154 offset:3072
	v_lshl_add_u64 v[154:155], s[62:63], 0, v[156:157]
	s_mov_b32 m0, s6
	v_lshl_add_u64 v[230:231], s[62:63], 0, v[128:129]
	global_load_lds_dwordx4 v[154:155], off
	s_add_i32 m0, s6, 0x2000
	s_nop 0
	global_load_lds_dwordx4 v[230:231], off
	s_barrier
	s_waitcnt lgkmcnt(0)
	v_mfma_f32_16x16x32_bf16 v[104:107], v[214:217], v[162:165], 0
	v_mfma_f32_16x16x32_bf16 v[96:99], v[222:225], v[162:165], 0
	v_mfma_f32_16x16x32_bf16 v[88:91], v[214:217], v[170:173], 0
	v_mfma_f32_16x16x32_bf16 v[80:83], v[222:225], v[170:173], 0
	v_mfma_f32_16x16x32_bf16 v[76:79], v[214:217], v[178:181], 0
	v_mfma_f32_16x16x32_bf16 v[72:75], v[222:225], v[178:181], 0
	v_mfma_f32_16x16x32_bf16 v[68:71], v[214:217], v[186:189], 0
	v_mfma_f32_16x16x32_bf16 v[64:67], v[222:225], v[186:189], 0
	v_mfma_f32_16x16x32_bf16 v[104:107], v[218:221], v[166:169], v[104:107]
	v_mfma_f32_16x16x32_bf16 v[96:99], v[226:229], v[166:169], v[96:99]
	v_mfma_f32_16x16x32_bf16 v[88:91], v[218:221], v[174:177], v[88:91]
	v_mfma_f32_16x16x32_bf16 v[80:83], v[226:229], v[174:177], v[80:83]
	v_mfma_f32_16x16x32_bf16 v[76:79], v[218:221], v[182:185], v[76:79]
	v_mfma_f32_16x16x32_bf16 v[72:75], v[226:229], v[182:185], v[72:75]
	v_mfma_f32_16x16x32_bf16 v[68:71], v[218:221], v[206:209], v[68:71]
	v_mfma_f32_16x16x32_bf16 v[64:67], v[226:229], v[206:209], v[64:67]
	s_mov_b32 m0, s19
	v_lshl_add_u64 v[232:233], s[2:3], 0, v[156:157]
	s_barrier
	global_load_lds_dwordx4 v[232:233], off
	v_lshl_add_u64 v[234:235], s[2:3], 0, v[128:129]
	s_mov_b32 m0, s24
	s_nop 0
	global_load_lds_dwordx4 v[234:235], off
	ds_read_b128 v[162:165], v137 offset:16384
	ds_read_b128 v[166:169], v137 offset:17408
	ds_read_b128 v[170:173], v137 offset:18432
	ds_read_b128 v[174:177], v137 offset:19456
	ds_read_b128 v[178:181], v137 offset:20480
	ds_read_b128 v[182:185], v137 offset:21504
	ds_read_b128 v[186:189], v137 offset:22528
	ds_read_b128 v[206:209], v137 offset:23552
	s_barrier
	s_waitcnt lgkmcnt(0)
	v_mfma_f32_16x16x32_bf16 v[60:63], v[138:141], v[162:165], 0
	v_mfma_f32_16x16x32_bf16 v[56:59], v[146:149], v[162:165], 0
	v_mfma_f32_16x16x32_bf16 v[52:55], v[138:141], v[170:173], 0
	v_mfma_f32_16x16x32_bf16 v[48:51], v[146:149], v[170:173], 0
	v_mfma_f32_16x16x32_bf16 v[40:43], v[138:141], v[178:181], 0
	v_mfma_f32_16x16x32_bf16 v[32:35], v[146:149], v[178:181], 0
	v_mfma_f32_16x16x32_bf16 v[24:27], v[138:141], v[186:189], 0
	v_mfma_f32_16x16x32_bf16 v[16:19], v[146:149], v[186:189], 0
	v_mfma_f32_16x16x32_bf16 v[60:63], v[142:145], v[166:169], v[60:63]
	v_mfma_f32_16x16x32_bf16 v[56:59], v[150:153], v[166:169], v[56:59]
	v_mfma_f32_16x16x32_bf16 v[52:55], v[142:145], v[174:177], v[52:55]
	v_mfma_f32_16x16x32_bf16 v[48:51], v[150:153], v[174:177], v[48:51]
	v_mfma_f32_16x16x32_bf16 v[40:43], v[142:145], v[182:185], v[40:43]
	v_mfma_f32_16x16x32_bf16 v[32:35], v[150:153], v[182:185], v[32:35]
	v_mfma_f32_16x16x32_bf16 v[24:27], v[142:145], v[206:209], v[24:27]
	v_mfma_f32_16x16x32_bf16 v[16:19], v[150:153], v[206:209], v[16:19]
	s_barrier
	s_add_u32 s6, s62, 0x80000
	s_addc_u32 s7, s63, 0
	s_add_i32 s21, s21, s10
	v_lshl_add_u64 v[138:139], s[6:7], 0, v[156:157]
	s_mov_b32 m0, s21
	s_nop 0
	global_load_lds_dwordx4 v[138:139], off
	v_lshl_add_u64 v[138:139], s[6:7], 0, v[128:129]
	s_add_i32 m0, s21, 0x2000
	s_nop 0
	global_load_lds_dwordx4 v[138:139], off
	s_waitcnt vmcnt(6)
	s_barrier
	v_mfma_f32_16x16x32_bf16 v[44:47], v[214:217], v[162:165], 0
	v_mfma_f32_16x16x32_bf16 v[36:39], v[222:225], v[162:165], 0
	v_mfma_f32_16x16x32_bf16 v[28:31], v[214:217], v[170:173], 0
	v_mfma_f32_16x16x32_bf16 v[20:23], v[222:225], v[170:173], 0
	v_mfma_f32_16x16x32_bf16 v[12:15], v[214:217], v[178:181], 0
	v_mfma_f32_16x16x32_bf16 v[8:11], v[222:225], v[178:181], 0
	v_mfma_f32_16x16x32_bf16 v[4:7], v[214:217], v[186:189], 0
	v_mfma_f32_16x16x32_bf16 v[0:3], v[222:225], v[186:189], 0
	v_mfma_f32_16x16x32_bf16 v[44:47], v[218:221], v[166:169], v[44:47]
	v_mfma_f32_16x16x32_bf16 v[36:39], v[226:229], v[166:169], v[36:39]
	v_mfma_f32_16x16x32_bf16 v[28:31], v[218:221], v[174:177], v[28:31]
	v_mfma_f32_16x16x32_bf16 v[20:23], v[226:229], v[174:177], v[20:23]
	v_mfma_f32_16x16x32_bf16 v[12:15], v[218:221], v[182:185], v[12:15]
	v_mfma_f32_16x16x32_bf16 v[8:11], v[226:229], v[182:185], v[8:11]
	v_mfma_f32_16x16x32_bf16 v[4:7], v[218:221], v[206:209], v[4:7]
	v_mfma_f32_16x16x32_bf16 v[0:3], v[226:229], v[206:209], v[0:3]
	s_add_i32 s6, 0, 0x18000
	v_add_u32_e32 v150, s6, v136
	s_barrier
	s_add_u32 s2, s2, 0x80000
	s_addc_u32 s3, s3, 0
	s_mov_b32 m0, s25
	v_lshl_add_u64 v[214:215], s[2:3], 0, v[156:157]
	global_load_lds_dwordx4 v[214:215], off
	v_lshl_add_u64 v[214:215], s[2:3], 0, v[128:129]
	s_mov_b32 m0, s34
	s_nop 0
	global_load_lds_dwordx4 v[214:215], off
	ds_read_b128 v[138:141], v150
	ds_read_b128 v[142:145], v150 offset:1024
	ds_read_b128 v[146:149], v150 offset:2048
	ds_read_b128 v[150:153], v150 offset:3072
	ds_read_b128 v[162:165], v137 offset:32768
	ds_read_b128 v[166:169], v137 offset:33792
	ds_read_b128 v[170:173], v137 offset:34816
	ds_read_b128 v[174:177], v137 offset:35840
	ds_read_b128 v[178:181], v137 offset:36864
	ds_read_b128 v[182:185], v137 offset:37888
	ds_read_b128 v[186:189], v137 offset:38912
	ds_read_b128 v[206:209], v137 offset:39936
	s_waitcnt lgkmcnt(8)
	s_barrier
	s_waitcnt lgkmcnt(0)
	v_mfma_f32_16x16x32_bf16 v[124:127], v[138:141], v[162:165], v[124:127]
	v_mfma_f32_16x16x32_bf16 v[120:123], v[146:149], v[162:165], v[120:123]
	v_mfma_f32_16x16x32_bf16 v[116:119], v[138:141], v[170:173], v[116:119]
	v_mfma_f32_16x16x32_bf16 v[112:115], v[146:149], v[170:173], v[112:115]
	v_mfma_f32_16x16x32_bf16 v[108:111], v[138:141], v[178:181], v[108:111]
	v_mfma_f32_16x16x32_bf16 v[100:103], v[146:149], v[178:181], v[100:103]
	v_mfma_f32_16x16x32_bf16 v[92:95], v[138:141], v[186:189], v[92:95]
	v_mfma_f32_16x16x32_bf16 v[84:87], v[146:149], v[186:189], v[84:87]
	v_mfma_f32_16x16x32_bf16 v[124:127], v[142:145], v[166:169], v[124:127]
	v_mfma_f32_16x16x32_bf16 v[120:123], v[150:153], v[166:169], v[120:123]
	v_mfma_f32_16x16x32_bf16 v[116:119], v[142:145], v[174:177], v[116:119]
	v_mfma_f32_16x16x32_bf16 v[112:115], v[150:153], v[174:177], v[112:115]
	v_mfma_f32_16x16x32_bf16 v[108:111], v[142:145], v[182:185], v[108:111]
	v_mfma_f32_16x16x32_bf16 v[100:103], v[150:153], v[182:185], v[100:103]
	v_mfma_f32_16x16x32_bf16 v[92:95], v[142:145], v[206:209], v[92:95]
	v_mfma_f32_16x16x32_bf16 v[84:87], v[150:153], v[206:209], v[84:87]
	s_barrier
	s_add_i32 s7, 0, 0x1c000
	s_add_i32 s2, s6, s10
	v_add_u32_e32 v161, s7, v136
	v_lshl_add_u64 v[154:155], v[154:155], 0, s[50:51]
	s_mov_b32 m0, s2
	s_nop 0
	global_load_lds_dwordx4 v[154:155], off
	v_lshl_add_u64 v[154:155], v[230:231], 0, s[50:51]
	s_add_i32 m0, s2, 0x2000
	s_nop 0
	global_load_lds_dwordx4 v[154:155], off
	ds_read_b128 v[214:217], v161
	ds_read_b128 v[218:221], v161 offset:1024
	ds_read_b128 v[222:225], v161 offset:2048
	ds_read_b128 v[226:229], v161 offset:3072
	s_barrier
	s_waitcnt lgkmcnt(0)
	v_mfma_f32_16x16x32_bf16 v[104:107], v[214:217], v[162:165], v[104:107]
	v_mfma_f32_16x16x32_bf16 v[96:99], v[222:225], v[162:165], v[96:99]
	v_mfma_f32_16x16x32_bf16 v[88:91], v[214:217], v[170:173], v[88:91]
	v_mfma_f32_16x16x32_bf16 v[80:83], v[222:225], v[170:173], v[80:83]
	v_mfma_f32_16x16x32_bf16 v[76:79], v[214:217], v[178:181], v[76:79]
	v_mfma_f32_16x16x32_bf16 v[72:75], v[222:225], v[178:181], v[72:75]
	v_mfma_f32_16x16x32_bf16 v[68:71], v[214:217], v[186:189], v[68:71]
	v_mfma_f32_16x16x32_bf16 v[64:67], v[222:225], v[186:189], v[64:67]
	v_mfma_f32_16x16x32_bf16 v[104:107], v[218:221], v[166:169], v[104:107]
	v_mfma_f32_16x16x32_bf16 v[96:99], v[226:229], v[166:169], v[96:99]
	v_mfma_f32_16x16x32_bf16 v[88:91], v[218:221], v[174:177], v[88:91]
	v_mfma_f32_16x16x32_bf16 v[80:83], v[226:229], v[174:177], v[80:83]
	v_mfma_f32_16x16x32_bf16 v[76:79], v[218:221], v[182:185], v[76:79]
	v_mfma_f32_16x16x32_bf16 v[72:75], v[226:229], v[182:185], v[72:75]
	v_mfma_f32_16x16x32_bf16 v[68:71], v[218:221], v[206:209], v[68:71]
	v_mfma_f32_16x16x32_bf16 v[64:67], v[226:229], v[206:209], v[64:67]
	s_mov_b32 m0, s45
	v_lshl_add_u64 v[154:155], v[232:233], 0, s[50:51]
	s_barrier
	global_load_lds_dwordx4 v[154:155], off
	v_lshl_add_u64 v[154:155], v[234:235], 0, s[50:51]
	s_mov_b32 m0, s53
	s_nop 0
	global_load_lds_dwordx4 v[154:155], off
	ds_read_b128 v[162:165], v137 offset:49152
	ds_read_b128 v[166:169], v137 offset:50176
	ds_read_b128 v[170:173], v137 offset:51200
	ds_read_b128 v[174:177], v137 offset:52224
	ds_read_b128 v[178:181], v137 offset:53248
	ds_read_b128 v[182:185], v137 offset:54272
	ds_read_b128 v[186:189], v137 offset:55296
	ds_read_b128 v[206:209], v137 offset:56320
	s_barrier
	s_waitcnt lgkmcnt(0)
	v_mfma_f32_16x16x32_bf16 v[60:63], v[138:141], v[162:165], v[60:63]
	v_mfma_f32_16x16x32_bf16 v[56:59], v[146:149], v[162:165], v[56:59]
	v_mfma_f32_16x16x32_bf16 v[52:55], v[138:141], v[170:173], v[52:55]
	v_mfma_f32_16x16x32_bf16 v[48:51], v[146:149], v[170:173], v[48:51]
	v_mfma_f32_16x16x32_bf16 v[40:43], v[138:141], v[178:181], v[40:43]
	v_mfma_f32_16x16x32_bf16 v[32:35], v[146:149], v[178:181], v[32:35]
	v_mfma_f32_16x16x32_bf16 v[24:27], v[138:141], v[186:189], v[24:27]
	v_mfma_f32_16x16x32_bf16 v[16:19], v[146:149], v[186:189], v[16:19]
	v_mfma_f32_16x16x32_bf16 v[60:63], v[142:145], v[166:169], v[60:63]
	v_mfma_f32_16x16x32_bf16 v[56:59], v[150:153], v[166:169], v[56:59]
	v_mfma_f32_16x16x32_bf16 v[52:55], v[142:145], v[174:177], v[52:55]
	v_mfma_f32_16x16x32_bf16 v[48:51], v[150:153], v[174:177], v[48:51]
	v_mfma_f32_16x16x32_bf16 v[40:43], v[142:145], v[182:185], v[40:43]
	v_mfma_f32_16x16x32_bf16 v[32:35], v[150:153], v[182:185], v[32:35]
	v_mfma_f32_16x16x32_bf16 v[24:27], v[142:145], v[206:209], v[24:27]
	v_mfma_f32_16x16x32_bf16 v[16:19], v[150:153], v[206:209], v[16:19]
	s_barrier
	s_add_u32 s2, s62, 0x80080
	s_addc_u32 s3, s63, 0
	s_add_i32 s6, s7, s10
	v_lshl_add_u64 v[138:139], s[2:3], 0, v[156:157]
	s_mov_b32 m0, s6
	s_nop 0
	global_load_lds_dwordx4 v[138:139], off
	v_lshl_add_u64 v[138:139], s[2:3], 0, v[128:129]
	s_add_i32 m0, s6, 0x2000
	s_nop 0
	global_load_lds_dwordx4 v[138:139], off
	s_waitcnt vmcnt(6)
	s_barrier
	v_mfma_f32_16x16x32_bf16 v[44:47], v[214:217], v[162:165], v[44:47]
	v_mfma_f32_16x16x32_bf16 v[36:39], v[222:225], v[162:165], v[36:39]
	v_mfma_f32_16x16x32_bf16 v[28:31], v[214:217], v[170:173], v[28:31]
	v_mfma_f32_16x16x32_bf16 v[20:23], v[222:225], v[170:173], v[20:23]
	v_mfma_f32_16x16x32_bf16 v[12:15], v[214:217], v[178:181], v[12:15]
	v_mfma_f32_16x16x32_bf16 v[8:11], v[222:225], v[178:181], v[8:11]
	v_mfma_f32_16x16x32_bf16 v[4:7], v[214:217], v[186:189], v[4:7]
	v_mfma_f32_16x16x32_bf16 v[0:3], v[222:225], v[186:189], v[0:3]
	v_mfma_f32_16x16x32_bf16 v[44:47], v[218:221], v[166:169], v[44:47]
	v_mfma_f32_16x16x32_bf16 v[36:39], v[226:229], v[166:169], v[36:39]
	v_mfma_f32_16x16x32_bf16 v[28:31], v[218:221], v[174:177], v[28:31]
	v_mfma_f32_16x16x32_bf16 v[20:23], v[226:229], v[174:177], v[20:23]
	v_mfma_f32_16x16x32_bf16 v[12:15], v[218:221], v[182:185], v[12:15]
	v_mfma_f32_16x16x32_bf16 v[8:11], v[226:229], v[182:185], v[8:11]
	v_mfma_f32_16x16x32_bf16 v[4:7], v[218:221], v[206:209], v[4:7]
	v_mfma_f32_16x16x32_bf16 v[0:3], v[226:229], v[206:209], v[0:3]
	s_add_i32 s54, s54, 2
	s_cmp_gt_u32 s54, 29
	s_mov_b64 s[6:7], s[60:61]
	s_barrier
	s_cbranch_scc1 .Lpost_286
.LBB0_286:
	s_add_u32 s60, s6, 0x100
	s_addc_u32 s61, s7, 0
	s_cmp_lg_u32 s54, 28
	s_cselect_b32 s55, s60, 0
	s_cselect_b32 s21, s61, 0
	s_add_u32 s2, s48, s55
	s_addc_u32 s3, s49, s21
	s_add_i32 s66, 0, 0x10000
	v_add_u32_e32 v150, s66, v136
	ds_read_b128 v[138:141], v150
	ds_read_b128 v[142:145], v150 offset:1024
	ds_read_b128 v[146:149], v150 offset:2048
	ds_read_b128 v[150:153], v150 offset:3072
	s_add_u32 s62, s42, s55
	s_addc_u32 s63, s43, s21
	v_lshl_add_u64 v[154:155], v[134:135], 0, s[6:7]
	s_add_i32 m0, s19, 0xc000
	s_nop 0
	global_load_lds_dwordx4 v[154:155], off
	v_lshl_add_u64 v[154:155], v[132:133], 0, s[6:7]
	s_add_i32 m0, s19, 0xe000
	s_nop 0
	global_load_lds_dwordx4 v[154:155], off
	ds_read_b128 v[162:165], v137
	ds_read_b128 v[166:169], v137 offset:1024
	ds_read_b128 v[170:173], v137 offset:2048
	ds_read_b128 v[174:177], v137 offset:3072
	ds_read_b128 v[178:181], v137 offset:4096
	ds_read_b128 v[182:185], v137 offset:5120
	ds_read_b128 v[186:189], v137 offset:6144
	ds_read_b128 v[206:209], v137 offset:7168
	s_waitcnt lgkmcnt(8)
	s_barrier
	s_waitcnt lgkmcnt(0)
	v_mfma_f32_16x16x32_bf16 v[124:127], v[138:141], v[162:165], v[124:127]
	v_mfma_f32_16x16x32_bf16 v[120:123], v[146:149], v[162:165], v[120:123]
	v_mfma_f32_16x16x32_bf16 v[116:119], v[138:141], v[170:173], v[116:119]
	v_mfma_f32_16x16x32_bf16 v[112:115], v[146:149], v[170:173], v[112:115]
	v_mfma_f32_16x16x32_bf16 v[108:111], v[138:141], v[178:181], v[108:111]
	v_mfma_f32_16x16x32_bf16 v[100:103], v[146:149], v[178:181], v[100:103]
	v_mfma_f32_16x16x32_bf16 v[92:95], v[138:141], v[186:189], v[92:95]
	v_mfma_f32_16x16x32_bf16 v[84:87], v[146:149], v[186:189], v[84:87]
	v_mfma_f32_16x16x32_bf16 v[124:127], v[142:145], v[166:169], v[124:127]
	v_mfma_f32_16x16x32_bf16 v[120:123], v[150:153], v[166:169], v[120:123]
	v_mfma_f32_16x16x32_bf16 v[116:119], v[142:145], v[174:177], v[116:119]
	v_mfma_f32_16x16x32_bf16 v[112:115], v[150:153], v[174:177], v[112:115]
	v_mfma_f32_16x16x32_bf16 v[108:111], v[142:145], v[182:185], v[108:111]
	v_mfma_f32_16x16x32_bf16 v[100:103], v[150:153], v[182:185], v[100:103]
	v_mfma_f32_16x16x32_bf16 v[92:95], v[142:145], v[206:209], v[92:95]
	v_mfma_f32_16x16x32_bf16 v[84:87], v[150:153], v[206:209], v[84:87]
	s_barrier
	s_add_i32 s21, 0, 0x14000
	v_add_u32_e32 v154, s21, v136
	s_add_i32 s6, s66, s10
	ds_read_b128 v[214:217], v154
	ds_read_b128 v[218:221], v154 offset:1024
	ds_read_b128 v[222:225], v154 offset:2048
	ds_read_b128 v[226:229], v154 offset:3072
	v_lshl_add_u64 v[154:155], s[62:63], 0, v[156:157]
	s_mov_b32 m0, s6
	v_lshl_add_u64 v[230:231], s[62:63], 0, v[128:129]
	global_load_lds_dwordx4 v[154:155], off
	s_add_i32 m0, s6, 0x2000
	s_nop 0
	global_load_lds_dwordx4 v[230:231], off
	s_barrier
	s_waitcnt lgkmcnt(0)
	v_mfma_f32_16x16x32_bf16 v[104:107], v[214:217], v[162:165], v[104:107]
	v_mfma_f32_16x16x32_bf16 v[96:99], v[222:225], v[162:165], v[96:99]
	v_mfma_f32_16x16x32_bf16 v[88:91], v[214:217], v[170:173], v[88:91]
	v_mfma_f32_16x16x32_bf16 v[80:83], v[222:225], v[170:173], v[80:83]
	v_mfma_f32_16x16x32_bf16 v[76:79], v[214:217], v[178:181], v[76:79]
	v_mfma_f32_16x16x32_bf16 v[72:75], v[222:225], v[178:181], v[72:75]
	v_mfma_f32_16x16x32_bf16 v[68:71], v[214:217], v[186:189], v[68:71]
	v_mfma_f32_16x16x32_bf16 v[64:67], v[222:225], v[186:189], v[64:67]
	v_mfma_f32_16x16x32_bf16 v[104:107], v[218:221], v[166:169], v[104:107]
	v_mfma_f32_16x16x32_bf16 v[96:99], v[226:229], v[166:169], v[96:99]
	v_mfma_f32_16x16x32_bf16 v[88:91], v[218:221], v[174:177], v[88:91]
	v_mfma_f32_16x16x32_bf16 v[80:83], v[226:229], v[174:177], v[80:83]
	v_mfma_f32_16x16x32_bf16 v[76:79], v[218:221], v[182:185], v[76:79]
	v_mfma_f32_16x16x32_bf16 v[72:75], v[226:229], v[182:185], v[72:75]
	v_mfma_f32_16x16x32_bf16 v[68:71], v[218:221], v[206:209], v[68:71]
	v_mfma_f32_16x16x32_bf16 v[64:67], v[226:229], v[206:209], v[64:67]
	s_mov_b32 m0, s19
	v_lshl_add_u64 v[232:233], s[2:3], 0, v[156:157]
	s_barrier
	global_load_lds_dwordx4 v[232:233], off
	v_lshl_add_u64 v[234:235], s[2:3], 0, v[128:129]
	s_mov_b32 m0, s24
	s_nop 0
	global_load_lds_dwordx4 v[234:235], off
	ds_read_b128 v[162:165], v137 offset:16384
	ds_read_b128 v[166:169], v137 offset:17408
	ds_read_b128 v[170:173], v137 offset:18432
	ds_read_b128 v[174:177], v137 offset:19456
	ds_read_b128 v[178:181], v137 offset:20480
	ds_read_b128 v[182:185], v137 offset:21504
	ds_read_b128 v[186:189], v137 offset:22528
	ds_read_b128 v[206:209], v137 offset:23552
	s_barrier
	s_waitcnt lgkmcnt(0)
	v_mfma_f32_16x16x32_bf16 v[60:63], v[138:141], v[162:165], v[60:63]
	v_mfma_f32_16x16x32_bf16 v[56:59], v[146:149], v[162:165], v[56:59]
	v_mfma_f32_16x16x32_bf16 v[52:55], v[138:141], v[170:173], v[52:55]
	v_mfma_f32_16x16x32_bf16 v[48:51], v[146:149], v[170:173], v[48:51]
	v_mfma_f32_16x16x32_bf16 v[40:43], v[138:141], v[178:181], v[40:43]
	v_mfma_f32_16x16x32_bf16 v[32:35], v[146:149], v[178:181], v[32:35]
	v_mfma_f32_16x16x32_bf16 v[24:27], v[138:141], v[186:189], v[24:27]
	v_mfma_f32_16x16x32_bf16 v[16:19], v[146:149], v[186:189], v[16:19]
	v_mfma_f32_16x16x32_bf16 v[60:63], v[142:145], v[166:169], v[60:63]
	v_mfma_f32_16x16x32_bf16 v[56:59], v[150:153], v[166:169], v[56:59]
	v_mfma_f32_16x16x32_bf16 v[52:55], v[142:145], v[174:177], v[52:55]
	v_mfma_f32_16x16x32_bf16 v[48:51], v[150:153], v[174:177], v[48:51]
	v_mfma_f32_16x16x32_bf16 v[40:43], v[142:145], v[182:185], v[40:43]
	v_mfma_f32_16x16x32_bf16 v[32:35], v[150:153], v[182:185], v[32:35]
	v_mfma_f32_16x16x32_bf16 v[24:27], v[142:145], v[206:209], v[24:27]
	v_mfma_f32_16x16x32_bf16 v[16:19], v[150:153], v[206:209], v[16:19]
	s_barrier
	s_add_u32 s6, s62, 0x80000
	s_addc_u32 s7, s63, 0
	s_add_i32 s21, s21, s10
	v_lshl_add_u64 v[138:139], s[6:7], 0, v[156:157]
	s_mov_b32 m0, s21
	s_nop 0
	global_load_lds_dwordx4 v[138:139], off
	v_lshl_add_u64 v[138:139], s[6:7], 0, v[128:129]
	s_add_i32 m0, s21, 0x2000
	s_nop 0
	global_load_lds_dwordx4 v[138:139], off
	s_waitcnt vmcnt(6)
	s_barrier
	v_mfma_f32_16x16x32_bf16 v[44:47], v[214:217], v[162:165], v[44:47]
	v_mfma_f32_16x16x32_bf16 v[36:39], v[222:225], v[162:165], v[36:39]
	v_mfma_f32_16x16x32_bf16 v[28:31], v[214:217], v[170:173], v[28:31]
	v_mfma_f32_16x16x32_bf16 v[20:23], v[222:225], v[170:173], v[20:23]
	v_mfma_f32_16x16x32_bf16 v[12:15], v[214:217], v[178:181], v[12:15]
	v_mfma_f32_16x16x32_bf16 v[8:11], v[222:225], v[178:181], v[8:11]
	v_mfma_f32_16x16x32_bf16 v[4:7], v[214:217], v[186:189], v[4:7]
	v_mfma_f32_16x16x32_bf16 v[0:3], v[222:225], v[186:189], v[0:3]
	v_mfma_f32_16x16x32_bf16 v[44:47], v[218:221], v[166:169], v[44:47]
	v_mfma_f32_16x16x32_bf16 v[36:39], v[226:229], v[166:169], v[36:39]
	v_mfma_f32_16x16x32_bf16 v[28:31], v[218:221], v[174:177], v[28:31]
	v_mfma_f32_16x16x32_bf16 v[20:23], v[226:229], v[174:177], v[20:23]
	v_mfma_f32_16x16x32_bf16 v[12:15], v[218:221], v[182:185], v[12:15]
	v_mfma_f32_16x16x32_bf16 v[8:11], v[226:229], v[182:185], v[8:11]
	v_mfma_f32_16x16x32_bf16 v[4:7], v[218:221], v[206:209], v[4:7]
	v_mfma_f32_16x16x32_bf16 v[0:3], v[226:229], v[206:209], v[0:3]
	s_add_i32 s6, 0, 0x18000
	v_add_u32_e32 v150, s6, v136
	s_barrier
	ds_read_b128 v[138:141], v150
	ds_read_b128 v[142:145], v150 offset:1024
	ds_read_b128 v[146:149], v150 offset:2048
	ds_read_b128 v[150:153], v150 offset:3072
	s_add_u32 s2, s2, 0x80000
	s_addc_u32 s3, s3, 0
	s_mov_b32 m0, s25
	v_lshl_add_u64 v[214:215], s[2:3], 0, v[156:157]
	global_load_lds_dwordx4 v[214:215], off
	v_lshl_add_u64 v[214:215], s[2:3], 0, v[128:129]
	s_mov_b32 m0, s34
	s_nop 0
	global_load_lds_dwordx4 v[214:215], off
	ds_read_b128 v[162:165], v137 offset:32768
	ds_read_b128 v[166:169], v137 offset:33792
	ds_read_b128 v[170:173], v137 offset:34816
	ds_read_b128 v[174:177], v137 offset:35840
	ds_read_b128 v[178:181], v137 offset:36864
	ds_read_b128 v[182:185], v137 offset:37888
	ds_read_b128 v[186:189], v137 offset:38912
	ds_read_b128 v[206:209], v137 offset:39936
	s_waitcnt lgkmcnt(8)
	s_barrier
	s_waitcnt lgkmcnt(0)
	v_mfma_f32_16x16x32_bf16 v[124:127], v[138:141], v[162:165], v[124:127]
	v_mfma_f32_16x16x32_bf16 v[120:123], v[146:149], v[162:165], v[120:123]
	v_mfma_f32_16x16x32_bf16 v[116:119], v[138:141], v[170:173], v[116:119]
	v_mfma_f32_16x16x32_bf16 v[112:115], v[146:149], v[170:173], v[112:115]
	v_mfma_f32_16x16x32_bf16 v[108:111], v[138:141], v[178:181], v[108:111]
	v_mfma_f32_16x16x32_bf16 v[100:103], v[146:149], v[178:181], v[100:103]
	v_mfma_f32_16x16x32_bf16 v[92:95], v[138:141], v[186:189], v[92:95]
	v_mfma_f32_16x16x32_bf16 v[84:87], v[146:149], v[186:189], v[84:87]
	v_mfma_f32_16x16x32_bf16 v[124:127], v[142:145], v[166:169], v[124:127]
	v_mfma_f32_16x16x32_bf16 v[120:123], v[150:153], v[166:169], v[120:123]
	v_mfma_f32_16x16x32_bf16 v[116:119], v[142:145], v[174:177], v[116:119]
	v_mfma_f32_16x16x32_bf16 v[112:115], v[150:153], v[174:177], v[112:115]
	v_mfma_f32_16x16x32_bf16 v[108:111], v[142:145], v[182:185], v[108:111]
	v_mfma_f32_16x16x32_bf16 v[100:103], v[150:153], v[182:185], v[100:103]
	v_mfma_f32_16x16x32_bf16 v[92:95], v[142:145], v[206:209], v[92:95]
	v_mfma_f32_16x16x32_bf16 v[84:87], v[150:153], v[206:209], v[84:87]
	s_barrier
	s_add_i32 s7, 0, 0x1c000
	s_add_i32 s2, s6, s10
	v_add_u32_e32 v161, s7, v136
	v_lshl_add_u64 v[154:155], v[154:155], 0, s[50:51]
	s_mov_b32 m0, s2
	s_nop 0
	global_load_lds_dwordx4 v[154:155], off
	v_lshl_add_u64 v[154:155], v[230:231], 0, s[50:51]
	s_add_i32 m0, s2, 0x2000
	s_nop 0
	global_load_lds_dwordx4 v[154:155], off
	ds_read_b128 v[214:217], v161
	ds_read_b128 v[218:221], v161 offset:1024
	ds_read_b128 v[222:225], v161 offset:2048
	ds_read_b128 v[226:229], v161 offset:3072
	s_barrier
	s_waitcnt lgkmcnt(0)
	v_mfma_f32_16x16x32_bf16 v[104:107], v[214:217], v[162:165], v[104:107]
	v_mfma_f32_16x16x32_bf16 v[96:99], v[222:225], v[162:165], v[96:99]
	v_mfma_f32_16x16x32_bf16 v[88:91], v[214:217], v[170:173], v[88:91]
	v_mfma_f32_16x16x32_bf16 v[80:83], v[222:225], v[170:173], v[80:83]
	v_mfma_f32_16x16x32_bf16 v[76:79], v[214:217], v[178:181], v[76:79]
	v_mfma_f32_16x16x32_bf16 v[72:75], v[222:225], v[178:181], v[72:75]
	v_mfma_f32_16x16x32_bf16 v[68:71], v[214:217], v[186:189], v[68:71]
	v_mfma_f32_16x16x32_bf16 v[64:67], v[222:225], v[186:189], v[64:67]
	v_mfma_f32_16x16x32_bf16 v[104:107], v[218:221], v[166:169], v[104:107]
	v_mfma_f32_16x16x32_bf16 v[96:99], v[226:229], v[166:169], v[96:99]
	v_mfma_f32_16x16x32_bf16 v[88:91], v[218:221], v[174:177], v[88:91]
	v_mfma_f32_16x16x32_bf16 v[80:83], v[226:229], v[174:177], v[80:83]
	v_mfma_f32_16x16x32_bf16 v[76:79], v[218:221], v[182:185], v[76:79]
	v_mfma_f32_16x16x32_bf16 v[72:75], v[226:229], v[182:185], v[72:75]
	v_mfma_f32_16x16x32_bf16 v[68:71], v[218:221], v[206:209], v[68:71]
	v_mfma_f32_16x16x32_bf16 v[64:67], v[226:229], v[206:209], v[64:67]
	s_mov_b32 m0, s45
	v_lshl_add_u64 v[154:155], v[232:233], 0, s[50:51]
	s_barrier
	global_load_lds_dwordx4 v[154:155], off
	v_lshl_add_u64 v[154:155], v[234:235], 0, s[50:51]
	s_mov_b32 m0, s53
	s_nop 0
	global_load_lds_dwordx4 v[154:155], off
	ds_read_b128 v[162:165], v137 offset:49152
	ds_read_b128 v[166:169], v137 offset:50176
	ds_read_b128 v[170:173], v137 offset:51200
	ds_read_b128 v[174:177], v137 offset:52224
	ds_read_b128 v[178:181], v137 offset:53248
	ds_read_b128 v[182:185], v137 offset:54272
	ds_read_b128 v[186:189], v137 offset:55296
	ds_read_b128 v[206:209], v137 offset:56320
	s_barrier
	s_waitcnt lgkmcnt(0)
	v_mfma_f32_16x16x32_bf16 v[60:63], v[138:141], v[162:165], v[60:63]
	v_mfma_f32_16x16x32_bf16 v[56:59], v[146:149], v[162:165], v[56:59]
	v_mfma_f32_16x16x32_bf16 v[52:55], v[138:141], v[170:173], v[52:55]
	v_mfma_f32_16x16x32_bf16 v[48:51], v[146:149], v[170:173], v[48:51]
	v_mfma_f32_16x16x32_bf16 v[40:43], v[138:141], v[178:181], v[40:43]
	v_mfma_f32_16x16x32_bf16 v[32:35], v[146:149], v[178:181], v[32:35]
	v_mfma_f32_16x16x32_bf16 v[24:27], v[138:141], v[186:189], v[24:27]
	v_mfma_f32_16x16x32_bf16 v[16:19], v[146:149], v[186:189], v[16:19]
	v_mfma_f32_16x16x32_bf16 v[60:63], v[142:145], v[166:169], v[60:63]
	v_mfma_f32_16x16x32_bf16 v[56:59], v[150:153], v[166:169], v[56:59]
	v_mfma_f32_16x16x32_bf16 v[52:55], v[142:145], v[174:177], v[52:55]
	v_mfma_f32_16x16x32_bf16 v[48:51], v[150:153], v[174:177], v[48:51]
	v_mfma_f32_16x16x32_bf16 v[40:43], v[142:145], v[182:185], v[40:43]
	v_mfma_f32_16x16x32_bf16 v[32:35], v[150:153], v[182:185], v[32:35]
	v_mfma_f32_16x16x32_bf16 v[24:27], v[142:145], v[206:209], v[24:27]
	v_mfma_f32_16x16x32_bf16 v[16:19], v[150:153], v[206:209], v[16:19]
	s_barrier
	s_add_u32 s2, s62, 0x80080
	s_addc_u32 s3, s63, 0
	s_add_i32 s6, s7, s10
	v_lshl_add_u64 v[138:139], s[2:3], 0, v[156:157]
	s_mov_b32 m0, s6
	s_nop 0
	global_load_lds_dwordx4 v[138:139], off
	v_lshl_add_u64 v[138:139], s[2:3], 0, v[128:129]
	s_add_i32 m0, s6, 0x2000
	s_nop 0
	global_load_lds_dwordx4 v[138:139], off
	s_waitcnt vmcnt(6)
	s_barrier
	v_mfma_f32_16x16x32_bf16 v[44:47], v[214:217], v[162:165], v[44:47]
	v_mfma_f32_16x16x32_bf16 v[36:39], v[222:225], v[162:165], v[36:39]
	v_mfma_f32_16x16x32_bf16 v[28:31], v[214:217], v[170:173], v[28:31]
	v_mfma_f32_16x16x32_bf16 v[20:23], v[222:225], v[170:173], v[20:23]
	v_mfma_f32_16x16x32_bf16 v[12:15], v[214:217], v[178:181], v[12:15]
	v_mfma_f32_16x16x32_bf16 v[8:11], v[222:225], v[178:181], v[8:11]
	v_mfma_f32_16x16x32_bf16 v[4:7], v[214:217], v[186:189], v[4:7]
	v_mfma_f32_16x16x32_bf16 v[0:3], v[222:225], v[186:189], v[0:3]
	v_mfma_f32_16x16x32_bf16 v[44:47], v[218:221], v[166:169], v[44:47]
	v_mfma_f32_16x16x32_bf16 v[36:39], v[226:229], v[166:169], v[36:39]
	v_mfma_f32_16x16x32_bf16 v[28:31], v[218:221], v[174:177], v[28:31]
	v_mfma_f32_16x16x32_bf16 v[20:23], v[226:229], v[174:177], v[20:23]
	v_mfma_f32_16x16x32_bf16 v[12:15], v[218:221], v[182:185], v[12:15]
	v_mfma_f32_16x16x32_bf16 v[8:11], v[226:229], v[182:185], v[8:11]
	v_mfma_f32_16x16x32_bf16 v[4:7], v[218:221], v[206:209], v[4:7]
	v_mfma_f32_16x16x32_bf16 v[0:3], v[226:229], v[206:209], v[0:3]
	s_add_i32 s54, s54, 2
	s_cmp_gt_u32 s54, 29
	s_mov_b64 s[6:7], s[60:61]
	s_barrier
	s_cbranch_scc0 .LBB0_286

.LBB0_325:
	s_add_i32 s83, s83, 1
	s_mul_i32 s6, s83, s18
	s_add_i32 s10, s6, s20
	s_cmpk_lt_i32 s10, 0x3b8
	s_cselect_b64 s[6:7], -1, 0
	s_cmpk_gt_i32 s10, 0x3b7
	s_cselect_b64 s[68:69], -1, 0
	s_and_b64 s[24:25], s[6:7], exec
	s_cselect_b32 s10, s10, 0
	s_ashr_i32 s21, s10, 31
	s_lshr_b32 s21, s21, 29
	s_add_i32 s21, s10, s21
	s_ashr_i32 s24, s21, 3
	s_and_b32 s21, s21, -8
	s_sub_i32 s10, s10, s21
	s_cmp_lt_i32 s10, 0
	s_movk_i32 s21, 0x78
	s_cselect_b32 s21, s21, 0x77
	s_mul_i32 s10, s21, s10
	s_add_i32 s21, s10, s24
	s_mul_hi_i32 s10, s21, 0x92492493
	s_add_i32 s10, s10, s21
	s_lshr_b32 s24, s10, 31
	s_ashr_i32 s10, s10, 4
	s_add_i32 s25, s10, s24
	s_lshl_b32 s37, s25, 2
	s_sub_i32 s10, 0x88, s37
	s_min_i32 s44, s10, 4
	s_abs_i32 s45, s44
	v_cvt_f32_u32_e32 v0, s45
	s_sub_i32 s46, 0, s45
	s_mul_i32 s25, s25, 28
	s_sub_i32 s21, s21, s25
	v_rcp_iflag_f32_e32 v0, v0
	s_mov_b32 s24, s36
	s_abs_i32 s36, s21
	s_xor_b32 s25, s21, s44
	v_mul_f32_e32 v0, 0x4f7ffffe, v0
	v_cvt_u32_f32_e32 v0, v0
	s_mov_b64 s[42:43], s[48:49]
	s_ashr_i32 s25, s25, 31
	s_mov_b32 s10, s66
	v_readfirstlane_b32 s47, v0
	s_mul_i32 s46, s46, s47
	s_mul_hi_u32 s46, s47, s46
	s_add_i32 s47, s47, s46
	s_mul_hi_u32 s46, s36, s47
	s_mul_i32 s47, s46, s45
	s_sub_i32 s36, s36, s47
	s_add_i32 s47, s46, 1
	s_sub_i32 s48, s36, s45
	s_cmp_ge_u32 s36, s45
	s_cselect_b32 s46, s47, s46
	s_cselect_b32 s36, s48, s36
	s_add_i32 s47, s46, 1
	s_cmp_ge_u32 s36, s45
	s_cselect_b32 s36, s47, s46
	s_xor_b32 s36, s36, s25
	s_sub_i32 s66, s36, s25
	s_mul_i32 s25, s66, s44
	s_sub_i32 s21, s21, s25
	s_add_i32 s36, s37, s21
	s_ashr_i32 s37, s36, 31
	s_lshl_b64 s[44:45], s[36:37], 19
	s_mov_b64 s[2:3], s[62:63]
	s_add_u32 s62, s58, s44
	s_addc_u32 s63, s59, s45
	s_and_b64 s[44:45], s[6:7], exec
	s_cselect_b32 s25, s63, s3
	s_cselect_b32 s37, s62, s2
	s_ashr_i32 s67, s66, 31
	s_lshl_b64 s[44:45], s[66:67], 19
	s_add_u32 s48, s19, s44
	s_addc_u32 s49, s34, s45
	s_and_b64 s[6:7], s[6:7], exec
	s_cselect_b32 s44, s49, s43
	s_cselect_b32 s45, s48, s42
	s_add_u32 s46, s42, 0x100
	s_addc_u32 s47, s43, 0
	s_add_u32 s6, s2, 0x40080
	s_addc_u32 s7, s3, 0
	s_mov_b32 s60, -2
	s_add_u32 s2, s6, 0xfffc0080
	s_addc_u32 s3, s7, -1
	s_add_i32 s21, 0, 0x10000
	v_add_u32_e32 v154, s21, v141
	s_cmp_eq_u32 s60, 12
	s_cselect_b32 s3, s25, s3
	s_cselect_b32 s2, s37, s2
	s_cselect_b32 s43, s44, s47
	s_cselect_b32 s42, s45, s46
	ds_read_b128 v[136:139], v154
	ds_read_b128 v[150:153], v154 offset:1024
	ds_read_b128 v[162:165], v154 offset:2048
	ds_read_b128 v[166:169], v154 offset:3072
	v_lshl_add_u64 v[154:155], s[6:7], 0, v[134:135]
	s_add_i32 m0, s53, 0xc000
	s_nop 0
	global_load_lds_dwordx4 v[154:155], off
	v_lshl_add_u64 v[154:155], s[6:7], 0, v[132:133]
	s_add_i32 m0, s53, 0xe000
	s_nop 0
	global_load_lds_dwordx4 v[154:155], off
	ds_read_b128 v[170:173], v149
	ds_read_b128 v[174:177], v149 offset:1024
	ds_read_b128 v[178:181], v149 offset:2048
	ds_read_b128 v[182:185], v149 offset:3072
	ds_read_b128 v[186:189], v149 offset:4096
	ds_read_b128 v[206:209], v149 offset:5120
	ds_read_b128 v[214:217], v149 offset:6144
	ds_read_b128 v[218:221], v149 offset:7168
	s_waitcnt lgkmcnt(8)
	s_barrier
	s_waitcnt lgkmcnt(0)
	v_mfma_f32_16x16x32_bf16 v[124:127], v[136:139], v[170:173], 0
	v_mfma_f32_16x16x32_bf16 v[120:123], v[162:165], v[170:173], 0
	v_mfma_f32_16x16x32_bf16 v[108:111], v[136:139], v[178:181], 0
	v_mfma_f32_16x16x32_bf16 v[104:107], v[162:165], v[178:181], 0
	v_mfma_f32_16x16x32_bf16 v[92:95], v[136:139], v[186:189], 0
	v_mfma_f32_16x16x32_bf16 v[88:91], v[162:165], v[186:189], 0
	v_mfma_f32_16x16x32_bf16 v[76:79], v[136:139], v[214:217], 0
	v_mfma_f32_16x16x32_bf16 v[72:75], v[162:165], v[214:217], 0
	v_mfma_f32_16x16x32_bf16 v[124:127], v[150:153], v[174:177], v[124:127]
	v_mfma_f32_16x16x32_bf16 v[120:123], v[166:169], v[174:177], v[120:123]
	v_mfma_f32_16x16x32_bf16 v[108:111], v[150:153], v[182:185], v[108:111]
	v_mfma_f32_16x16x32_bf16 v[104:107], v[166:169], v[182:185], v[104:107]
	v_mfma_f32_16x16x32_bf16 v[92:95], v[150:153], v[206:209], v[92:95]
	v_mfma_f32_16x16x32_bf16 v[88:91], v[166:169], v[206:209], v[88:91]
	v_mfma_f32_16x16x32_bf16 v[76:79], v[150:153], v[218:221], v[76:79]
	v_mfma_f32_16x16x32_bf16 v[72:75], v[166:169], v[218:221], v[72:75]
	s_barrier
	s_add_i32 s61, 0, 0x14000
	v_add_u32_e32 v154, s61, v141
	s_add_i32 s21, s21, s35
	ds_read_b128 v[222:225], v154
	ds_read_b128 v[226:229], v154 offset:1024
	ds_read_b128 v[230:233], v154 offset:2048
	ds_read_b128 v[234:237], v154 offset:3072
	v_lshl_add_u64 v[154:155], s[42:43], 0, v[130:131]
	s_mov_b32 m0, s21
	v_lshl_add_u64 v[238:239], s[42:43], 0, v[128:129]
	global_load_lds_dwordx4 v[154:155], off
	s_add_i32 m0, s21, 0x2000
	s_nop 0
	global_load_lds_dwordx4 v[238:239], off
	s_barrier
	s_waitcnt lgkmcnt(0)
	v_mfma_f32_16x16x32_bf16 v[116:119], v[222:225], v[170:173], 0
	v_mfma_f32_16x16x32_bf16 v[112:115], v[230:233], v[170:173], 0
	v_mfma_f32_16x16x32_bf16 v[100:103], v[222:225], v[178:181], 0
	v_mfma_f32_16x16x32_bf16 v[96:99], v[230:233], v[178:181], 0
	v_mfma_f32_16x16x32_bf16 v[84:87], v[222:225], v[186:189], 0
	v_mfma_f32_16x16x32_bf16 v[80:83], v[230:233], v[186:189], 0
	v_mfma_f32_16x16x32_bf16 v[68:71], v[222:225], v[214:217], 0
	v_mfma_f32_16x16x32_bf16 v[64:67], v[230:233], v[214:217], 0
	v_mfma_f32_16x16x32_bf16 v[116:119], v[226:229], v[174:177], v[116:119]
	v_mfma_f32_16x16x32_bf16 v[112:115], v[234:237], v[174:177], v[112:115]
	v_mfma_f32_16x16x32_bf16 v[100:103], v[226:229], v[182:185], v[100:103]
	v_mfma_f32_16x16x32_bf16 v[96:99], v[234:237], v[182:185], v[96:99]
	v_mfma_f32_16x16x32_bf16 v[84:87], v[226:229], v[206:209], v[84:87]
	v_mfma_f32_16x16x32_bf16 v[80:83], v[234:237], v[206:209], v[80:83]
	v_mfma_f32_16x16x32_bf16 v[68:71], v[226:229], v[218:221], v[68:71]
	v_mfma_f32_16x16x32_bf16 v[64:67], v[234:237], v[218:221], v[64:67]
	s_mov_b32 m0, s53
	v_lshl_add_u64 v[240:241], s[2:3], 0, v[130:131]
	s_barrier
	global_load_lds_dwordx4 v[240:241], off
	v_lshl_add_u64 v[242:243], s[2:3], 0, v[128:129]
	s_mov_b32 m0, s54
	s_nop 0
	global_load_lds_dwordx4 v[242:243], off
	ds_read_b128 v[170:173], v149 offset:16384
	ds_read_b128 v[174:177], v149 offset:17408
	ds_read_b128 v[178:181], v149 offset:18432
	ds_read_b128 v[182:185], v149 offset:19456
	ds_read_b128 v[186:189], v149 offset:20480
	ds_read_b128 v[206:209], v149 offset:21504
	ds_read_b128 v[214:217], v149 offset:22528
	ds_read_b128 v[218:221], v149 offset:23552
	s_barrier
	s_waitcnt lgkmcnt(0)
	v_mfma_f32_16x16x32_bf16 v[60:63], v[136:139], v[170:173], 0
	v_mfma_f32_16x16x32_bf16 v[56:59], v[162:165], v[170:173], 0
	v_mfma_f32_16x16x32_bf16 v[44:47], v[136:139], v[178:181], 0
	v_mfma_f32_16x16x32_bf16 v[40:43], v[162:165], v[178:181], 0
	v_mfma_f32_16x16x32_bf16 v[28:31], v[136:139], v[186:189], 0
	v_mfma_f32_16x16x32_bf16 v[24:27], v[162:165], v[186:189], 0
	v_mfma_f32_16x16x32_bf16 v[12:15], v[136:139], v[214:217], 0
	v_mfma_f32_16x16x32_bf16 v[8:11], v[162:165], v[214:217], 0
	v_mfma_f32_16x16x32_bf16 v[60:63], v[150:153], v[174:177], v[60:63]
	v_mfma_f32_16x16x32_bf16 v[56:59], v[166:169], v[174:177], v[56:59]
	v_mfma_f32_16x16x32_bf16 v[44:47], v[150:153], v[182:185], v[44:47]
	v_mfma_f32_16x16x32_bf16 v[40:43], v[166:169], v[182:185], v[40:43]
	v_mfma_f32_16x16x32_bf16 v[28:31], v[150:153], v[206:209], v[28:31]
	v_mfma_f32_16x16x32_bf16 v[24:27], v[166:169], v[206:209], v[24:27]
	v_mfma_f32_16x16x32_bf16 v[12:15], v[150:153], v[218:221], v[12:15]
	v_mfma_f32_16x16x32_bf16 v[8:11], v[166:169], v[218:221], v[8:11]
	s_barrier
	s_add_u32 s80, s42, 0x40000
	s_addc_u32 s81, s43, 0
	s_add_i32 s21, s61, s35
	v_lshl_add_u64 v[136:137], s[80:81], 0, v[130:131]
	s_mov_b32 m0, s21
	s_nop 0
	global_load_lds_dwordx4 v[136:137], off
	v_lshl_add_u64 v[136:137], s[80:81], 0, v[128:129]
	s_add_i32 m0, s21, 0x2000
	s_nop 0
	global_load_lds_dwordx4 v[136:137], off
	s_waitcnt vmcnt(6)
	s_barrier
	v_mfma_f32_16x16x32_bf16 v[52:55], v[222:225], v[170:173], 0
	v_mfma_f32_16x16x32_bf16 v[48:51], v[230:233], v[170:173], 0
	v_mfma_f32_16x16x32_bf16 v[36:39], v[222:225], v[178:181], 0
	v_mfma_f32_16x16x32_bf16 v[32:35], v[230:233], v[178:181], 0
	v_mfma_f32_16x16x32_bf16 v[20:23], v[222:225], v[186:189], 0
	v_mfma_f32_16x16x32_bf16 v[16:19], v[230:233], v[186:189], 0
	v_mfma_f32_16x16x32_bf16 v[4:7], v[222:225], v[214:217], 0
	v_mfma_f32_16x16x32_bf16 v[0:3], v[230:233], v[214:217], 0
	v_mfma_f32_16x16x32_bf16 v[52:55], v[226:229], v[174:177], v[52:55]
	v_mfma_f32_16x16x32_bf16 v[48:51], v[234:237], v[174:177], v[48:51]
	v_mfma_f32_16x16x32_bf16 v[36:39], v[226:229], v[182:185], v[36:39]
	v_mfma_f32_16x16x32_bf16 v[32:35], v[234:237], v[182:185], v[32:35]
	v_mfma_f32_16x16x32_bf16 v[20:23], v[226:229], v[206:209], v[20:23]
	v_mfma_f32_16x16x32_bf16 v[16:19], v[234:237], v[206:209], v[16:19]
	v_mfma_f32_16x16x32_bf16 v[4:7], v[226:229], v[218:221], v[4:7]
	v_mfma_f32_16x16x32_bf16 v[0:3], v[234:237], v[218:221], v[0:3]
	s_add_i32 s21, 0, 0x18000
	v_add_u32_e32 v156, s21, v141
	s_barrier
	s_add_u32 s2, s2, 0x40000
	s_addc_u32 s3, s3, 0
	s_mov_b32 m0, s55
	v_lshl_add_u64 v[222:223], s[2:3], 0, v[130:131]
	global_load_lds_dwordx4 v[222:223], off
	v_lshl_add_u64 v[222:223], s[2:3], 0, v[128:129]
	s_mov_b32 m0, s78
	s_nop 0
	global_load_lds_dwordx4 v[222:223], off
	ds_read_b128 v[136:139], v156
	ds_read_b128 v[150:153], v156 offset:1024
	ds_read_b128 v[162:165], v156 offset:2048
	ds_read_b128 v[166:169], v156 offset:3072
	ds_read_b128 v[170:173], v149 offset:32768
	ds_read_b128 v[174:177], v149 offset:33792
	ds_read_b128 v[178:181], v149 offset:34816
	ds_read_b128 v[182:185], v149 offset:35840
	ds_read_b128 v[186:189], v149 offset:36864
	ds_read_b128 v[206:209], v149 offset:37888
	ds_read_b128 v[214:217], v149 offset:38912
	ds_read_b128 v[218:221], v149 offset:39936
	s_waitcnt lgkmcnt(8)
	s_barrier
	s_waitcnt lgkmcnt(0)
	v_mfma_f32_16x16x32_bf16 v[124:127], v[136:139], v[170:173], v[124:127]
	v_mfma_f32_16x16x32_bf16 v[120:123], v[162:165], v[170:173], v[120:123]
	v_mfma_f32_16x16x32_bf16 v[108:111], v[136:139], v[178:181], v[108:111]
	v_mfma_f32_16x16x32_bf16 v[104:107], v[162:165], v[178:181], v[104:107]
	v_mfma_f32_16x16x32_bf16 v[92:95], v[136:139], v[186:189], v[92:95]
	v_mfma_f32_16x16x32_bf16 v[88:91], v[162:165], v[186:189], v[88:91]
	v_mfma_f32_16x16x32_bf16 v[76:79], v[136:139], v[214:217], v[76:79]
	v_mfma_f32_16x16x32_bf16 v[72:75], v[162:165], v[214:217], v[72:75]
	v_mfma_f32_16x16x32_bf16 v[124:127], v[150:153], v[174:177], v[124:127]
	v_mfma_f32_16x16x32_bf16 v[120:123], v[166:169], v[174:177], v[120:123]
	v_mfma_f32_16x16x32_bf16 v[108:111], v[150:153], v[182:185], v[108:111]
	v_mfma_f32_16x16x32_bf16 v[104:107], v[166:169], v[182:185], v[104:107]
	v_mfma_f32_16x16x32_bf16 v[92:95], v[150:153], v[206:209], v[92:95]
	v_mfma_f32_16x16x32_bf16 v[88:91], v[166:169], v[206:209], v[88:91]
	v_mfma_f32_16x16x32_bf16 v[76:79], v[150:153], v[218:221], v[76:79]
	v_mfma_f32_16x16x32_bf16 v[72:75], v[166:169], v[218:221], v[72:75]
	s_barrier
	s_add_i32 s61, 0, 0x1c000
	s_add_i32 s2, s21, s35
	v_add_u32_e32 v156, s61, v141
	v_lshl_add_u64 v[154:155], v[154:155], 0, s[50:51]
	s_mov_b32 m0, s2
	s_nop 0
	global_load_lds_dwordx4 v[154:155], off
	v_lshl_add_u64 v[154:155], v[238:239], 0, s[50:51]
	s_add_i32 m0, s2, 0x2000
	s_nop 0
	global_load_lds_dwordx4 v[154:155], off
	ds_read_b128 v[222:225], v156
	ds_read_b128 v[226:229], v156 offset:1024
	ds_read_b128 v[230:233], v156 offset:2048
	ds_read_b128 v[234:237], v156 offset:3072
	s_barrier
	s_waitcnt lgkmcnt(0)
	v_mfma_f32_16x16x32_bf16 v[116:119], v[222:225], v[170:173], v[116:119]
	v_mfma_f32_16x16x32_bf16 v[112:115], v[230:233], v[170:173], v[112:115]
	v_mfma_f32_16x16x32_bf16 v[100:103], v[222:225], v[178:181], v[100:103]
	v_mfma_f32_16x16x32_bf16 v[96:99], v[230:233], v[178:181], v[96:99]
	v_mfma_f32_16x16x32_bf16 v[84:87], v[222:225], v[186:189], v[84:87]
	v_mfma_f32_16x16x32_bf16 v[80:83], v[230:233], v[186:189], v[80:83]
	v_mfma_f32_16x16x32_bf16 v[68:71], v[222:225], v[214:217], v[68:71]
	v_mfma_f32_16x16x32_bf16 v[64:67], v[230:233], v[214:217], v[64:67]
	v_mfma_f32_16x16x32_bf16 v[116:119], v[226:229], v[174:177], v[116:119]
	v_mfma_f32_16x16x32_bf16 v[112:115], v[234:237], v[174:177], v[112:115]
	v_mfma_f32_16x16x32_bf16 v[100:103], v[226:229], v[182:185], v[100:103]
	v_mfma_f32_16x16x32_bf16 v[96:99], v[234:237], v[182:185], v[96:99]
	v_mfma_f32_16x16x32_bf16 v[84:87], v[226:229], v[206:209], v[84:87]
	v_mfma_f32_16x16x32_bf16 v[80:83], v[234:237], v[206:209], v[80:83]
	v_mfma_f32_16x16x32_bf16 v[68:71], v[226:229], v[218:221], v[68:71]
	v_mfma_f32_16x16x32_bf16 v[64:67], v[234:237], v[218:221], v[64:67]
	s_mov_b32 m0, s79
	v_lshl_add_u64 v[154:155], v[240:241], 0, s[50:51]
	s_barrier
	global_load_lds_dwordx4 v[154:155], off
	v_lshl_add_u64 v[154:155], v[242:243], 0, s[50:51]
	s_mov_b32 m0, s82
	s_nop 0
	global_load_lds_dwordx4 v[154:155], off
	ds_read_b128 v[170:173], v149 offset:49152
	ds_read_b128 v[174:177], v149 offset:50176
	ds_read_b128 v[178:181], v149 offset:51200
	ds_read_b128 v[182:185], v149 offset:52224
	ds_read_b128 v[186:189], v149 offset:53248
	ds_read_b128 v[206:209], v149 offset:54272
	ds_read_b128 v[214:217], v149 offset:55296
	ds_read_b128 v[218:221], v149 offset:56320
	s_barrier
	s_waitcnt lgkmcnt(0)
	v_mfma_f32_16x16x32_bf16 v[60:63], v[136:139], v[170:173], v[60:63]
	v_mfma_f32_16x16x32_bf16 v[56:59], v[162:165], v[170:173], v[56:59]
	v_mfma_f32_16x16x32_bf16 v[44:47], v[136:139], v[178:181], v[44:47]
	v_mfma_f32_16x16x32_bf16 v[40:43], v[162:165], v[178:181], v[40:43]
	v_mfma_f32_16x16x32_bf16 v[28:31], v[136:139], v[186:189], v[28:31]
	v_mfma_f32_16x16x32_bf16 v[24:27], v[162:165], v[186:189], v[24:27]
	v_mfma_f32_16x16x32_bf16 v[12:15], v[136:139], v[214:217], v[12:15]
	v_mfma_f32_16x16x32_bf16 v[8:11], v[162:165], v[214:217], v[8:11]
	v_mfma_f32_16x16x32_bf16 v[60:63], v[150:153], v[174:177], v[60:63]
	v_mfma_f32_16x16x32_bf16 v[56:59], v[166:169], v[174:177], v[56:59]
	v_mfma_f32_16x16x32_bf16 v[44:47], v[150:153], v[182:185], v[44:47]
	v_mfma_f32_16x16x32_bf16 v[40:43], v[166:169], v[182:185], v[40:43]
	v_mfma_f32_16x16x32_bf16 v[28:31], v[150:153], v[206:209], v[28:31]
	v_mfma_f32_16x16x32_bf16 v[24:27], v[166:169], v[206:209], v[24:27]
	v_mfma_f32_16x16x32_bf16 v[12:15], v[150:153], v[218:221], v[12:15]
	v_mfma_f32_16x16x32_bf16 v[8:11], v[166:169], v[218:221], v[8:11]
	s_barrier
	s_add_u32 s2, s42, 0x40080
	s_addc_u32 s3, s43, 0
	s_add_i32 s21, s61, s35
	v_lshl_add_u64 v[136:137], s[2:3], 0, v[130:131]
	s_mov_b32 m0, s21
	s_nop 0
	global_load_lds_dwordx4 v[136:137], off
	v_lshl_add_u64 v[136:137], s[2:3], 0, v[128:129]
	s_add_i32 m0, s21, 0x2000
	s_nop 0
	global_load_lds_dwordx4 v[136:137], off
	s_waitcnt vmcnt(6)
	s_barrier
	v_mfma_f32_16x16x32_bf16 v[52:55], v[222:225], v[170:173], v[52:55]
	v_mfma_f32_16x16x32_bf16 v[48:51], v[230:233], v[170:173], v[48:51]
	v_mfma_f32_16x16x32_bf16 v[36:39], v[222:225], v[178:181], v[36:39]
	v_mfma_f32_16x16x32_bf16 v[32:35], v[230:233], v[178:181], v[32:35]
	v_mfma_f32_16x16x32_bf16 v[20:23], v[222:225], v[186:189], v[20:23]
	v_mfma_f32_16x16x32_bf16 v[16:19], v[230:233], v[186:189], v[16:19]
	v_mfma_f32_16x16x32_bf16 v[4:7], v[222:225], v[214:217], v[4:7]
	v_mfma_f32_16x16x32_bf16 v[0:3], v[230:233], v[214:217], v[0:3]
	v_mfma_f32_16x16x32_bf16 v[52:55], v[226:229], v[174:177], v[52:55]
	v_mfma_f32_16x16x32_bf16 v[48:51], v[234:237], v[174:177], v[48:51]
	v_mfma_f32_16x16x32_bf16 v[36:39], v[226:229], v[182:185], v[36:39]
	v_mfma_f32_16x16x32_bf16 v[32:35], v[234:237], v[182:185], v[32:35]
	v_mfma_f32_16x16x32_bf16 v[20:23], v[226:229], v[206:209], v[20:23]
	v_mfma_f32_16x16x32_bf16 v[16:19], v[234:237], v[206:209], v[16:19]
	v_mfma_f32_16x16x32_bf16 v[4:7], v[226:229], v[218:221], v[4:7]
	v_mfma_f32_16x16x32_bf16 v[0:3], v[234:237], v[218:221], v[0:3]
	s_add_i32 s60, s60, 2
	s_add_u32 s46, s46, 0x100
	s_addc_u32 s47, s47, 0
	s_add_u32 s6, s6, 0x100
	s_addc_u32 s7, s7, 0
	s_cmp_gt_u32 s60, 13
	s_barrier
	s_cbranch_scc1 .Lpost_326
.LBB0_326:
	s_add_u32 s2, s6, 0xfffc0080
	s_addc_u32 s3, s7, -1
	s_add_i32 s21, 0, 0x10000
	v_add_u32_e32 v154, s21, v141
	ds_read_b128 v[136:139], v154
	ds_read_b128 v[150:153], v154 offset:1024
	ds_read_b128 v[162:165], v154 offset:2048
	ds_read_b128 v[166:169], v154 offset:3072
	s_cmp_eq_u32 s60, 12
	s_cselect_b32 s3, s25, s3
	s_cselect_b32 s2, s37, s2
	s_cselect_b32 s43, s44, s47
	s_cselect_b32 s42, s45, s46
	v_lshl_add_u64 v[154:155], s[6:7], 0, v[134:135]
	s_add_i32 m0, s53, 0xc000
	s_nop 0
	global_load_lds_dwordx4 v[154:155], off
	v_lshl_add_u64 v[154:155], s[6:7], 0, v[132:133]
	s_add_i32 m0, s53, 0xe000
	s_nop 0
	global_load_lds_dwordx4 v[154:155], off
	ds_read_b128 v[170:173], v149
	ds_read_b128 v[174:177], v149 offset:1024
	ds_read_b128 v[178:181], v149 offset:2048
	ds_read_b128 v[182:185], v149 offset:3072
	ds_read_b128 v[186:189], v149 offset:4096
	ds_read_b128 v[206:209], v149 offset:5120
	ds_read_b128 v[214:217], v149 offset:6144
	ds_read_b128 v[218:221], v149 offset:7168
	s_waitcnt lgkmcnt(8)
	s_barrier
	s_waitcnt lgkmcnt(0)
	v_mfma_f32_16x16x32_bf16 v[124:127], v[136:139], v[170:173], v[124:127]
	v_mfma_f32_16x16x32_bf16 v[120:123], v[162:165], v[170:173], v[120:123]
	v_mfma_f32_16x16x32_bf16 v[108:111], v[136:139], v[178:181], v[108:111]
	v_mfma_f32_16x16x32_bf16 v[104:107], v[162:165], v[178:181], v[104:107]
	v_mfma_f32_16x16x32_bf16 v[92:95], v[136:139], v[186:189], v[92:95]
	v_mfma_f32_16x16x32_bf16 v[88:91], v[162:165], v[186:189], v[88:91]
	v_mfma_f32_16x16x32_bf16 v[76:79], v[136:139], v[214:217], v[76:79]
	v_mfma_f32_16x16x32_bf16 v[72:75], v[162:165], v[214:217], v[72:75]
	v_mfma_f32_16x16x32_bf16 v[124:127], v[150:153], v[174:177], v[124:127]
	v_mfma_f32_16x16x32_bf16 v[120:123], v[166:169], v[174:177], v[120:123]
	v_mfma_f32_16x16x32_bf16 v[108:111], v[150:153], v[182:185], v[108:111]
	v_mfma_f32_16x16x32_bf16 v[104:107], v[166:169], v[182:185], v[104:107]
	v_mfma_f32_16x16x32_bf16 v[92:95], v[150:153], v[206:209], v[92:95]
	v_mfma_f32_16x16x32_bf16 v[88:91], v[166:169], v[206:209], v[88:91]
	v_mfma_f32_16x16x32_bf16 v[76:79], v[150:153], v[218:221], v[76:79]
	v_mfma_f32_16x16x32_bf16 v[72:75], v[166:169], v[218:221], v[72:75]
	s_barrier
	s_add_i32 s61, 0, 0x14000
	v_add_u32_e32 v154, s61, v141
	s_add_i32 s21, s21, s35
	ds_read_b128 v[222:225], v154
	ds_read_b128 v[226:229], v154 offset:1024
	ds_read_b128 v[230:233], v154 offset:2048
	ds_read_b128 v[234:237], v154 offset:3072
	v_lshl_add_u64 v[154:155], s[42:43], 0, v[130:131]
	s_mov_b32 m0, s21
	v_lshl_add_u64 v[238:239], s[42:43], 0, v[128:129]
	global_load_lds_dwordx4 v[154:155], off
	s_add_i32 m0, s21, 0x2000
	s_nop 0
	global_load_lds_dwordx4 v[238:239], off
	s_barrier
	s_waitcnt lgkmcnt(0)
	v_mfma_f32_16x16x32_bf16 v[116:119], v[222:225], v[170:173], v[116:119]
	v_mfma_f32_16x16x32_bf16 v[112:115], v[230:233], v[170:173], v[112:115]
	v_mfma_f32_16x16x32_bf16 v[100:103], v[222:225], v[178:181], v[100:103]
	v_mfma_f32_16x16x32_bf16 v[96:99], v[230:233], v[178:181], v[96:99]
	v_mfma_f32_16x16x32_bf16 v[84:87], v[222:225], v[186:189], v[84:87]
	v_mfma_f32_16x16x32_bf16 v[80:83], v[230:233], v[186:189], v[80:83]
	v_mfma_f32_16x16x32_bf16 v[68:71], v[222:225], v[214:217], v[68:71]
	v_mfma_f32_16x16x32_bf16 v[64:67], v[230:233], v[214:217], v[64:67]
	v_mfma_f32_16x16x32_bf16 v[116:119], v[226:229], v[174:177], v[116:119]
	v_mfma_f32_16x16x32_bf16 v[112:115], v[234:237], v[174:177], v[112:115]
	v_mfma_f32_16x16x32_bf16 v[100:103], v[226:229], v[182:185], v[100:103]
	v_mfma_f32_16x16x32_bf16 v[96:99], v[234:237], v[182:185], v[96:99]
	v_mfma_f32_16x16x32_bf16 v[84:87], v[226:229], v[206:209], v[84:87]
	v_mfma_f32_16x16x32_bf16 v[80:83], v[234:237], v[206:209], v[80:83]
	v_mfma_f32_16x16x32_bf16 v[68:71], v[226:229], v[218:221], v[68:71]
	v_mfma_f32_16x16x32_bf16 v[64:67], v[234:237], v[218:221], v[64:67]
	s_mov_b32 m0, s53
	v_lshl_add_u64 v[240:241], s[2:3], 0, v[130:131]
	s_barrier
	global_load_lds_dwordx4 v[240:241], off
	v_lshl_add_u64 v[242:243], s[2:3], 0, v[128:129]
	s_mov_b32 m0, s54
	s_nop 0
	global_load_lds_dwordx4 v[242:243], off
	ds_read_b128 v[170:173], v149 offset:16384
	ds_read_b128 v[174:177], v149 offset:17408
	ds_read_b128 v[178:181], v149 offset:18432
	ds_read_b128 v[182:185], v149 offset:19456
	ds_read_b128 v[186:189], v149 offset:20480
	ds_read_b128 v[206:209], v149 offset:21504
	ds_read_b128 v[214:217], v149 offset:22528
	ds_read_b128 v[218:221], v149 offset:23552
	s_barrier
	s_waitcnt lgkmcnt(0)
	v_mfma_f32_16x16x32_bf16 v[60:63], v[136:139], v[170:173], v[60:63]
	v_mfma_f32_16x16x32_bf16 v[56:59], v[162:165], v[170:173], v[56:59]
	v_mfma_f32_16x16x32_bf16 v[44:47], v[136:139], v[178:181], v[44:47]
	v_mfma_f32_16x16x32_bf16 v[40:43], v[162:165], v[178:181], v[40:43]
	v_mfma_f32_16x16x32_bf16 v[28:31], v[136:139], v[186:189], v[28:31]
	v_mfma_f32_16x16x32_bf16 v[24:27], v[162:165], v[186:189], v[24:27]
	v_mfma_f32_16x16x32_bf16 v[12:15], v[136:139], v[214:217], v[12:15]
	v_mfma_f32_16x16x32_bf16 v[8:11], v[162:165], v[214:217], v[8:11]
	v_mfma_f32_16x16x32_bf16 v[60:63], v[150:153], v[174:177], v[60:63]
	v_mfma_f32_16x16x32_bf16 v[56:59], v[166:169], v[174:177], v[56:59]
	v_mfma_f32_16x16x32_bf16 v[44:47], v[150:153], v[182:185], v[44:47]
	v_mfma_f32_16x16x32_bf16 v[40:43], v[166:169], v[182:185], v[40:43]
	v_mfma_f32_16x16x32_bf16 v[28:31], v[150:153], v[206:209], v[28:31]
	v_mfma_f32_16x16x32_bf16 v[24:27], v[166:169], v[206:209], v[24:27]
	v_mfma_f32_16x16x32_bf16 v[12:15], v[150:153], v[218:221], v[12:15]
	v_mfma_f32_16x16x32_bf16 v[8:11], v[166:169], v[218:221], v[8:11]
	s_barrier
	s_add_u32 s80, s42, 0x40000
	s_addc_u32 s81, s43, 0
	s_add_i32 s21, s61, s35
	v_lshl_add_u64 v[136:137], s[80:81], 0, v[130:131]
	s_mov_b32 m0, s21
	s_nop 0
	global_load_lds_dwordx4 v[136:137], off
	v_lshl_add_u64 v[136:137], s[80:81], 0, v[128:129]
	s_add_i32 m0, s21, 0x2000
	s_nop 0
	global_load_lds_dwordx4 v[136:137], off
	s_waitcnt vmcnt(6)
	s_barrier
	v_mfma_f32_16x16x32_bf16 v[52:55], v[222:225], v[170:173], v[52:55]
	v_mfma_f32_16x16x32_bf16 v[48:51], v[230:233], v[170:173], v[48:51]
	v_mfma_f32_16x16x32_bf16 v[36:39], v[222:225], v[178:181], v[36:39]
	v_mfma_f32_16x16x32_bf16 v[32:35], v[230:233], v[178:181], v[32:35]
	v_mfma_f32_16x16x32_bf16 v[20:23], v[222:225], v[186:189], v[20:23]
	v_mfma_f32_16x16x32_bf16 v[16:19], v[230:233], v[186:189], v[16:19]
	v_mfma_f32_16x16x32_bf16 v[4:7], v[222:225], v[214:217], v[4:7]
	v_mfma_f32_16x16x32_bf16 v[0:3], v[230:233], v[214:217], v[0:3]
	v_mfma_f32_16x16x32_bf16 v[52:55], v[226:229], v[174:177], v[52:55]
	v_mfma_f32_16x16x32_bf16 v[48:51], v[234:237], v[174:177], v[48:51]
	v_mfma_f32_16x16x32_bf16 v[36:39], v[226:229], v[182:185], v[36:39]
	v_mfma_f32_16x16x32_bf16 v[32:35], v[234:237], v[182:185], v[32:35]
	v_mfma_f32_16x16x32_bf16 v[20:23], v[226:229], v[206:209], v[20:23]
	v_mfma_f32_16x16x32_bf16 v[16:19], v[234:237], v[206:209], v[16:19]
	v_mfma_f32_16x16x32_bf16 v[4:7], v[226:229], v[218:221], v[4:7]
	v_mfma_f32_16x16x32_bf16 v[0:3], v[234:237], v[218:221], v[0:3]
	s_add_i32 s21, 0, 0x18000
	v_add_u32_e32 v156, s21, v141
	s_barrier
	ds_read_b128 v[136:139], v156
	ds_read_b128 v[150:153], v156 offset:1024
	ds_read_b128 v[162:165], v156 offset:2048
	ds_read_b128 v[166:169], v156 offset:3072
	s_add_u32 s2, s2, 0x40000
	s_addc_u32 s3, s3, 0
	s_mov_b32 m0, s55
	v_lshl_add_u64 v[222:223], s[2:3], 0, v[130:131]
	global_load_lds_dwordx4 v[222:223], off
	v_lshl_add_u64 v[222:223], s[2:3], 0, v[128:129]
	s_mov_b32 m0, s78
	s_nop 0
	global_load_lds_dwordx4 v[222:223], off
	ds_read_b128 v[170:173], v149 offset:32768
	ds_read_b128 v[174:177], v149 offset:33792
	ds_read_b128 v[178:181], v149 offset:34816
	ds_read_b128 v[182:185], v149 offset:35840
	ds_read_b128 v[186:189], v149 offset:36864
	ds_read_b128 v[206:209], v149 offset:37888
	ds_read_b128 v[214:217], v149 offset:38912
	ds_read_b128 v[218:221], v149 offset:39936
	s_waitcnt lgkmcnt(8)
	s_barrier
	s_waitcnt lgkmcnt(0)
	v_mfma_f32_16x16x32_bf16 v[124:127], v[136:139], v[170:173], v[124:127]
	v_mfma_f32_16x16x32_bf16 v[120:123], v[162:165], v[170:173], v[120:123]
	v_mfma_f32_16x16x32_bf16 v[108:111], v[136:139], v[178:181], v[108:111]
	v_mfma_f32_16x16x32_bf16 v[104:107], v[162:165], v[178:181], v[104:107]
	v_mfma_f32_16x16x32_bf16 v[92:95], v[136:139], v[186:189], v[92:95]
	v_mfma_f32_16x16x32_bf16 v[88:91], v[162:165], v[186:189], v[88:91]
	v_mfma_f32_16x16x32_bf16 v[76:79], v[136:139], v[214:217], v[76:79]
	v_mfma_f32_16x16x32_bf16 v[72:75], v[162:165], v[214:217], v[72:75]
	v_mfma_f32_16x16x32_bf16 v[124:127], v[150:153], v[174:177], v[124:127]
	v_mfma_f32_16x16x32_bf16 v[120:123], v[166:169], v[174:177], v[120:123]
	v_mfma_f32_16x16x32_bf16 v[108:111], v[150:153], v[182:185], v[108:111]
	v_mfma_f32_16x16x32_bf16 v[104:107], v[166:169], v[182:185], v[104:107]
	v_mfma_f32_16x16x32_bf16 v[92:95], v[150:153], v[206:209], v[92:95]
	v_mfma_f32_16x16x32_bf16 v[88:91], v[166:169], v[206:209], v[88:91]
	v_mfma_f32_16x16x32_bf16 v[76:79], v[150:153], v[218:221], v[76:79]
	v_mfma_f32_16x16x32_bf16 v[72:75], v[166:169], v[218:221], v[72:75]
	s_barrier
	s_add_i32 s61, 0, 0x1c000
	s_add_i32 s2, s21, s35
	v_add_u32_e32 v156, s61, v141
	v_lshl_add_u64 v[154:155], v[154:155], 0, s[50:51]
	s_mov_b32 m0, s2
	s_nop 0
	global_load_lds_dwordx4 v[154:155], off
	v_lshl_add_u64 v[154:155], v[238:239], 0, s[50:51]
	s_add_i32 m0, s2, 0x2000
	s_nop 0
	global_load_lds_dwordx4 v[154:155], off
	ds_read_b128 v[222:225], v156
	ds_read_b128 v[226:229], v156 offset:1024
	ds_read_b128 v[230:233], v156 offset:2048
	ds_read_b128 v[234:237], v156 offset:3072
	s_barrier
	s_waitcnt lgkmcnt(0)
	v_mfma_f32_16x16x32_bf16 v[116:119], v[222:225], v[170:173], v[116:119]
	v_mfma_f32_16x16x32_bf16 v[112:115], v[230:233], v[170:173], v[112:115]
	v_mfma_f32_16x16x32_bf16 v[100:103], v[222:225], v[178:181], v[100:103]
	v_mfma_f32_16x16x32_bf16 v[96:99], v[230:233], v[178:181], v[96:99]
	v_mfma_f32_16x16x32_bf16 v[84:87], v[222:225], v[186:189], v[84:87]
	v_mfma_f32_16x16x32_bf16 v[80:83], v[230:233], v[186:189], v[80:83]
	v_mfma_f32_16x16x32_bf16 v[68:71], v[222:225], v[214:217], v[68:71]
	v_mfma_f32_16x16x32_bf16 v[64:67], v[230:233], v[214:217], v[64:67]
	v_mfma_f32_16x16x32_bf16 v[116:119], v[226:229], v[174:177], v[116:119]
	v_mfma_f32_16x16x32_bf16 v[112:115], v[234:237], v[174:177], v[112:115]
	v_mfma_f32_16x16x32_bf16 v[100:103], v[226:229], v[182:185], v[100:103]
	v_mfma_f32_16x16x32_bf16 v[96:99], v[234:237], v[182:185], v[96:99]
	v_mfma_f32_16x16x32_bf16 v[84:87], v[226:229], v[206:209], v[84:87]
	v_mfma_f32_16x16x32_bf16 v[80:83], v[234:237], v[206:209], v[80:83]
	v_mfma_f32_16x16x32_bf16 v[68:71], v[226:229], v[218:221], v[68:71]
	v_mfma_f32_16x16x32_bf16 v[64:67], v[234:237], v[218:221], v[64:67]
	s_mov_b32 m0, s79
	v_lshl_add_u64 v[154:155], v[240:241], 0, s[50:51]
	s_barrier
	global_load_lds_dwordx4 v[154:155], off
	v_lshl_add_u64 v[154:155], v[242:243], 0, s[50:51]
	s_mov_b32 m0, s82
	s_nop 0
	global_load_lds_dwordx4 v[154:155], off
	ds_read_b128 v[170:173], v149 offset:49152
	ds_read_b128 v[174:177], v149 offset:50176
	ds_read_b128 v[178:181], v149 offset:51200
	ds_read_b128 v[182:185], v149 offset:52224
	ds_read_b128 v[186:189], v149 offset:53248
	ds_read_b128 v[206:209], v149 offset:54272
	ds_read_b128 v[214:217], v149 offset:55296
	ds_read_b128 v[218:221], v149 offset:56320
	s_barrier
	s_waitcnt lgkmcnt(0)
	v_mfma_f32_16x16x32_bf16 v[60:63], v[136:139], v[170:173], v[60:63]
	v_mfma_f32_16x16x32_bf16 v[56:59], v[162:165], v[170:173], v[56:59]
	v_mfma_f32_16x16x32_bf16 v[44:47], v[136:139], v[178:181], v[44:47]
	v_mfma_f32_16x16x32_bf16 v[40:43], v[162:165], v[178:181], v[40:43]
	v_mfma_f32_16x16x32_bf16 v[28:31], v[136:139], v[186:189], v[28:31]
	v_mfma_f32_16x16x32_bf16 v[24:27], v[162:165], v[186:189], v[24:27]
	v_mfma_f32_16x16x32_bf16 v[12:15], v[136:139], v[214:217], v[12:15]
	v_mfma_f32_16x16x32_bf16 v[8:11], v[162:165], v[214:217], v[8:11]
	v_mfma_f32_16x16x32_bf16 v[60:63], v[150:153], v[174:177], v[60:63]
	v_mfma_f32_16x16x32_bf16 v[56:59], v[166:169], v[174:177], v[56:59]
	v_mfma_f32_16x16x32_bf16 v[44:47], v[150:153], v[182:185], v[44:47]
	v_mfma_f32_16x16x32_bf16 v[40:43], v[166:169], v[182:185], v[40:43]
	v_mfma_f32_16x16x32_bf16 v[28:31], v[150:153], v[206:209], v[28:31]
	v_mfma_f32_16x16x32_bf16 v[24:27], v[166:169], v[206:209], v[24:27]
	v_mfma_f32_16x16x32_bf16 v[12:15], v[150:153], v[218:221], v[12:15]
	v_mfma_f32_16x16x32_bf16 v[8:11], v[166:169], v[218:221], v[8:11]
	s_barrier
	s_add_u32 s2, s42, 0x40080
	s_addc_u32 s3, s43, 0
	s_add_i32 s21, s61, s35
	v_lshl_add_u64 v[136:137], s[2:3], 0, v[130:131]
	s_mov_b32 m0, s21
	s_nop 0
	global_load_lds_dwordx4 v[136:137], off
	v_lshl_add_u64 v[136:137], s[2:3], 0, v[128:129]
	s_add_i32 m0, s21, 0x2000
	s_nop 0
	global_load_lds_dwordx4 v[136:137], off
	s_waitcnt vmcnt(6)
	s_barrier
	v_mfma_f32_16x16x32_bf16 v[52:55], v[222:225], v[170:173], v[52:55]
	v_mfma_f32_16x16x32_bf16 v[48:51], v[230:233], v[170:173], v[48:51]
	v_mfma_f32_16x16x32_bf16 v[36:39], v[222:225], v[178:181], v[36:39]
	v_mfma_f32_16x16x32_bf16 v[32:35], v[230:233], v[178:181], v[32:35]
	v_mfma_f32_16x16x32_bf16 v[20:23], v[222:225], v[186:189], v[20:23]
	v_mfma_f32_16x16x32_bf16 v[16:19], v[230:233], v[186:189], v[16:19]
	v_mfma_f32_16x16x32_bf16 v[4:7], v[222:225], v[214:217], v[4:7]
	v_mfma_f32_16x16x32_bf16 v[0:3], v[230:233], v[214:217], v[0:3]
	v_mfma_f32_16x16x32_bf16 v[52:55], v[226:229], v[174:177], v[52:55]
	v_mfma_f32_16x16x32_bf16 v[48:51], v[234:237], v[174:177], v[48:51]
	v_mfma_f32_16x16x32_bf16 v[36:39], v[226:229], v[182:185], v[36:39]
	v_mfma_f32_16x16x32_bf16 v[32:35], v[234:237], v[182:185], v[32:35]
	v_mfma_f32_16x16x32_bf16 v[20:23], v[226:229], v[206:209], v[20:23]
	v_mfma_f32_16x16x32_bf16 v[16:19], v[234:237], v[206:209], v[16:19]
	v_mfma_f32_16x16x32_bf16 v[4:7], v[226:229], v[218:221], v[4:7]
	v_mfma_f32_16x16x32_bf16 v[0:3], v[234:237], v[218:221], v[0:3]
	s_add_i32 s60, s60, 2
	s_add_u32 s46, s46, 0x100
	s_addc_u32 s47, s47, 0
	s_add_u32 s6, s6, 0x100
	s_addc_u32 s7, s7, 0
	s_cmp_gt_u32 s60, 13
	s_barrier
	s_cbranch_scc0 .LBB0_326

.LBB0_513:
	s_add_i32 s82, s84, -2
	s_add_u32 s83, s6, 0x100
	s_addc_u32 vcc_lo, s7, 0
	s_add_u32 s6, s60, 0x80
	s_addc_u32 s7, s61, 0
	s_mov_b32 s2, 0
	s_add_i32 vcc_hi, s2, 2
	s_add_u32 s21, s6, 0x80
	s_addc_u32 s3, s7, 0
	s_add_i32 s74, 0, 0x10000
	v_add_u32_e32 v140, s74, v161
	s_cmp_eq_u32 s82, s2
	s_cselect_b32 s2, s80, s21
	s_cselect_b32 s3, s81, s3
	s_cselect_b32 s61, s39, vcc_lo
	s_cselect_b32 s60, s38, s83
	v_lshl_add_u64 v[206:207], s[6:7], 0, v[168:169]
	s_add_i32 m0, s88, 0xc000
	s_nop 0
	global_load_lds_dwordx4 v[206:207], off
	v_lshl_add_u64 v[206:207], s[6:7], 0, v[166:167]
	s_add_i32 m0, s88, 0xe000
	s_nop 0
	global_load_lds_dwordx4 v[206:207], off
	ds_read_b128 v[128:131], v140
	ds_read_b128 v[132:135], v140 offset:1024
	ds_read_b128 v[136:139], v140 offset:2048
	ds_read_b128 v[140:143], v140 offset:3072
	ds_read_b128 v[144:147], v214
	ds_read_b128 v[148:151], v214 offset:1024
	ds_read_b128 v[152:155], v214 offset:2048
	ds_read_b128 v[170:173], v214 offset:3072
	ds_read_b128 v[174:177], v214 offset:4096
	ds_read_b128 v[178:181], v214 offset:5120
	ds_read_b128 v[182:185], v214 offset:6144
	ds_read_b128 v[186:189], v214 offset:7168
	s_waitcnt lgkmcnt(8)
	s_barrier
	s_waitcnt lgkmcnt(0)
	v_mfma_f32_16x16x32_bf16 v[124:127], v[128:131], v[144:147], 0
	v_mfma_f32_16x16x32_bf16 v[120:123], v[136:139], v[144:147], 0
	v_mfma_f32_16x16x32_bf16 v[116:119], v[128:131], v[152:155], 0
	v_mfma_f32_16x16x32_bf16 v[108:111], v[136:139], v[152:155], 0
	v_mfma_f32_16x16x32_bf16 v[100:103], v[128:131], v[174:177], 0
	v_mfma_f32_16x16x32_bf16 v[92:95], v[136:139], v[174:177], 0
	v_mfma_f32_16x16x32_bf16 v[84:87], v[128:131], v[182:185], 0
	v_mfma_f32_16x16x32_bf16 v[76:79], v[136:139], v[182:185], 0
	v_mfma_f32_16x16x32_bf16 v[124:127], v[132:135], v[148:151], v[124:127]
	v_mfma_f32_16x16x32_bf16 v[120:123], v[140:143], v[148:151], v[120:123]
	v_mfma_f32_16x16x32_bf16 v[116:119], v[132:135], v[170:173], v[116:119]
	v_mfma_f32_16x16x32_bf16 v[108:111], v[140:143], v[170:173], v[108:111]
	v_mfma_f32_16x16x32_bf16 v[100:103], v[132:135], v[178:181], v[100:103]
	v_mfma_f32_16x16x32_bf16 v[92:95], v[140:143], v[178:181], v[92:95]
	v_mfma_f32_16x16x32_bf16 v[84:87], v[132:135], v[186:189], v[84:87]
	v_mfma_f32_16x16x32_bf16 v[76:79], v[140:143], v[186:189], v[76:79]
	s_barrier
	s_add_i32 s21, 0, 0x14000
	s_add_i32 s74, s74, s53
	v_add_u32_e32 v215, s21, v161
	v_lshl_add_u64 v[228:229], s[60:61], 0, v[156:157]
	s_mov_b32 m0, s74
	s_nop 0
	global_load_lds_dwordx4 v[228:229], off
	v_lshl_add_u64 v[230:231], s[60:61], 0, v[162:163]
	s_add_i32 m0, s74, 0x2000
	s_nop 0
	global_load_lds_dwordx4 v[230:231], off
	ds_read_b128 v[206:209], v215
	ds_read_b128 v[216:219], v215 offset:1024
	ds_read_b128 v[220:223], v215 offset:2048
	ds_read_b128 v[224:227], v215 offset:3072
	s_barrier
	s_waitcnt lgkmcnt(0)
	v_mfma_f32_16x16x32_bf16 v[112:115], v[206:209], v[144:147], 0
	v_mfma_f32_16x16x32_bf16 v[104:107], v[220:223], v[144:147], 0
	v_mfma_f32_16x16x32_bf16 v[96:99], v[206:209], v[152:155], 0
	v_mfma_f32_16x16x32_bf16 v[88:91], v[220:223], v[152:155], 0
	v_mfma_f32_16x16x32_bf16 v[80:83], v[206:209], v[174:177], 0
	v_mfma_f32_16x16x32_bf16 v[72:75], v[220:223], v[174:177], 0
	v_mfma_f32_16x16x32_bf16 v[68:71], v[206:209], v[182:185], 0
	v_mfma_f32_16x16x32_bf16 v[64:67], v[220:223], v[182:185], 0
	v_mfma_f32_16x16x32_bf16 v[112:115], v[216:219], v[148:151], v[112:115]
	v_mfma_f32_16x16x32_bf16 v[104:107], v[224:227], v[148:151], v[104:107]
	v_mfma_f32_16x16x32_bf16 v[96:99], v[216:219], v[170:173], v[96:99]
	v_mfma_f32_16x16x32_bf16 v[88:91], v[224:227], v[170:173], v[88:91]
	v_mfma_f32_16x16x32_bf16 v[80:83], v[216:219], v[178:181], v[80:83]
	v_mfma_f32_16x16x32_bf16 v[72:75], v[224:227], v[178:181], v[72:75]
	v_mfma_f32_16x16x32_bf16 v[68:71], v[216:219], v[186:189], v[68:71]
	v_mfma_f32_16x16x32_bf16 v[64:67], v[224:227], v[186:189], v[64:67]
	s_mov_b32 m0, s88
	v_lshl_add_u64 v[232:233], s[2:3], 0, v[156:157]
	s_barrier
	global_load_lds_dwordx4 v[232:233], off
	v_lshl_add_u64 v[234:235], s[2:3], 0, v[162:163]
	s_mov_b32 m0, s89
	s_nop 0
	global_load_lds_dwordx4 v[234:235], off
	ds_read_b128 v[144:147], v214 offset:16384
	ds_read_b128 v[148:151], v214 offset:17408
	ds_read_b128 v[152:155], v214 offset:18432
	ds_read_b128 v[170:173], v214 offset:19456
	ds_read_b128 v[174:177], v214 offset:20480
	ds_read_b128 v[178:181], v214 offset:21504
	ds_read_b128 v[182:185], v214 offset:22528
	ds_read_b128 v[186:189], v214 offset:23552
	s_barrier
	s_waitcnt lgkmcnt(0)
	v_mfma_f32_16x16x32_bf16 v[60:63], v[128:131], v[144:147], 0
	v_mfma_f32_16x16x32_bf16 v[56:59], v[136:139], v[144:147], 0
	v_mfma_f32_16x16x32_bf16 v[52:55], v[128:131], v[152:155], 0
	v_mfma_f32_16x16x32_bf16 v[44:47], v[136:139], v[152:155], 0
	v_mfma_f32_16x16x32_bf16 v[36:39], v[128:131], v[174:177], 0
	v_mfma_f32_16x16x32_bf16 v[28:31], v[136:139], v[174:177], 0
	v_mfma_f32_16x16x32_bf16 v[20:23], v[128:131], v[182:185], 0
	v_mfma_f32_16x16x32_bf16 v[12:15], v[136:139], v[182:185], 0
	v_mfma_f32_16x16x32_bf16 v[60:63], v[132:135], v[148:151], v[60:63]
	v_mfma_f32_16x16x32_bf16 v[56:59], v[140:143], v[148:151], v[56:59]
	v_mfma_f32_16x16x32_bf16 v[52:55], v[132:135], v[170:173], v[52:55]
	v_mfma_f32_16x16x32_bf16 v[44:47], v[140:143], v[170:173], v[44:47]
	v_mfma_f32_16x16x32_bf16 v[36:39], v[132:135], v[178:181], v[36:39]
	v_mfma_f32_16x16x32_bf16 v[28:31], v[140:143], v[178:181], v[28:31]
	v_mfma_f32_16x16x32_bf16 v[20:23], v[132:135], v[186:189], v[20:23]
	v_mfma_f32_16x16x32_bf16 v[12:15], v[140:143], v[186:189], v[12:15]
	s_barrier
	s_add_u32 s60, s60, s54
	s_addc_u32 s61, s61, 0
	s_add_i32 s21, s21, s53
	v_lshl_add_u64 v[236:237], s[60:61], 0, v[156:157]
	s_mov_b32 m0, s21
	v_lshl_add_u64 v[238:239], s[60:61], 0, v[162:163]
	global_load_lds_dwordx4 v[236:237], off
	s_add_i32 m0, s21, 0x2000
	s_nop 0
	global_load_lds_dwordx4 v[238:239], off
	s_waitcnt vmcnt(6)
	s_barrier
	v_mfma_f32_16x16x32_bf16 v[48:51], v[206:209], v[144:147], 0
	v_mfma_f32_16x16x32_bf16 v[40:43], v[220:223], v[144:147], 0
	v_mfma_f32_16x16x32_bf16 v[32:35], v[206:209], v[152:155], 0
	v_mfma_f32_16x16x32_bf16 v[24:27], v[220:223], v[152:155], 0
	v_mfma_f32_16x16x32_bf16 v[16:19], v[206:209], v[174:177], 0
	v_mfma_f32_16x16x32_bf16 v[8:11], v[220:223], v[174:177], 0
	v_mfma_f32_16x16x32_bf16 v[4:7], v[206:209], v[182:185], 0
	v_mfma_f32_16x16x32_bf16 v[0:3], v[220:223], v[182:185], 0
	v_mfma_f32_16x16x32_bf16 v[48:51], v[216:219], v[148:151], v[48:51]
	v_mfma_f32_16x16x32_bf16 v[40:43], v[224:227], v[148:151], v[40:43]
	v_mfma_f32_16x16x32_bf16 v[32:35], v[216:219], v[170:173], v[32:35]
	v_mfma_f32_16x16x32_bf16 v[24:27], v[224:227], v[170:173], v[24:27]
	v_mfma_f32_16x16x32_bf16 v[16:19], v[216:219], v[178:181], v[16:19]
	v_mfma_f32_16x16x32_bf16 v[8:11], v[224:227], v[178:181], v[8:11]
	v_mfma_f32_16x16x32_bf16 v[4:7], v[216:219], v[186:189], v[4:7]
	v_mfma_f32_16x16x32_bf16 v[0:3], v[224:227], v[186:189], v[0:3]
	s_add_i32 s21, 0, 0x18000
	v_add_u32_e32 v140, s21, v161
	s_barrier
	s_add_u32 s2, s2, s54
	s_addc_u32 s3, s3, 0
	s_mov_b32 m0, s94
	v_lshl_add_u64 v[206:207], s[2:3], 0, v[156:157]
	global_load_lds_dwordx4 v[206:207], off
	v_lshl_add_u64 v[206:207], s[2:3], 0, v[162:163]
	s_mov_b32 m0, s95
	s_nop 0
	global_load_lds_dwordx4 v[206:207], off
	ds_read_b128 v[128:131], v140
	ds_read_b128 v[132:135], v140 offset:1024
	ds_read_b128 v[136:139], v140 offset:2048
	ds_read_b128 v[140:143], v140 offset:3072
	ds_read_b128 v[144:147], v214 offset:32768
	ds_read_b128 v[148:151], v214 offset:33792
	ds_read_b128 v[152:155], v214 offset:34816
	ds_read_b128 v[170:173], v214 offset:35840
	ds_read_b128 v[174:177], v214 offset:36864
	ds_read_b128 v[178:181], v214 offset:37888
	ds_read_b128 v[182:185], v214 offset:38912
	ds_read_b128 v[186:189], v214 offset:39936
	s_waitcnt lgkmcnt(8)
	s_barrier
	s_waitcnt lgkmcnt(0)
	v_mfma_f32_16x16x32_bf16 v[124:127], v[128:131], v[144:147], v[124:127]
	v_mfma_f32_16x16x32_bf16 v[120:123], v[136:139], v[144:147], v[120:123]
	v_mfma_f32_16x16x32_bf16 v[116:119], v[128:131], v[152:155], v[116:119]
	v_mfma_f32_16x16x32_bf16 v[108:111], v[136:139], v[152:155], v[108:111]
	v_mfma_f32_16x16x32_bf16 v[100:103], v[128:131], v[174:177], v[100:103]
	v_mfma_f32_16x16x32_bf16 v[92:95], v[136:139], v[174:177], v[92:95]
	v_mfma_f32_16x16x32_bf16 v[84:87], v[128:131], v[182:185], v[84:87]
	v_mfma_f32_16x16x32_bf16 v[76:79], v[136:139], v[182:185], v[76:79]
	v_mfma_f32_16x16x32_bf16 v[124:127], v[132:135], v[148:151], v[124:127]
	v_mfma_f32_16x16x32_bf16 v[120:123], v[140:143], v[148:151], v[120:123]
	v_mfma_f32_16x16x32_bf16 v[116:119], v[132:135], v[170:173], v[116:119]
	v_mfma_f32_16x16x32_bf16 v[108:111], v[140:143], v[170:173], v[108:111]
	v_mfma_f32_16x16x32_bf16 v[100:103], v[132:135], v[178:181], v[100:103]
	v_mfma_f32_16x16x32_bf16 v[92:95], v[140:143], v[178:181], v[92:95]
	v_mfma_f32_16x16x32_bf16 v[84:87], v[132:135], v[186:189], v[84:87]
	v_mfma_f32_16x16x32_bf16 v[76:79], v[140:143], v[186:189], v[76:79]
	s_barrier
	s_add_i32 s2, 0, 0x1c000
	s_add_i32 s3, s21, s53
	v_add_u32_e32 v215, s2, v161
	v_lshl_add_u64 v[228:229], v[228:229], 0, s[50:51]
	s_mov_b32 m0, s3
	s_nop 0
	global_load_lds_dwordx4 v[228:229], off
	v_lshl_add_u64 v[228:229], v[230:231], 0, s[50:51]
	s_add_i32 m0, s3, 0x2000
	s_nop 0
	global_load_lds_dwordx4 v[228:229], off
	ds_read_b128 v[206:209], v215
	ds_read_b128 v[216:219], v215 offset:1024
	ds_read_b128 v[220:223], v215 offset:2048
	ds_read_b128 v[224:227], v215 offset:3072
	s_barrier
	s_waitcnt lgkmcnt(0)
	v_mfma_f32_16x16x32_bf16 v[112:115], v[206:209], v[144:147], v[112:115]
	v_mfma_f32_16x16x32_bf16 v[104:107], v[220:223], v[144:147], v[104:107]
	v_mfma_f32_16x16x32_bf16 v[96:99], v[206:209], v[152:155], v[96:99]
	v_mfma_f32_16x16x32_bf16 v[88:91], v[220:223], v[152:155], v[88:91]
	v_mfma_f32_16x16x32_bf16 v[80:83], v[206:209], v[174:177], v[80:83]
	v_mfma_f32_16x16x32_bf16 v[72:75], v[220:223], v[174:177], v[72:75]
	v_mfma_f32_16x16x32_bf16 v[68:71], v[206:209], v[182:185], v[68:71]
	v_mfma_f32_16x16x32_bf16 v[64:67], v[220:223], v[182:185], v[64:67]
	v_mfma_f32_16x16x32_bf16 v[112:115], v[216:219], v[148:151], v[112:115]
	v_mfma_f32_16x16x32_bf16 v[104:107], v[224:227], v[148:151], v[104:107]
	v_mfma_f32_16x16x32_bf16 v[96:99], v[216:219], v[170:173], v[96:99]
	v_mfma_f32_16x16x32_bf16 v[88:91], v[224:227], v[170:173], v[88:91]
	v_mfma_f32_16x16x32_bf16 v[80:83], v[216:219], v[178:181], v[80:83]
	v_mfma_f32_16x16x32_bf16 v[72:75], v[224:227], v[178:181], v[72:75]
	v_mfma_f32_16x16x32_bf16 v[68:71], v[216:219], v[186:189], v[68:71]
	v_mfma_f32_16x16x32_bf16 v[64:67], v[224:227], v[186:189], v[64:67]
	s_mov_b32 m0, s96
	v_lshl_add_u64 v[228:229], v[232:233], 0, s[50:51]
	s_barrier
	global_load_lds_dwordx4 v[228:229], off
	v_lshl_add_u64 v[228:229], v[234:235], 0, s[50:51]
	s_mov_b32 m0, s97
	s_nop 0
	global_load_lds_dwordx4 v[228:229], off
	ds_read_b128 v[144:147], v214 offset:49152
	ds_read_b128 v[148:151], v214 offset:50176
	ds_read_b128 v[152:155], v214 offset:51200
	ds_read_b128 v[170:173], v214 offset:52224
	ds_read_b128 v[174:177], v214 offset:53248
	ds_read_b128 v[178:181], v214 offset:54272
	ds_read_b128 v[182:185], v214 offset:55296
	ds_read_b128 v[186:189], v214 offset:56320
	s_barrier
	s_waitcnt lgkmcnt(0)
	v_mfma_f32_16x16x32_bf16 v[60:63], v[128:131], v[144:147], v[60:63]
	v_mfma_f32_16x16x32_bf16 v[56:59], v[136:139], v[144:147], v[56:59]
	v_mfma_f32_16x16x32_bf16 v[52:55], v[128:131], v[152:155], v[52:55]
	v_mfma_f32_16x16x32_bf16 v[44:47], v[136:139], v[152:155], v[44:47]
	v_mfma_f32_16x16x32_bf16 v[36:39], v[128:131], v[174:177], v[36:39]
	v_mfma_f32_16x16x32_bf16 v[28:31], v[136:139], v[174:177], v[28:31]
	v_mfma_f32_16x16x32_bf16 v[20:23], v[128:131], v[182:185], v[20:23]
	v_mfma_f32_16x16x32_bf16 v[12:15], v[136:139], v[182:185], v[12:15]
	v_mfma_f32_16x16x32_bf16 v[60:63], v[132:135], v[148:151], v[60:63]
	v_mfma_f32_16x16x32_bf16 v[56:59], v[140:143], v[148:151], v[56:59]
	v_mfma_f32_16x16x32_bf16 v[52:55], v[132:135], v[170:173], v[52:55]
	v_mfma_f32_16x16x32_bf16 v[44:47], v[140:143], v[170:173], v[44:47]
	v_mfma_f32_16x16x32_bf16 v[36:39], v[132:135], v[178:181], v[36:39]
	v_mfma_f32_16x16x32_bf16 v[28:31], v[140:143], v[178:181], v[28:31]
	v_mfma_f32_16x16x32_bf16 v[20:23], v[132:135], v[186:189], v[20:23]
	v_mfma_f32_16x16x32_bf16 v[12:15], v[140:143], v[186:189], v[12:15]
	s_barrier
	s_add_i32 s2, s2, s53
	v_lshl_add_u64 v[128:129], v[236:237], 0, s[50:51]
	s_mov_b32 m0, s2
	s_nop 0
	global_load_lds_dwordx4 v[128:129], off
	v_lshl_add_u64 v[128:129], v[238:239], 0, s[50:51]
	s_add_i32 m0, s2, 0x2000
	s_nop 0
	global_load_lds_dwordx4 v[128:129], off
	s_waitcnt vmcnt(6)
	s_barrier
	v_mfma_f32_16x16x32_bf16 v[48:51], v[206:209], v[144:147], v[48:51]
	v_mfma_f32_16x16x32_bf16 v[40:43], v[220:223], v[144:147], v[40:43]
	v_mfma_f32_16x16x32_bf16 v[32:35], v[206:209], v[152:155], v[32:35]
	v_mfma_f32_16x16x32_bf16 v[24:27], v[220:223], v[152:155], v[24:27]
	v_mfma_f32_16x16x32_bf16 v[16:19], v[206:209], v[174:177], v[16:19]
	v_mfma_f32_16x16x32_bf16 v[8:11], v[220:223], v[174:177], v[8:11]
	v_mfma_f32_16x16x32_bf16 v[4:7], v[206:209], v[182:185], v[4:7]
	v_mfma_f32_16x16x32_bf16 v[0:3], v[220:223], v[182:185], v[0:3]
	v_mfma_f32_16x16x32_bf16 v[48:51], v[216:219], v[148:151], v[48:51]
	v_mfma_f32_16x16x32_bf16 v[40:43], v[224:227], v[148:151], v[40:43]
	v_mfma_f32_16x16x32_bf16 v[32:35], v[216:219], v[170:173], v[32:35]
	v_mfma_f32_16x16x32_bf16 v[24:27], v[224:227], v[170:173], v[24:27]
	v_mfma_f32_16x16x32_bf16 v[16:19], v[216:219], v[178:181], v[16:19]
	v_mfma_f32_16x16x32_bf16 v[8:11], v[224:227], v[178:181], v[8:11]
	v_mfma_f32_16x16x32_bf16 v[4:7], v[216:219], v[186:189], v[4:7]
	v_mfma_f32_16x16x32_bf16 v[0:3], v[224:227], v[186:189], v[0:3]
	s_add_u32 s83, s83, 0x100
	s_addc_u32 vcc_lo, vcc_lo, 0
	s_add_u32 s6, s6, 0x100
	s_addc_u32 s7, s7, 0
	s_cmp_ge_u32 vcc_hi, s84
	s_mov_b32 s2, vcc_hi
	s_barrier
	s_cbranch_scc1 .Lpost_514
.LBB0_514:
	s_add_i32 vcc_hi, s2, 2
	s_add_u32 s21, s6, 0x80
	s_addc_u32 s3, s7, 0
	s_add_i32 s74, 0, 0x10000
	v_add_u32_e32 v140, s74, v161
	ds_read_b128 v[128:131], v140
	ds_read_b128 v[132:135], v140 offset:1024
	ds_read_b128 v[136:139], v140 offset:2048
	ds_read_b128 v[140:143], v140 offset:3072
	s_cmp_eq_u32 s82, s2
	s_cselect_b32 s2, s80, s21
	s_cselect_b32 s3, s81, s3
	s_cselect_b32 s61, s39, vcc_lo
	s_cselect_b32 s60, s38, s83
	v_lshl_add_u64 v[206:207], s[6:7], 0, v[168:169]
	s_add_i32 m0, s88, 0xc000
	s_nop 0
	global_load_lds_dwordx4 v[206:207], off
	v_lshl_add_u64 v[206:207], s[6:7], 0, v[166:167]
	s_add_i32 m0, s88, 0xe000
	s_nop 0
	global_load_lds_dwordx4 v[206:207], off
	ds_read_b128 v[144:147], v214
	ds_read_b128 v[148:151], v214 offset:1024
	ds_read_b128 v[152:155], v214 offset:2048
	ds_read_b128 v[170:173], v214 offset:3072
	ds_read_b128 v[174:177], v214 offset:4096
	ds_read_b128 v[178:181], v214 offset:5120
	ds_read_b128 v[182:185], v214 offset:6144
	ds_read_b128 v[186:189], v214 offset:7168
	s_waitcnt lgkmcnt(8)
	s_barrier
	s_waitcnt lgkmcnt(0)
	v_mfma_f32_16x16x32_bf16 v[124:127], v[128:131], v[144:147], v[124:127]
	v_mfma_f32_16x16x32_bf16 v[120:123], v[136:139], v[144:147], v[120:123]
	v_mfma_f32_16x16x32_bf16 v[116:119], v[128:131], v[152:155], v[116:119]
	v_mfma_f32_16x16x32_bf16 v[108:111], v[136:139], v[152:155], v[108:111]
	v_mfma_f32_16x16x32_bf16 v[100:103], v[128:131], v[174:177], v[100:103]
	v_mfma_f32_16x16x32_bf16 v[92:95], v[136:139], v[174:177], v[92:95]
	v_mfma_f32_16x16x32_bf16 v[84:87], v[128:131], v[182:185], v[84:87]
	v_mfma_f32_16x16x32_bf16 v[76:79], v[136:139], v[182:185], v[76:79]
	v_mfma_f32_16x16x32_bf16 v[124:127], v[132:135], v[148:151], v[124:127]
	v_mfma_f32_16x16x32_bf16 v[120:123], v[140:143], v[148:151], v[120:123]
	v_mfma_f32_16x16x32_bf16 v[116:119], v[132:135], v[170:173], v[116:119]
	v_mfma_f32_16x16x32_bf16 v[108:111], v[140:143], v[170:173], v[108:111]
	v_mfma_f32_16x16x32_bf16 v[100:103], v[132:135], v[178:181], v[100:103]
	v_mfma_f32_16x16x32_bf16 v[92:95], v[140:143], v[178:181], v[92:95]
	v_mfma_f32_16x16x32_bf16 v[84:87], v[132:135], v[186:189], v[84:87]
	v_mfma_f32_16x16x32_bf16 v[76:79], v[140:143], v[186:189], v[76:79]
	s_barrier
	s_add_i32 s21, 0, 0x14000
	s_add_i32 s74, s74, s53
	v_add_u32_e32 v215, s21, v161
	v_lshl_add_u64 v[228:229], s[60:61], 0, v[156:157]
	s_mov_b32 m0, s74
	s_nop 0
	global_load_lds_dwordx4 v[228:229], off
	v_lshl_add_u64 v[230:231], s[60:61], 0, v[162:163]
	s_add_i32 m0, s74, 0x2000
	s_nop 0
	global_load_lds_dwordx4 v[230:231], off
	ds_read_b128 v[206:209], v215
	ds_read_b128 v[216:219], v215 offset:1024
	ds_read_b128 v[220:223], v215 offset:2048
	ds_read_b128 v[224:227], v215 offset:3072
	s_barrier
	s_waitcnt lgkmcnt(0)
	v_mfma_f32_16x16x32_bf16 v[112:115], v[206:209], v[144:147], v[112:115]
	v_mfma_f32_16x16x32_bf16 v[104:107], v[220:223], v[144:147], v[104:107]
	v_mfma_f32_16x16x32_bf16 v[96:99], v[206:209], v[152:155], v[96:99]
	v_mfma_f32_16x16x32_bf16 v[88:91], v[220:223], v[152:155], v[88:91]
	v_mfma_f32_16x16x32_bf16 v[80:83], v[206:209], v[174:177], v[80:83]
	v_mfma_f32_16x16x32_bf16 v[72:75], v[220:223], v[174:177], v[72:75]
	v_mfma_f32_16x16x32_bf16 v[68:71], v[206:209], v[182:185], v[68:71]
	v_mfma_f32_16x16x32_bf16 v[64:67], v[220:223], v[182:185], v[64:67]
	v_mfma_f32_16x16x32_bf16 v[112:115], v[216:219], v[148:151], v[112:115]
	v_mfma_f32_16x16x32_bf16 v[104:107], v[224:227], v[148:151], v[104:107]
	v_mfma_f32_16x16x32_bf16 v[96:99], v[216:219], v[170:173], v[96:99]
	v_mfma_f32_16x16x32_bf16 v[88:91], v[224:227], v[170:173], v[88:91]
	v_mfma_f32_16x16x32_bf16 v[80:83], v[216:219], v[178:181], v[80:83]
	v_mfma_f32_16x16x32_bf16 v[72:75], v[224:227], v[178:181], v[72:75]
	v_mfma_f32_16x16x32_bf16 v[68:71], v[216:219], v[186:189], v[68:71]
	v_mfma_f32_16x16x32_bf16 v[64:67], v[224:227], v[186:189], v[64:67]
	s_mov_b32 m0, s88
	v_lshl_add_u64 v[232:233], s[2:3], 0, v[156:157]
	s_barrier
	global_load_lds_dwordx4 v[232:233], off
	v_lshl_add_u64 v[234:235], s[2:3], 0, v[162:163]
	s_mov_b32 m0, s89
	s_nop 0
	global_load_lds_dwordx4 v[234:235], off
	ds_read_b128 v[144:147], v214 offset:16384
	ds_read_b128 v[148:151], v214 offset:17408
	ds_read_b128 v[152:155], v214 offset:18432
	ds_read_b128 v[170:173], v214 offset:19456
	ds_read_b128 v[174:177], v214 offset:20480
	ds_read_b128 v[178:181], v214 offset:21504
	ds_read_b128 v[182:185], v214 offset:22528
	ds_read_b128 v[186:189], v214 offset:23552
	s_barrier
	s_waitcnt lgkmcnt(0)
	v_mfma_f32_16x16x32_bf16 v[60:63], v[128:131], v[144:147], v[60:63]
	v_mfma_f32_16x16x32_bf16 v[56:59], v[136:139], v[144:147], v[56:59]
	v_mfma_f32_16x16x32_bf16 v[52:55], v[128:131], v[152:155], v[52:55]
	v_mfma_f32_16x16x32_bf16 v[44:47], v[136:139], v[152:155], v[44:47]
	v_mfma_f32_16x16x32_bf16 v[36:39], v[128:131], v[174:177], v[36:39]
	v_mfma_f32_16x16x32_bf16 v[28:31], v[136:139], v[174:177], v[28:31]
	v_mfma_f32_16x16x32_bf16 v[20:23], v[128:131], v[182:185], v[20:23]
	v_mfma_f32_16x16x32_bf16 v[12:15], v[136:139], v[182:185], v[12:15]
	v_mfma_f32_16x16x32_bf16 v[60:63], v[132:135], v[148:151], v[60:63]
	v_mfma_f32_16x16x32_bf16 v[56:59], v[140:143], v[148:151], v[56:59]
	v_mfma_f32_16x16x32_bf16 v[52:55], v[132:135], v[170:173], v[52:55]
	v_mfma_f32_16x16x32_bf16 v[44:47], v[140:143], v[170:173], v[44:47]
	v_mfma_f32_16x16x32_bf16 v[36:39], v[132:135], v[178:181], v[36:39]
	v_mfma_f32_16x16x32_bf16 v[28:31], v[140:143], v[178:181], v[28:31]
	v_mfma_f32_16x16x32_bf16 v[20:23], v[132:135], v[186:189], v[20:23]
	v_mfma_f32_16x16x32_bf16 v[12:15], v[140:143], v[186:189], v[12:15]
	s_barrier
	s_add_u32 s60, s60, s54
	s_addc_u32 s61, s61, 0
	s_add_i32 s21, s21, s53
	v_lshl_add_u64 v[236:237], s[60:61], 0, v[156:157]
	s_mov_b32 m0, s21
	v_lshl_add_u64 v[238:239], s[60:61], 0, v[162:163]
	global_load_lds_dwordx4 v[236:237], off
	s_add_i32 m0, s21, 0x2000
	s_nop 0
	global_load_lds_dwordx4 v[238:239], off
	s_waitcnt vmcnt(6)
	s_barrier
	v_mfma_f32_16x16x32_bf16 v[48:51], v[206:209], v[144:147], v[48:51]
	v_mfma_f32_16x16x32_bf16 v[40:43], v[220:223], v[144:147], v[40:43]
	v_mfma_f32_16x16x32_bf16 v[32:35], v[206:209], v[152:155], v[32:35]
	v_mfma_f32_16x16x32_bf16 v[24:27], v[220:223], v[152:155], v[24:27]
	v_mfma_f32_16x16x32_bf16 v[16:19], v[206:209], v[174:177], v[16:19]
	v_mfma_f32_16x16x32_bf16 v[8:11], v[220:223], v[174:177], v[8:11]
	v_mfma_f32_16x16x32_bf16 v[4:7], v[206:209], v[182:185], v[4:7]
	v_mfma_f32_16x16x32_bf16 v[0:3], v[220:223], v[182:185], v[0:3]
	v_mfma_f32_16x16x32_bf16 v[48:51], v[216:219], v[148:151], v[48:51]
	v_mfma_f32_16x16x32_bf16 v[40:43], v[224:227], v[148:151], v[40:43]
	v_mfma_f32_16x16x32_bf16 v[32:35], v[216:219], v[170:173], v[32:35]
	v_mfma_f32_16x16x32_bf16 v[24:27], v[224:227], v[170:173], v[24:27]
	v_mfma_f32_16x16x32_bf16 v[16:19], v[216:219], v[178:181], v[16:19]
	v_mfma_f32_16x16x32_bf16 v[8:11], v[224:227], v[178:181], v[8:11]
	v_mfma_f32_16x16x32_bf16 v[4:7], v[216:219], v[186:189], v[4:7]
	v_mfma_f32_16x16x32_bf16 v[0:3], v[224:227], v[186:189], v[0:3]
	s_add_i32 s21, 0, 0x18000
	v_add_u32_e32 v140, s21, v161
	s_barrier
	ds_read_b128 v[128:131], v140
	ds_read_b128 v[132:135], v140 offset:1024
	ds_read_b128 v[136:139], v140 offset:2048
	ds_read_b128 v[140:143], v140 offset:3072
	s_add_u32 s2, s2, s54
	s_addc_u32 s3, s3, 0
	s_mov_b32 m0, s94
	v_lshl_add_u64 v[206:207], s[2:3], 0, v[156:157]
	global_load_lds_dwordx4 v[206:207], off
	v_lshl_add_u64 v[206:207], s[2:3], 0, v[162:163]
	s_mov_b32 m0, s95
	s_nop 0
	global_load_lds_dwordx4 v[206:207], off
	ds_read_b128 v[144:147], v214 offset:32768
	ds_read_b128 v[148:151], v214 offset:33792
	ds_read_b128 v[152:155], v214 offset:34816
	ds_read_b128 v[170:173], v214 offset:35840
	ds_read_b128 v[174:177], v214 offset:36864
	ds_read_b128 v[178:181], v214 offset:37888
	ds_read_b128 v[182:185], v214 offset:38912
	ds_read_b128 v[186:189], v214 offset:39936
	s_waitcnt lgkmcnt(8)
	s_barrier
	s_waitcnt lgkmcnt(0)
	v_mfma_f32_16x16x32_bf16 v[124:127], v[128:131], v[144:147], v[124:127]
	v_mfma_f32_16x16x32_bf16 v[120:123], v[136:139], v[144:147], v[120:123]
	v_mfma_f32_16x16x32_bf16 v[116:119], v[128:131], v[152:155], v[116:119]
	v_mfma_f32_16x16x32_bf16 v[108:111], v[136:139], v[152:155], v[108:111]
	v_mfma_f32_16x16x32_bf16 v[100:103], v[128:131], v[174:177], v[100:103]
	v_mfma_f32_16x16x32_bf16 v[92:95], v[136:139], v[174:177], v[92:95]
	v_mfma_f32_16x16x32_bf16 v[84:87], v[128:131], v[182:185], v[84:87]
	v_mfma_f32_16x16x32_bf16 v[76:79], v[136:139], v[182:185], v[76:79]
	v_mfma_f32_16x16x32_bf16 v[124:127], v[132:135], v[148:151], v[124:127]
	v_mfma_f32_16x16x32_bf16 v[120:123], v[140:143], v[148:151], v[120:123]
	v_mfma_f32_16x16x32_bf16 v[116:119], v[132:135], v[170:173], v[116:119]
	v_mfma_f32_16x16x32_bf16 v[108:111], v[140:143], v[170:173], v[108:111]
	v_mfma_f32_16x16x32_bf16 v[100:103], v[132:135], v[178:181], v[100:103]
	v_mfma_f32_16x16x32_bf16 v[92:95], v[140:143], v[178:181], v[92:95]
	v_mfma_f32_16x16x32_bf16 v[84:87], v[132:135], v[186:189], v[84:87]
	v_mfma_f32_16x16x32_bf16 v[76:79], v[140:143], v[186:189], v[76:79]
	s_barrier
	s_add_i32 s2, 0, 0x1c000
	s_add_i32 s3, s21, s53
	v_add_u32_e32 v215, s2, v161
	v_lshl_add_u64 v[228:229], v[228:229], 0, s[50:51]
	s_mov_b32 m0, s3
	s_nop 0
	global_load_lds_dwordx4 v[228:229], off
	v_lshl_add_u64 v[228:229], v[230:231], 0, s[50:51]
	s_add_i32 m0, s3, 0x2000
	s_nop 0
	global_load_lds_dwordx4 v[228:229], off
	ds_read_b128 v[206:209], v215
	ds_read_b128 v[216:219], v215 offset:1024
	ds_read_b128 v[220:223], v215 offset:2048
	ds_read_b128 v[224:227], v215 offset:3072
	s_barrier
	s_waitcnt lgkmcnt(0)
	v_mfma_f32_16x16x32_bf16 v[112:115], v[206:209], v[144:147], v[112:115]
	v_mfma_f32_16x16x32_bf16 v[104:107], v[220:223], v[144:147], v[104:107]
	v_mfma_f32_16x16x32_bf16 v[96:99], v[206:209], v[152:155], v[96:99]
	v_mfma_f32_16x16x32_bf16 v[88:91], v[220:223], v[152:155], v[88:91]
	v_mfma_f32_16x16x32_bf16 v[80:83], v[206:209], v[174:177], v[80:83]
	v_mfma_f32_16x16x32_bf16 v[72:75], v[220:223], v[174:177], v[72:75]
	v_mfma_f32_16x16x32_bf16 v[68:71], v[206:209], v[182:185], v[68:71]
	v_mfma_f32_16x16x32_bf16 v[64:67], v[220:223], v[182:185], v[64:67]
	v_mfma_f32_16x16x32_bf16 v[112:115], v[216:219], v[148:151], v[112:115]
	v_mfma_f32_16x16x32_bf16 v[104:107], v[224:227], v[148:151], v[104:107]
	v_mfma_f32_16x16x32_bf16 v[96:99], v[216:219], v[170:173], v[96:99]
	v_mfma_f32_16x16x32_bf16 v[88:91], v[224:227], v[170:173], v[88:91]
	v_mfma_f32_16x16x32_bf16 v[80:83], v[216:219], v[178:181], v[80:83]
	v_mfma_f32_16x16x32_bf16 v[72:75], v[224:227], v[178:181], v[72:75]
	v_mfma_f32_16x16x32_bf16 v[68:71], v[216:219], v[186:189], v[68:71]
	v_mfma_f32_16x16x32_bf16 v[64:67], v[224:227], v[186:189], v[64:67]
	s_mov_b32 m0, s96
	v_lshl_add_u64 v[228:229], v[232:233], 0, s[50:51]
	s_barrier
	global_load_lds_dwordx4 v[228:229], off
	v_lshl_add_u64 v[228:229], v[234:235], 0, s[50:51]
	s_mov_b32 m0, s97
	s_nop 0
	global_load_lds_dwordx4 v[228:229], off
	ds_read_b128 v[144:147], v214 offset:49152
	ds_read_b128 v[148:151], v214 offset:50176
	ds_read_b128 v[152:155], v214 offset:51200
	ds_read_b128 v[170:173], v214 offset:52224
	ds_read_b128 v[174:177], v214 offset:53248
	ds_read_b128 v[178:181], v214 offset:54272
	ds_read_b128 v[182:185], v214 offset:55296
	ds_read_b128 v[186:189], v214 offset:56320
	s_barrier
	s_waitcnt lgkmcnt(0)
	v_mfma_f32_16x16x32_bf16 v[60:63], v[128:131], v[144:147], v[60:63]
	v_mfma_f32_16x16x32_bf16 v[56:59], v[136:139], v[144:147], v[56:59]
	v_mfma_f32_16x16x32_bf16 v[52:55], v[128:131], v[152:155], v[52:55]
	v_mfma_f32_16x16x32_bf16 v[44:47], v[136:139], v[152:155], v[44:47]
	v_mfma_f32_16x16x32_bf16 v[36:39], v[128:131], v[174:177], v[36:39]
	v_mfma_f32_16x16x32_bf16 v[28:31], v[136:139], v[174:177], v[28:31]
	v_mfma_f32_16x16x32_bf16 v[20:23], v[128:131], v[182:185], v[20:23]
	v_mfma_f32_16x16x32_bf16 v[12:15], v[136:139], v[182:185], v[12:15]
	v_mfma_f32_16x16x32_bf16 v[60:63], v[132:135], v[148:151], v[60:63]
	v_mfma_f32_16x16x32_bf16 v[56:59], v[140:143], v[148:151], v[56:59]
	v_mfma_f32_16x16x32_bf16 v[52:55], v[132:135], v[170:173], v[52:55]
	v_mfma_f32_16x16x32_bf16 v[44:47], v[140:143], v[170:173], v[44:47]
	v_mfma_f32_16x16x32_bf16 v[36:39], v[132:135], v[178:181], v[36:39]
	v_mfma_f32_16x16x32_bf16 v[28:31], v[140:143], v[178:181], v[28:31]
	v_mfma_f32_16x16x32_bf16 v[20:23], v[132:135], v[186:189], v[20:23]
	v_mfma_f32_16x16x32_bf16 v[12:15], v[140:143], v[186:189], v[12:15]
	s_barrier
	s_add_i32 s2, s2, s53
	v_lshl_add_u64 v[128:129], v[236:237], 0, s[50:51]
	s_mov_b32 m0, s2
	s_nop 0
	global_load_lds_dwordx4 v[128:129], off
	v_lshl_add_u64 v[128:129], v[238:239], 0, s[50:51]
	s_add_i32 m0, s2, 0x2000
	s_nop 0
	global_load_lds_dwordx4 v[128:129], off
	s_waitcnt vmcnt(6)
	s_barrier
	v_mfma_f32_16x16x32_bf16 v[48:51], v[206:209], v[144:147], v[48:51]
	v_mfma_f32_16x16x32_bf16 v[40:43], v[220:223], v[144:147], v[40:43]
	v_mfma_f32_16x16x32_bf16 v[32:35], v[206:209], v[152:155], v[32:35]
	v_mfma_f32_16x16x32_bf16 v[24:27], v[220:223], v[152:155], v[24:27]
	v_mfma_f32_16x16x32_bf16 v[16:19], v[206:209], v[174:177], v[16:19]
	v_mfma_f32_16x16x32_bf16 v[8:11], v[220:223], v[174:177], v[8:11]
	v_mfma_f32_16x16x32_bf16 v[4:7], v[206:209], v[182:185], v[4:7]
	v_mfma_f32_16x16x32_bf16 v[0:3], v[220:223], v[182:185], v[0:3]
	v_mfma_f32_16x16x32_bf16 v[48:51], v[216:219], v[148:151], v[48:51]
	v_mfma_f32_16x16x32_bf16 v[40:43], v[224:227], v[148:151], v[40:43]
	v_mfma_f32_16x16x32_bf16 v[32:35], v[216:219], v[170:173], v[32:35]
	v_mfma_f32_16x16x32_bf16 v[24:27], v[224:227], v[170:173], v[24:27]
	v_mfma_f32_16x16x32_bf16 v[16:19], v[216:219], v[178:181], v[16:19]
	v_mfma_f32_16x16x32_bf16 v[8:11], v[224:227], v[178:181], v[8:11]
	v_mfma_f32_16x16x32_bf16 v[4:7], v[216:219], v[186:189], v[4:7]
	v_mfma_f32_16x16x32_bf16 v[0:3], v[224:227], v[186:189], v[0:3]
	s_add_u32 s83, s83, 0x100
	s_addc_u32 vcc_lo, vcc_lo, 0
	s_add_u32 s6, s6, 0x100
	s_addc_u32 s7, s7, 0
	s_cmp_ge_u32 vcc_hi, s84
	s_mov_b32 s2, vcc_hi
	s_barrier
	s_cbranch_scc0 .LBB0_514

.LBB0_554:
	s_add_i32 s68, s68, 1
	s_mul_i32 s2, s68, s18
	s_add_i32 s10, s2, s20
	s_cmp_lt_i32 s10, s19
	s_cselect_b64 s[2:3], -1, 0
	s_cmp_ge_i32 s10, s19
	s_cselect_b64 s[38:39], -1, 0
	s_and_b64 s[6:7], s[2:3], exec
	s_cselect_b32 s6, s10, 0
	s_ashr_i32 s7, s6, 31
	s_lshr_b32 s7, s7, 29
	s_add_i32 s7, s6, s7
	s_ashr_i32 s10, s7, 3
	s_and_b32 s7, s7, -8
	s_sub_i32 s6, s6, s7
	s_cmp_lt_i32 s6, 0
	s_cselect_b32 s7, s61, s60
	s_mul_i32 s6, s7, s6
	s_add_i32 s10, s6, s10
	s_mul_hi_i32 s6, s10, 0x2e8ba2e9
	s_lshr_b32 s7, s6, 31
	s_ashr_i32 s6, s6, 4
	s_add_i32 s24, s6, s7
	s_lshl_b32 s25, s24, 2
	s_sub_i32 s6, s9, s25
	s_min_i32 s41, s6, 4
	s_abs_i32 s40, s41
	v_cvt_f32_u32_e32 v0, s40
	s_mov_b64 s[6:7], s[34:35]
	s_mov_b64 s[54:55], s[36:37]
	s_sub_i32 s35, 0, s40
	v_rcp_iflag_f32_e32 v0, v0
	s_mulk_i32 s24, 0x58
	s_sub_i32 s10, s10, s24
	s_abs_i32 s34, s10
	v_mul_f32_e32 v0, 0x4f7ffffe, v0
	v_cvt_u32_f32_e32 v0, v0
	s_xor_b32 s24, s10, s41
	s_ashr_i32 s24, s24, 31
	s_mov_b32 s73, -2
	v_readfirstlane_b32 s36, v0
	s_mul_i32 s35, s35, s36
	s_mul_hi_u32 s35, s36, s35
	s_add_i32 s36, s36, s35
	s_mul_hi_u32 s35, s34, s36
	s_mul_i32 s36, s35, s40
	s_sub_i32 s34, s34, s36
	s_add_i32 s36, s35, 1
	s_sub_i32 s37, s34, s40
	s_cmp_ge_u32 s34, s40
	s_cselect_b32 s35, s36, s35
	s_cselect_b32 s34, s37, s34
	s_add_i32 s36, s35, 1
	s_cmp_ge_u32 s34, s40
	s_cselect_b32 s34, s36, s35
	s_xor_b32 s34, s34, s24
	s_sub_i32 s40, s34, s24
	s_mul_i32 s24, s40, s41
	s_sub_i32 s10, s10, s24
	s_add_i32 s42, s25, s10
	s_ashr_i32 s43, s42, 31
	s_lshl_b64 s[24:25], s[42:43], 19
	s_add_u32 s34, s58, s24
	s_addc_u32 s35, s59, s25
	s_and_b64 s[24:25], s[2:3], exec
	s_cselect_b32 s10, s35, s7
	s_cselect_b32 s24, s34, s6
	s_ashr_i32 s41, s40, 31
	s_lshl_b64 s[36:37], s[40:41], 19
	s_add_u32 s36, s44, s36
	s_addc_u32 s37, s45, s37
	s_and_b64 s[2:3], s[2:3], exec
	s_cselect_b32 s25, s37, s55
	s_cselect_b32 s41, s36, s54
	s_add_u32 s43, s54, 0x100
	s_addc_u32 s69, s55, 0
	s_add_u32 s6, s6, 0x40080
	s_addc_u32 s7, s7, 0
	s_add_u32 s2, s6, 0xfffc0080
	s_addc_u32 s3, s7, -1
	s_add_i32 s77, 0, 0x10000
	v_add_u32_e32 v150, s77, v139
	s_cmp_eq_u32 s73, 12
	s_cselect_b32 s3, s10, s3
	s_cselect_b32 s2, s24, s2
	s_cselect_b32 s55, s25, s69
	s_cselect_b32 s54, s41, s43
	v_lshl_add_u64 v[154:155], s[6:7], 0, v[132:133]
	s_add_i32 m0, s47, 0xc000
	s_nop 0
	global_load_lds_dwordx4 v[154:155], off
	v_lshl_add_u64 v[154:155], s[6:7], 0, v[130:131]
	s_add_i32 m0, s47, 0xe000
	s_nop 0
	global_load_lds_dwordx4 v[154:155], off
	ds_read_b128 v[134:137], v150
	ds_read_b128 v[142:145], v150 offset:1024
	ds_read_b128 v[146:149], v150 offset:2048
	ds_read_b128 v[150:153], v150 offset:3072
	ds_read_b128 v[162:165], v141
	ds_read_b128 v[166:169], v141 offset:1024
	ds_read_b128 v[170:173], v141 offset:2048
	ds_read_b128 v[174:177], v141 offset:3072
	ds_read_b128 v[178:181], v141 offset:4096
	ds_read_b128 v[182:185], v141 offset:5120
	ds_read_b128 v[186:189], v141 offset:6144
	ds_read_b128 v[214:217], v141 offset:7168
	s_waitcnt lgkmcnt(8)
	s_barrier
	s_waitcnt lgkmcnt(0)
	v_mfma_f32_16x16x32_bf16 v[124:127], v[134:137], v[162:165], 0
	v_mfma_f32_16x16x32_bf16 v[116:119], v[146:149], v[162:165], 0
	v_mfma_f32_16x16x32_bf16 v[108:111], v[134:137], v[170:173], 0
	v_mfma_f32_16x16x32_bf16 v[100:103], v[146:149], v[170:173], 0
	v_mfma_f32_16x16x32_bf16 v[92:95], v[134:137], v[178:181], 0
	v_mfma_f32_16x16x32_bf16 v[84:87], v[146:149], v[178:181], 0
	v_mfma_f32_16x16x32_bf16 v[76:79], v[134:137], v[186:189], 0
	v_mfma_f32_16x16x32_bf16 v[68:71], v[146:149], v[186:189], 0
	v_mfma_f32_16x16x32_bf16 v[124:127], v[142:145], v[166:169], v[124:127]
	v_mfma_f32_16x16x32_bf16 v[116:119], v[150:153], v[166:169], v[116:119]
	v_mfma_f32_16x16x32_bf16 v[108:111], v[142:145], v[174:177], v[108:111]
	v_mfma_f32_16x16x32_bf16 v[100:103], v[150:153], v[174:177], v[100:103]
	v_mfma_f32_16x16x32_bf16 v[92:95], v[142:145], v[182:185], v[92:95]
	v_mfma_f32_16x16x32_bf16 v[84:87], v[150:153], v[182:185], v[84:87]
	v_mfma_f32_16x16x32_bf16 v[76:79], v[142:145], v[214:217], v[76:79]
	v_mfma_f32_16x16x32_bf16 v[68:71], v[150:153], v[214:217], v[68:71]
	s_barrier
	s_add_i32 s80, 0, 0x14000
	v_add_u32_e32 v154, s80, v139
	s_add_i32 s77, s77, s53
	ds_read_b128 v[218:221], v154
	ds_read_b128 v[222:225], v154 offset:1024
	ds_read_b128 v[226:229], v154 offset:2048
	ds_read_b128 v[230:233], v154 offset:3072
	v_lshl_add_u64 v[154:155], s[54:55], 0, v[156:157]
	s_mov_b32 m0, s77
	v_lshl_add_u64 v[206:207], s[54:55], 0, v[128:129]
	global_load_lds_dwordx4 v[154:155], off
	s_add_i32 m0, s77, 0x2000
	s_nop 0
	global_load_lds_dwordx4 v[206:207], off
	s_barrier
	s_waitcnt lgkmcnt(0)
	v_mfma_f32_16x16x32_bf16 v[120:123], v[218:221], v[162:165], 0
	v_mfma_f32_16x16x32_bf16 v[112:115], v[226:229], v[162:165], 0
	v_mfma_f32_16x16x32_bf16 v[104:107], v[218:221], v[170:173], 0
	v_mfma_f32_16x16x32_bf16 v[96:99], v[226:229], v[170:173], 0
	v_mfma_f32_16x16x32_bf16 v[88:91], v[218:221], v[178:181], 0
	v_mfma_f32_16x16x32_bf16 v[80:83], v[226:229], v[178:181], 0
	v_mfma_f32_16x16x32_bf16 v[72:75], v[218:221], v[186:189], 0
	v_mfma_f32_16x16x32_bf16 v[64:67], v[226:229], v[186:189], 0
	v_mfma_f32_16x16x32_bf16 v[120:123], v[222:225], v[166:169], v[120:123]
	v_mfma_f32_16x16x32_bf16 v[112:115], v[230:233], v[166:169], v[112:115]
	v_mfma_f32_16x16x32_bf16 v[104:107], v[222:225], v[174:177], v[104:107]
	v_mfma_f32_16x16x32_bf16 v[96:99], v[230:233], v[174:177], v[96:99]
	v_mfma_f32_16x16x32_bf16 v[88:91], v[222:225], v[182:185], v[88:91]
	v_mfma_f32_16x16x32_bf16 v[80:83], v[230:233], v[182:185], v[80:83]
	v_mfma_f32_16x16x32_bf16 v[72:75], v[222:225], v[214:217], v[72:75]
	v_mfma_f32_16x16x32_bf16 v[64:67], v[230:233], v[214:217], v[64:67]
	s_mov_b32 m0, s47
	v_lshl_add_u64 v[208:209], s[2:3], 0, v[156:157]
	s_barrier
	global_load_lds_dwordx4 v[208:209], off
	v_lshl_add_u64 v[234:235], s[2:3], 0, v[128:129]
	s_mov_b32 m0, s49
	s_nop 0
	global_load_lds_dwordx4 v[234:235], off
	ds_read_b128 v[162:165], v141 offset:16384
	ds_read_b128 v[166:169], v141 offset:17408
	ds_read_b128 v[170:173], v141 offset:18432
	ds_read_b128 v[174:177], v141 offset:19456
	ds_read_b128 v[178:181], v141 offset:20480
	ds_read_b128 v[182:185], v141 offset:21504
	ds_read_b128 v[186:189], v141 offset:22528
	ds_read_b128 v[214:217], v141 offset:23552
	s_barrier
	s_waitcnt lgkmcnt(0)
	v_mfma_f32_16x16x32_bf16 v[60:63], v[134:137], v[162:165], 0
	v_mfma_f32_16x16x32_bf16 v[52:55], v[146:149], v[162:165], 0
	v_mfma_f32_16x16x32_bf16 v[44:47], v[134:137], v[170:173], 0
	v_mfma_f32_16x16x32_bf16 v[36:39], v[146:149], v[170:173], 0
	v_mfma_f32_16x16x32_bf16 v[28:31], v[134:137], v[178:181], 0
	v_mfma_f32_16x16x32_bf16 v[20:23], v[146:149], v[178:181], 0
	v_mfma_f32_16x16x32_bf16 v[12:15], v[134:137], v[186:189], 0
	v_mfma_f32_16x16x32_bf16 v[4:7], v[146:149], v[186:189], 0
	v_mfma_f32_16x16x32_bf16 v[60:63], v[142:145], v[166:169], v[60:63]
	v_mfma_f32_16x16x32_bf16 v[52:55], v[150:153], v[166:169], v[52:55]
	v_mfma_f32_16x16x32_bf16 v[44:47], v[142:145], v[174:177], v[44:47]
	v_mfma_f32_16x16x32_bf16 v[36:39], v[150:153], v[174:177], v[36:39]
	v_mfma_f32_16x16x32_bf16 v[28:31], v[142:145], v[182:185], v[28:31]
	v_mfma_f32_16x16x32_bf16 v[20:23], v[150:153], v[182:185], v[20:23]
	v_mfma_f32_16x16x32_bf16 v[12:15], v[142:145], v[214:217], v[12:15]
	v_mfma_f32_16x16x32_bf16 v[4:7], v[150:153], v[214:217], v[4:7]
	s_barrier
	s_add_u32 s78, s54, 0x40000
	s_addc_u32 s79, s55, 0
	s_add_i32 s77, s80, s53
	v_lshl_add_u64 v[134:135], s[78:79], 0, v[156:157]
	s_mov_b32 m0, s77
	s_nop 0
	global_load_lds_dwordx4 v[134:135], off
	v_lshl_add_u64 v[134:135], s[78:79], 0, v[128:129]
	s_add_i32 m0, s77, 0x2000
	s_nop 0
	global_load_lds_dwordx4 v[134:135], off
	s_waitcnt vmcnt(6)
	s_barrier
	v_mfma_f32_16x16x32_bf16 v[56:59], v[218:221], v[162:165], 0
	v_mfma_f32_16x16x32_bf16 v[48:51], v[226:229], v[162:165], 0
	v_mfma_f32_16x16x32_bf16 v[40:43], v[218:221], v[170:173], 0
	v_mfma_f32_16x16x32_bf16 v[32:35], v[226:229], v[170:173], 0
	v_mfma_f32_16x16x32_bf16 v[24:27], v[218:221], v[178:181], 0
	v_mfma_f32_16x16x32_bf16 v[16:19], v[226:229], v[178:181], 0
	v_mfma_f32_16x16x32_bf16 v[8:11], v[218:221], v[186:189], 0
	v_mfma_f32_16x16x32_bf16 v[0:3], v[226:229], v[186:189], 0
	v_mfma_f32_16x16x32_bf16 v[56:59], v[222:225], v[166:169], v[56:59]
	v_mfma_f32_16x16x32_bf16 v[48:51], v[230:233], v[166:169], v[48:51]
	v_mfma_f32_16x16x32_bf16 v[40:43], v[222:225], v[174:177], v[40:43]
	v_mfma_f32_16x16x32_bf16 v[32:35], v[230:233], v[174:177], v[32:35]
	v_mfma_f32_16x16x32_bf16 v[24:27], v[222:225], v[182:185], v[24:27]
	v_mfma_f32_16x16x32_bf16 v[16:19], v[230:233], v[182:185], v[16:19]
	v_mfma_f32_16x16x32_bf16 v[8:11], v[222:225], v[214:217], v[8:11]
	v_mfma_f32_16x16x32_bf16 v[0:3], v[230:233], v[214:217], v[0:3]
	s_add_i32 s77, 0, 0x18000
	v_add_u32_e32 v150, s77, v139
	s_barrier
	s_add_u32 s2, s2, 0x40000
	s_addc_u32 s3, s3, 0
	s_mov_b32 m0, s62
	v_lshl_add_u64 v[218:219], s[2:3], 0, v[156:157]
	global_load_lds_dwordx4 v[218:219], off
	v_lshl_add_u64 v[218:219], s[2:3], 0, v[128:129]
	s_mov_b32 m0, s63
	s_nop 0
	global_load_lds_dwordx4 v[218:219], off
	ds_read_b128 v[134:137], v150
	ds_read_b128 v[142:145], v150 offset:1024
	ds_read_b128 v[146:149], v150 offset:2048
	ds_read_b128 v[150:153], v150 offset:3072
	ds_read_b128 v[162:165], v141 offset:32768
	ds_read_b128 v[166:169], v141 offset:33792
	ds_read_b128 v[170:173], v141 offset:34816
	ds_read_b128 v[174:177], v141 offset:35840
	ds_read_b128 v[178:181], v141 offset:36864
	ds_read_b128 v[182:185], v141 offset:37888
	ds_read_b128 v[186:189], v141 offset:38912
	ds_read_b128 v[214:217], v141 offset:39936
	s_waitcnt lgkmcnt(8)
	s_barrier
	s_waitcnt lgkmcnt(0)
	v_mfma_f32_16x16x32_bf16 v[124:127], v[134:137], v[162:165], v[124:127]
	v_mfma_f32_16x16x32_bf16 v[116:119], v[146:149], v[162:165], v[116:119]
	v_mfma_f32_16x16x32_bf16 v[108:111], v[134:137], v[170:173], v[108:111]
	v_mfma_f32_16x16x32_bf16 v[100:103], v[146:149], v[170:173], v[100:103]
	v_mfma_f32_16x16x32_bf16 v[92:95], v[134:137], v[178:181], v[92:95]
	v_mfma_f32_16x16x32_bf16 v[84:87], v[146:149], v[178:181], v[84:87]
	v_mfma_f32_16x16x32_bf16 v[76:79], v[134:137], v[186:189], v[76:79]
	v_mfma_f32_16x16x32_bf16 v[68:71], v[146:149], v[186:189], v[68:71]
	v_mfma_f32_16x16x32_bf16 v[124:127], v[142:145], v[166:169], v[124:127]
	v_mfma_f32_16x16x32_bf16 v[116:119], v[150:153], v[166:169], v[116:119]
	v_mfma_f32_16x16x32_bf16 v[108:111], v[142:145], v[174:177], v[108:111]
	v_mfma_f32_16x16x32_bf16 v[100:103], v[150:153], v[174:177], v[100:103]
	v_mfma_f32_16x16x32_bf16 v[92:95], v[142:145], v[182:185], v[92:95]
	v_mfma_f32_16x16x32_bf16 v[84:87], v[150:153], v[182:185], v[84:87]
	v_mfma_f32_16x16x32_bf16 v[76:79], v[142:145], v[214:217], v[76:79]
	v_mfma_f32_16x16x32_bf16 v[68:71], v[150:153], v[214:217], v[68:71]
	s_barrier
	s_add_i32 s78, 0, 0x1c000
	s_add_i32 s2, s77, s53
	v_add_u32_e32 v161, s78, v139
	v_lshl_add_u64 v[154:155], v[154:155], 0, s[50:51]
	s_mov_b32 m0, s2
	s_nop 0
	global_load_lds_dwordx4 v[154:155], off
	v_lshl_add_u64 v[154:155], v[206:207], 0, s[50:51]
	s_add_i32 m0, s2, 0x2000
	s_nop 0
	global_load_lds_dwordx4 v[154:155], off
	ds_read_b128 v[218:221], v161
	ds_read_b128 v[222:225], v161 offset:1024
	ds_read_b128 v[226:229], v161 offset:2048
	ds_read_b128 v[230:233], v161 offset:3072
	s_barrier
	s_waitcnt lgkmcnt(0)
	v_mfma_f32_16x16x32_bf16 v[120:123], v[218:221], v[162:165], v[120:123]
	v_mfma_f32_16x16x32_bf16 v[112:115], v[226:229], v[162:165], v[112:115]
	v_mfma_f32_16x16x32_bf16 v[104:107], v[218:221], v[170:173], v[104:107]
	v_mfma_f32_16x16x32_bf16 v[96:99], v[226:229], v[170:173], v[96:99]
	v_mfma_f32_16x16x32_bf16 v[88:91], v[218:221], v[178:181], v[88:91]
	v_mfma_f32_16x16x32_bf16 v[80:83], v[226:229], v[178:181], v[80:83]
	v_mfma_f32_16x16x32_bf16 v[72:75], v[218:221], v[186:189], v[72:75]
	v_mfma_f32_16x16x32_bf16 v[64:67], v[226:229], v[186:189], v[64:67]
	v_mfma_f32_16x16x32_bf16 v[120:123], v[222:225], v[166:169], v[120:123]
	v_mfma_f32_16x16x32_bf16 v[112:115], v[230:233], v[166:169], v[112:115]
	v_mfma_f32_16x16x32_bf16 v[104:107], v[222:225], v[174:177], v[104:107]
	v_mfma_f32_16x16x32_bf16 v[96:99], v[230:233], v[174:177], v[96:99]
	v_mfma_f32_16x16x32_bf16 v[88:91], v[222:225], v[182:185], v[88:91]
	v_mfma_f32_16x16x32_bf16 v[80:83], v[230:233], v[182:185], v[80:83]
	v_mfma_f32_16x16x32_bf16 v[72:75], v[222:225], v[214:217], v[72:75]
	v_mfma_f32_16x16x32_bf16 v[64:67], v[230:233], v[214:217], v[64:67]
	s_mov_b32 m0, s66
	v_lshl_add_u64 v[154:155], v[208:209], 0, s[50:51]
	s_barrier
	global_load_lds_dwordx4 v[154:155], off
	v_lshl_add_u64 v[154:155], v[234:235], 0, s[50:51]
	s_mov_b32 m0, s67
	s_nop 0
	global_load_lds_dwordx4 v[154:155], off
	ds_read_b128 v[162:165], v141 offset:49152
	ds_read_b128 v[166:169], v141 offset:50176
	ds_read_b128 v[170:173], v141 offset:51200
	ds_read_b128 v[174:177], v141 offset:52224
	ds_read_b128 v[178:181], v141 offset:53248
	ds_read_b128 v[182:185], v141 offset:54272
	ds_read_b128 v[186:189], v141 offset:55296
	ds_read_b128 v[214:217], v141 offset:56320
	s_barrier
	s_waitcnt lgkmcnt(0)
	v_mfma_f32_16x16x32_bf16 v[60:63], v[134:137], v[162:165], v[60:63]
	v_mfma_f32_16x16x32_bf16 v[52:55], v[146:149], v[162:165], v[52:55]
	v_mfma_f32_16x16x32_bf16 v[44:47], v[134:137], v[170:173], v[44:47]
	v_mfma_f32_16x16x32_bf16 v[36:39], v[146:149], v[170:173], v[36:39]
	v_mfma_f32_16x16x32_bf16 v[28:31], v[134:137], v[178:181], v[28:31]
	v_mfma_f32_16x16x32_bf16 v[20:23], v[146:149], v[178:181], v[20:23]
	v_mfma_f32_16x16x32_bf16 v[12:15], v[134:137], v[186:189], v[12:15]
	v_mfma_f32_16x16x32_bf16 v[4:7], v[146:149], v[186:189], v[4:7]
	v_mfma_f32_16x16x32_bf16 v[60:63], v[142:145], v[166:169], v[60:63]
	v_mfma_f32_16x16x32_bf16 v[52:55], v[150:153], v[166:169], v[52:55]
	v_mfma_f32_16x16x32_bf16 v[44:47], v[142:145], v[174:177], v[44:47]
	v_mfma_f32_16x16x32_bf16 v[36:39], v[150:153], v[174:177], v[36:39]
	v_mfma_f32_16x16x32_bf16 v[28:31], v[142:145], v[182:185], v[28:31]
	v_mfma_f32_16x16x32_bf16 v[20:23], v[150:153], v[182:185], v[20:23]
	v_mfma_f32_16x16x32_bf16 v[12:15], v[142:145], v[214:217], v[12:15]
	v_mfma_f32_16x16x32_bf16 v[4:7], v[150:153], v[214:217], v[4:7]
	s_barrier
	s_add_u32 s2, s54, 0x40080
	s_addc_u32 s3, s55, 0
	s_add_i32 s54, s78, s53
	v_lshl_add_u64 v[134:135], s[2:3], 0, v[156:157]
	s_mov_b32 m0, s54
	s_nop 0
	global_load_lds_dwordx4 v[134:135], off
	v_lshl_add_u64 v[134:135], s[2:3], 0, v[128:129]
	s_add_i32 m0, s54, 0x2000
	s_nop 0
	global_load_lds_dwordx4 v[134:135], off
	s_waitcnt vmcnt(6)
	s_barrier
	v_mfma_f32_16x16x32_bf16 v[56:59], v[218:221], v[162:165], v[56:59]
	v_mfma_f32_16x16x32_bf16 v[48:51], v[226:229], v[162:165], v[48:51]
	v_mfma_f32_16x16x32_bf16 v[40:43], v[218:221], v[170:173], v[40:43]
	v_mfma_f32_16x16x32_bf16 v[32:35], v[226:229], v[170:173], v[32:35]
	v_mfma_f32_16x16x32_bf16 v[24:27], v[218:221], v[178:181], v[24:27]
	v_mfma_f32_16x16x32_bf16 v[16:19], v[226:229], v[178:181], v[16:19]
	v_mfma_f32_16x16x32_bf16 v[8:11], v[218:221], v[186:189], v[8:11]
	v_mfma_f32_16x16x32_bf16 v[0:3], v[226:229], v[186:189], v[0:3]
	v_mfma_f32_16x16x32_bf16 v[56:59], v[222:225], v[166:169], v[56:59]
	v_mfma_f32_16x16x32_bf16 v[48:51], v[230:233], v[166:169], v[48:51]
	v_mfma_f32_16x16x32_bf16 v[40:43], v[222:225], v[174:177], v[40:43]
	v_mfma_f32_16x16x32_bf16 v[32:35], v[230:233], v[174:177], v[32:35]
	v_mfma_f32_16x16x32_bf16 v[24:27], v[222:225], v[182:185], v[24:27]
	v_mfma_f32_16x16x32_bf16 v[16:19], v[230:233], v[182:185], v[16:19]
	v_mfma_f32_16x16x32_bf16 v[8:11], v[222:225], v[214:217], v[8:11]
	v_mfma_f32_16x16x32_bf16 v[0:3], v[230:233], v[214:217], v[0:3]
	s_add_i32 s73, s73, 2
	s_add_u32 s43, s43, 0x100
	s_addc_u32 s69, s69, 0
	s_add_u32 s6, s6, 0x100
	s_addc_u32 s7, s7, 0
	s_cmp_gt_u32 s73, 13
	s_barrier
	s_cbranch_scc1 .Lpost_555
.LBB0_555:
	s_add_u32 s2, s6, 0xfffc0080
	s_addc_u32 s3, s7, -1
	s_add_i32 s77, 0, 0x10000
	v_add_u32_e32 v150, s77, v139
	ds_read_b128 v[134:137], v150
	ds_read_b128 v[142:145], v150 offset:1024
	ds_read_b128 v[146:149], v150 offset:2048
	ds_read_b128 v[150:153], v150 offset:3072
	s_cmp_eq_u32 s73, 12
	s_cselect_b32 s3, s10, s3
	s_cselect_b32 s2, s24, s2
	s_cselect_b32 s55, s25, s69
	s_cselect_b32 s54, s41, s43
	v_lshl_add_u64 v[154:155], s[6:7], 0, v[132:133]
	s_add_i32 m0, s47, 0xc000
	s_nop 0
	global_load_lds_dwordx4 v[154:155], off
	v_lshl_add_u64 v[154:155], s[6:7], 0, v[130:131]
	s_add_i32 m0, s47, 0xe000
	s_nop 0
	global_load_lds_dwordx4 v[154:155], off
	ds_read_b128 v[162:165], v141
	ds_read_b128 v[166:169], v141 offset:1024
	ds_read_b128 v[170:173], v141 offset:2048
	ds_read_b128 v[174:177], v141 offset:3072
	ds_read_b128 v[178:181], v141 offset:4096
	ds_read_b128 v[182:185], v141 offset:5120
	ds_read_b128 v[186:189], v141 offset:6144
	ds_read_b128 v[214:217], v141 offset:7168
	s_waitcnt lgkmcnt(8)
	s_barrier
	s_waitcnt lgkmcnt(0)
	v_mfma_f32_16x16x32_bf16 v[124:127], v[134:137], v[162:165], v[124:127]
	v_mfma_f32_16x16x32_bf16 v[116:119], v[146:149], v[162:165], v[116:119]
	v_mfma_f32_16x16x32_bf16 v[108:111], v[134:137], v[170:173], v[108:111]
	v_mfma_f32_16x16x32_bf16 v[100:103], v[146:149], v[170:173], v[100:103]
	v_mfma_f32_16x16x32_bf16 v[92:95], v[134:137], v[178:181], v[92:95]
	v_mfma_f32_16x16x32_bf16 v[84:87], v[146:149], v[178:181], v[84:87]
	v_mfma_f32_16x16x32_bf16 v[76:79], v[134:137], v[186:189], v[76:79]
	v_mfma_f32_16x16x32_bf16 v[68:71], v[146:149], v[186:189], v[68:71]
	v_mfma_f32_16x16x32_bf16 v[124:127], v[142:145], v[166:169], v[124:127]
	v_mfma_f32_16x16x32_bf16 v[116:119], v[150:153], v[166:169], v[116:119]
	v_mfma_f32_16x16x32_bf16 v[108:111], v[142:145], v[174:177], v[108:111]
	v_mfma_f32_16x16x32_bf16 v[100:103], v[150:153], v[174:177], v[100:103]
	v_mfma_f32_16x16x32_bf16 v[92:95], v[142:145], v[182:185], v[92:95]
	v_mfma_f32_16x16x32_bf16 v[84:87], v[150:153], v[182:185], v[84:87]
	v_mfma_f32_16x16x32_bf16 v[76:79], v[142:145], v[214:217], v[76:79]
	v_mfma_f32_16x16x32_bf16 v[68:71], v[150:153], v[214:217], v[68:71]
	s_barrier
	s_add_i32 s80, 0, 0x14000
	v_add_u32_e32 v154, s80, v139
	s_add_i32 s77, s77, s53
	ds_read_b128 v[218:221], v154
	ds_read_b128 v[222:225], v154 offset:1024
	ds_read_b128 v[226:229], v154 offset:2048
	ds_read_b128 v[230:233], v154 offset:3072
	v_lshl_add_u64 v[154:155], s[54:55], 0, v[156:157]
	s_mov_b32 m0, s77
	v_lshl_add_u64 v[206:207], s[54:55], 0, v[128:129]
	global_load_lds_dwordx4 v[154:155], off
	s_add_i32 m0, s77, 0x2000
	s_nop 0
	global_load_lds_dwordx4 v[206:207], off
	s_barrier
	s_waitcnt lgkmcnt(0)
	v_mfma_f32_16x16x32_bf16 v[120:123], v[218:221], v[162:165], v[120:123]
	v_mfma_f32_16x16x32_bf16 v[112:115], v[226:229], v[162:165], v[112:115]
	v_mfma_f32_16x16x32_bf16 v[104:107], v[218:221], v[170:173], v[104:107]
	v_mfma_f32_16x16x32_bf16 v[96:99], v[226:229], v[170:173], v[96:99]
	v_mfma_f32_16x16x32_bf16 v[88:91], v[218:221], v[178:181], v[88:91]
	v_mfma_f32_16x16x32_bf16 v[80:83], v[226:229], v[178:181], v[80:83]
	v_mfma_f32_16x16x32_bf16 v[72:75], v[218:221], v[186:189], v[72:75]
	v_mfma_f32_16x16x32_bf16 v[64:67], v[226:229], v[186:189], v[64:67]
	v_mfma_f32_16x16x32_bf16 v[120:123], v[222:225], v[166:169], v[120:123]
	v_mfma_f32_16x16x32_bf16 v[112:115], v[230:233], v[166:169], v[112:115]
	v_mfma_f32_16x16x32_bf16 v[104:107], v[222:225], v[174:177], v[104:107]
	v_mfma_f32_16x16x32_bf16 v[96:99], v[230:233], v[174:177], v[96:99]
	v_mfma_f32_16x16x32_bf16 v[88:91], v[222:225], v[182:185], v[88:91]
	v_mfma_f32_16x16x32_bf16 v[80:83], v[230:233], v[182:185], v[80:83]
	v_mfma_f32_16x16x32_bf16 v[72:75], v[222:225], v[214:217], v[72:75]
	v_mfma_f32_16x16x32_bf16 v[64:67], v[230:233], v[214:217], v[64:67]
	s_mov_b32 m0, s47
	v_lshl_add_u64 v[208:209], s[2:3], 0, v[156:157]
	s_barrier
	global_load_lds_dwordx4 v[208:209], off
	v_lshl_add_u64 v[234:235], s[2:3], 0, v[128:129]
	s_mov_b32 m0, s49
	s_nop 0
	global_load_lds_dwordx4 v[234:235], off
	ds_read_b128 v[162:165], v141 offset:16384
	ds_read_b128 v[166:169], v141 offset:17408
	ds_read_b128 v[170:173], v141 offset:18432
	ds_read_b128 v[174:177], v141 offset:19456
	ds_read_b128 v[178:181], v141 offset:20480
	ds_read_b128 v[182:185], v141 offset:21504
	ds_read_b128 v[186:189], v141 offset:22528
	ds_read_b128 v[214:217], v141 offset:23552
	s_barrier
	s_waitcnt lgkmcnt(0)
	v_mfma_f32_16x16x32_bf16 v[60:63], v[134:137], v[162:165], v[60:63]
	v_mfma_f32_16x16x32_bf16 v[52:55], v[146:149], v[162:165], v[52:55]
	v_mfma_f32_16x16x32_bf16 v[44:47], v[134:137], v[170:173], v[44:47]
	v_mfma_f32_16x16x32_bf16 v[36:39], v[146:149], v[170:173], v[36:39]
	v_mfma_f32_16x16x32_bf16 v[28:31], v[134:137], v[178:181], v[28:31]
	v_mfma_f32_16x16x32_bf16 v[20:23], v[146:149], v[178:181], v[20:23]
	v_mfma_f32_16x16x32_bf16 v[12:15], v[134:137], v[186:189], v[12:15]
	v_mfma_f32_16x16x32_bf16 v[4:7], v[146:149], v[186:189], v[4:7]
	v_mfma_f32_16x16x32_bf16 v[60:63], v[142:145], v[166:169], v[60:63]
	v_mfma_f32_16x16x32_bf16 v[52:55], v[150:153], v[166:169], v[52:55]
	v_mfma_f32_16x16x32_bf16 v[44:47], v[142:145], v[174:177], v[44:47]
	v_mfma_f32_16x16x32_bf16 v[36:39], v[150:153], v[174:177], v[36:39]
	v_mfma_f32_16x16x32_bf16 v[28:31], v[142:145], v[182:185], v[28:31]
	v_mfma_f32_16x16x32_bf16 v[20:23], v[150:153], v[182:185], v[20:23]
	v_mfma_f32_16x16x32_bf16 v[12:15], v[142:145], v[214:217], v[12:15]
	v_mfma_f32_16x16x32_bf16 v[4:7], v[150:153], v[214:217], v[4:7]
	s_barrier
	s_add_u32 s78, s54, 0x40000
	s_addc_u32 s79, s55, 0
	s_add_i32 s77, s80, s53
	v_lshl_add_u64 v[134:135], s[78:79], 0, v[156:157]
	s_mov_b32 m0, s77
	s_nop 0
	global_load_lds_dwordx4 v[134:135], off
	v_lshl_add_u64 v[134:135], s[78:79], 0, v[128:129]
	s_add_i32 m0, s77, 0x2000
	s_nop 0
	global_load_lds_dwordx4 v[134:135], off
	s_waitcnt vmcnt(6)
	s_barrier
	v_mfma_f32_16x16x32_bf16 v[56:59], v[218:221], v[162:165], v[56:59]
	v_mfma_f32_16x16x32_bf16 v[48:51], v[226:229], v[162:165], v[48:51]
	v_mfma_f32_16x16x32_bf16 v[40:43], v[218:221], v[170:173], v[40:43]
	v_mfma_f32_16x16x32_bf16 v[32:35], v[226:229], v[170:173], v[32:35]
	v_mfma_f32_16x16x32_bf16 v[24:27], v[218:221], v[178:181], v[24:27]
	v_mfma_f32_16x16x32_bf16 v[16:19], v[226:229], v[178:181], v[16:19]
	v_mfma_f32_16x16x32_bf16 v[8:11], v[218:221], v[186:189], v[8:11]
	v_mfma_f32_16x16x32_bf16 v[0:3], v[226:229], v[186:189], v[0:3]
	v_mfma_f32_16x16x32_bf16 v[56:59], v[222:225], v[166:169], v[56:59]
	v_mfma_f32_16x16x32_bf16 v[48:51], v[230:233], v[166:169], v[48:51]
	v_mfma_f32_16x16x32_bf16 v[40:43], v[222:225], v[174:177], v[40:43]
	v_mfma_f32_16x16x32_bf16 v[32:35], v[230:233], v[174:177], v[32:35]
	v_mfma_f32_16x16x32_bf16 v[24:27], v[222:225], v[182:185], v[24:27]
	v_mfma_f32_16x16x32_bf16 v[16:19], v[230:233], v[182:185], v[16:19]
	v_mfma_f32_16x16x32_bf16 v[8:11], v[222:225], v[214:217], v[8:11]
	v_mfma_f32_16x16x32_bf16 v[0:3], v[230:233], v[214:217], v[0:3]
	s_add_i32 s77, 0, 0x18000
	v_add_u32_e32 v150, s77, v139
	s_barrier
	ds_read_b128 v[134:137], v150
	ds_read_b128 v[142:145], v150 offset:1024
	ds_read_b128 v[146:149], v150 offset:2048
	ds_read_b128 v[150:153], v150 offset:3072
	s_add_u32 s2, s2, 0x40000
	s_addc_u32 s3, s3, 0
	s_mov_b32 m0, s62
	v_lshl_add_u64 v[218:219], s[2:3], 0, v[156:157]
	global_load_lds_dwordx4 v[218:219], off
	v_lshl_add_u64 v[218:219], s[2:3], 0, v[128:129]
	s_mov_b32 m0, s63
	s_nop 0
	global_load_lds_dwordx4 v[218:219], off
	ds_read_b128 v[162:165], v141 offset:32768
	ds_read_b128 v[166:169], v141 offset:33792
	ds_read_b128 v[170:173], v141 offset:34816
	ds_read_b128 v[174:177], v141 offset:35840
	ds_read_b128 v[178:181], v141 offset:36864
	ds_read_b128 v[182:185], v141 offset:37888
	ds_read_b128 v[186:189], v141 offset:38912
	ds_read_b128 v[214:217], v141 offset:39936
	s_waitcnt lgkmcnt(8)
	s_barrier
	s_waitcnt lgkmcnt(0)
	v_mfma_f32_16x16x32_bf16 v[124:127], v[134:137], v[162:165], v[124:127]
	v_mfma_f32_16x16x32_bf16 v[116:119], v[146:149], v[162:165], v[116:119]
	v_mfma_f32_16x16x32_bf16 v[108:111], v[134:137], v[170:173], v[108:111]
	v_mfma_f32_16x16x32_bf16 v[100:103], v[146:149], v[170:173], v[100:103]
	v_mfma_f32_16x16x32_bf16 v[92:95], v[134:137], v[178:181], v[92:95]
	v_mfma_f32_16x16x32_bf16 v[84:87], v[146:149], v[178:181], v[84:87]
	v_mfma_f32_16x16x32_bf16 v[76:79], v[134:137], v[186:189], v[76:79]
	v_mfma_f32_16x16x32_bf16 v[68:71], v[146:149], v[186:189], v[68:71]
	v_mfma_f32_16x16x32_bf16 v[124:127], v[142:145], v[166:169], v[124:127]
	v_mfma_f32_16x16x32_bf16 v[116:119], v[150:153], v[166:169], v[116:119]
	v_mfma_f32_16x16x32_bf16 v[108:111], v[142:145], v[174:177], v[108:111]
	v_mfma_f32_16x16x32_bf16 v[100:103], v[150:153], v[174:177], v[100:103]
	v_mfma_f32_16x16x32_bf16 v[92:95], v[142:145], v[182:185], v[92:95]
	v_mfma_f32_16x16x32_bf16 v[84:87], v[150:153], v[182:185], v[84:87]
	v_mfma_f32_16x16x32_bf16 v[76:79], v[142:145], v[214:217], v[76:79]
	v_mfma_f32_16x16x32_bf16 v[68:71], v[150:153], v[214:217], v[68:71]
	s_barrier
	s_add_i32 s78, 0, 0x1c000
	s_add_i32 s2, s77, s53
	v_add_u32_e32 v161, s78, v139
	v_lshl_add_u64 v[154:155], v[154:155], 0, s[50:51]
	s_mov_b32 m0, s2
	s_nop 0
	global_load_lds_dwordx4 v[154:155], off
	v_lshl_add_u64 v[154:155], v[206:207], 0, s[50:51]
	s_add_i32 m0, s2, 0x2000
	s_nop 0
	global_load_lds_dwordx4 v[154:155], off
	ds_read_b128 v[218:221], v161
	ds_read_b128 v[222:225], v161 offset:1024
	ds_read_b128 v[226:229], v161 offset:2048
	ds_read_b128 v[230:233], v161 offset:3072
	s_barrier
	s_waitcnt lgkmcnt(0)
	v_mfma_f32_16x16x32_bf16 v[120:123], v[218:221], v[162:165], v[120:123]
	v_mfma_f32_16x16x32_bf16 v[112:115], v[226:229], v[162:165], v[112:115]
	v_mfma_f32_16x16x32_bf16 v[104:107], v[218:221], v[170:173], v[104:107]
	v_mfma_f32_16x16x32_bf16 v[96:99], v[226:229], v[170:173], v[96:99]
	v_mfma_f32_16x16x32_bf16 v[88:91], v[218:221], v[178:181], v[88:91]
	v_mfma_f32_16x16x32_bf16 v[80:83], v[226:229], v[178:181], v[80:83]
	v_mfma_f32_16x16x32_bf16 v[72:75], v[218:221], v[186:189], v[72:75]
	v_mfma_f32_16x16x32_bf16 v[64:67], v[226:229], v[186:189], v[64:67]
	v_mfma_f32_16x16x32_bf16 v[120:123], v[222:225], v[166:169], v[120:123]
	v_mfma_f32_16x16x32_bf16 v[112:115], v[230:233], v[166:169], v[112:115]
	v_mfma_f32_16x16x32_bf16 v[104:107], v[222:225], v[174:177], v[104:107]
	v_mfma_f32_16x16x32_bf16 v[96:99], v[230:233], v[174:177], v[96:99]
	v_mfma_f32_16x16x32_bf16 v[88:91], v[222:225], v[182:185], v[88:91]
	v_mfma_f32_16x16x32_bf16 v[80:83], v[230:233], v[182:185], v[80:83]
	v_mfma_f32_16x16x32_bf16 v[72:75], v[222:225], v[214:217], v[72:75]
	v_mfma_f32_16x16x32_bf16 v[64:67], v[230:233], v[214:217], v[64:67]
	s_mov_b32 m0, s66
	v_lshl_add_u64 v[154:155], v[208:209], 0, s[50:51]
	s_barrier
	global_load_lds_dwordx4 v[154:155], off
	v_lshl_add_u64 v[154:155], v[234:235], 0, s[50:51]
	s_mov_b32 m0, s67
	s_nop 0
	global_load_lds_dwordx4 v[154:155], off
	ds_read_b128 v[162:165], v141 offset:49152
	ds_read_b128 v[166:169], v141 offset:50176
	ds_read_b128 v[170:173], v141 offset:51200
	ds_read_b128 v[174:177], v141 offset:52224
	ds_read_b128 v[178:181], v141 offset:53248
	ds_read_b128 v[182:185], v141 offset:54272
	ds_read_b128 v[186:189], v141 offset:55296
	ds_read_b128 v[214:217], v141 offset:56320
	s_barrier
	s_waitcnt lgkmcnt(0)
	v_mfma_f32_16x16x32_bf16 v[60:63], v[134:137], v[162:165], v[60:63]
	v_mfma_f32_16x16x32_bf16 v[52:55], v[146:149], v[162:165], v[52:55]
	v_mfma_f32_16x16x32_bf16 v[44:47], v[134:137], v[170:173], v[44:47]
	v_mfma_f32_16x16x32_bf16 v[36:39], v[146:149], v[170:173], v[36:39]
	v_mfma_f32_16x16x32_bf16 v[28:31], v[134:137], v[178:181], v[28:31]
	v_mfma_f32_16x16x32_bf16 v[20:23], v[146:149], v[178:181], v[20:23]
	v_mfma_f32_16x16x32_bf16 v[12:15], v[134:137], v[186:189], v[12:15]
	v_mfma_f32_16x16x32_bf16 v[4:7], v[146:149], v[186:189], v[4:7]
	v_mfma_f32_16x16x32_bf16 v[60:63], v[142:145], v[166:169], v[60:63]
	v_mfma_f32_16x16x32_bf16 v[52:55], v[150:153], v[166:169], v[52:55]
	v_mfma_f32_16x16x32_bf16 v[44:47], v[142:145], v[174:177], v[44:47]
	v_mfma_f32_16x16x32_bf16 v[36:39], v[150:153], v[174:177], v[36:39]
	v_mfma_f32_16x16x32_bf16 v[28:31], v[142:145], v[182:185], v[28:31]
	v_mfma_f32_16x16x32_bf16 v[20:23], v[150:153], v[182:185], v[20:23]
	v_mfma_f32_16x16x32_bf16 v[12:15], v[142:145], v[214:217], v[12:15]
	v_mfma_f32_16x16x32_bf16 v[4:7], v[150:153], v[214:217], v[4:7]
	s_barrier
	s_add_u32 s2, s54, 0x40080
	s_addc_u32 s3, s55, 0
	s_add_i32 s54, s78, s53
	v_lshl_add_u64 v[134:135], s[2:3], 0, v[156:157]
	s_mov_b32 m0, s54
	s_nop 0
	global_load_lds_dwordx4 v[134:135], off
	v_lshl_add_u64 v[134:135], s[2:3], 0, v[128:129]
	s_add_i32 m0, s54, 0x2000
	s_nop 0
	global_load_lds_dwordx4 v[134:135], off
	s_waitcnt vmcnt(6)
	s_barrier
	v_mfma_f32_16x16x32_bf16 v[56:59], v[218:221], v[162:165], v[56:59]
	v_mfma_f32_16x16x32_bf16 v[48:51], v[226:229], v[162:165], v[48:51]
	v_mfma_f32_16x16x32_bf16 v[40:43], v[218:221], v[170:173], v[40:43]
	v_mfma_f32_16x16x32_bf16 v[32:35], v[226:229], v[170:173], v[32:35]
	v_mfma_f32_16x16x32_bf16 v[24:27], v[218:221], v[178:181], v[24:27]
	v_mfma_f32_16x16x32_bf16 v[16:19], v[226:229], v[178:181], v[16:19]
	v_mfma_f32_16x16x32_bf16 v[8:11], v[218:221], v[186:189], v[8:11]
	v_mfma_f32_16x16x32_bf16 v[0:3], v[226:229], v[186:189], v[0:3]
	v_mfma_f32_16x16x32_bf16 v[56:59], v[222:225], v[166:169], v[56:59]
	v_mfma_f32_16x16x32_bf16 v[48:51], v[230:233], v[166:169], v[48:51]
	v_mfma_f32_16x16x32_bf16 v[40:43], v[222:225], v[174:177], v[40:43]
	v_mfma_f32_16x16x32_bf16 v[32:35], v[230:233], v[174:177], v[32:35]
	v_mfma_f32_16x16x32_bf16 v[24:27], v[222:225], v[182:185], v[24:27]
	v_mfma_f32_16x16x32_bf16 v[16:19], v[230:233], v[182:185], v[16:19]
	v_mfma_f32_16x16x32_bf16 v[8:11], v[222:225], v[214:217], v[8:11]
	v_mfma_f32_16x16x32_bf16 v[0:3], v[230:233], v[214:217], v[0:3]
	s_add_i32 s73, s73, 2
	s_add_u32 s43, s43, 0x100
	s_addc_u32 s69, s69, 0
	s_add_u32 s6, s6, 0x100
	s_addc_u32 s7, s7, 0
	s_cmp_gt_u32 s73, 13
	s_barrier
	s_cbranch_scc0 .LBB0_555
